# K-loop interval edges trimmed: setprio raised before the barrier, redundant lgkmcnt wait and mid-phase setprio flips removed, setprio 0 after barrier, m0 nops removed by reordering, waits merged
# baseline (speedup 1.0000x reference)
.LBB0_141:
	s_lshl_b32 s34, s11, 8
	s_ashr_i32 s35, s34, 31
	s_lshl_b64 s[34:35], s[34:35], 11
	s_add_u32 s82, s49, s34
	s_addc_u32 s83, s53, s35
	s_and_b64 s[34:35], s[0:1], exec
	s_cselect_b32 s5, s83, s7
	s_cselect_b32 s22, s82, s6
	s_ashr_i32 s81, s80, 31
	s_lshl_b64 s[34:35], s[80:81], 19
	s_add_u32 s84, s55, s34
	s_addc_u32 s85, s57, s35
	s_and_b64 s[34:35], s[0:1], exec
	s_cselect_b32 s34, s85, s9
	s_cselect_b32 s35, s84, s8
	s_add_u32 s40, s8, 0x100
	s_addc_u32 s41, s9, 0
	s_mov_b32 s50, -2
	s_waitcnt vmcnt(0)
	s_waitcnt lgkmcnt(0)
	ds_read_b128 v[128:131], v175
	ds_read_b128 v[132:135], v175 offset:1024
	ds_read_b128 v[136:139], v175 offset:2048
	ds_read_b128 v[140:143], v175 offset:3072
	ds_read_b128 v[166:169], v176
	ds_read_b128 v[170:173], v176 offset:1024
	ds_read_b128 v[182:185], v176 offset:2048
	ds_read_b128 v[186:189], v176 offset:3072
	s_add_u32 s8, s6, 0x100
	s_addc_u32 s9, s7, 0
	s_cmp_eq_u32 s50, 12
	s_cselect_b32 s89, s5, s9
	s_cselect_b32 s88, s22, s8
	s_cselect_b32 s87, s34, s41
	s_cselect_b32 s86, s35, s40
	v_lshl_add_u64 v[220:221], s[6:7], 0, v[158:159]
	s_add_i32 m0, s61, 0xc000
	ds_read_b128 v[190:193], v177
	ds_read_b128 v[194:197], v177 offset:1024
	ds_read_b128 v[198:201], v177 offset:2048
	ds_read_b128 v[202:205], v177 offset:3072
	ds_read_b128 v[206:209], v177 offset:4096
	ds_read_b128 v[210:213], v177 offset:5120
	ds_read_b128 v[214:217], v177 offset:6144
	ds_read_b128 v[224:227], v177 offset:7168
	global_load_lds_dwordx4 v[220:221], off
	s_add_i32 m0, s61, 0xe000
	v_lshl_add_u64 v[220:221], s[6:7], 0, v[160:161]
	global_load_lds_dwordx4 v[220:221], off
	s_waitcnt vmcnt(8) lgkmcnt(0)
	s_setprio 1
	s_barrier
	v_mfma_f32_16x16x32_bf16 v[124:127], v[128:131], v[190:193], 0
	v_mfma_f32_16x16x32_bf16 v[120:123], v[136:139], v[190:193], 0
	v_mfma_f32_16x16x32_bf16 v[108:111], v[128:131], v[198:201], 0
	v_mfma_f32_16x16x32_bf16 v[104:107], v[136:139], v[198:201], 0
	v_mfma_f32_16x16x32_bf16 v[92:95], v[128:131], v[206:209], 0
	v_mfma_f32_16x16x32_bf16 v[88:91], v[136:139], v[206:209], 0
	v_mfma_f32_16x16x32_bf16 v[76:79], v[128:131], v[214:217], 0
	v_mfma_f32_16x16x32_bf16 v[72:75], v[136:139], v[214:217], 0
	v_mfma_f32_16x16x32_bf16 v[124:127], v[132:135], v[194:197], v[124:127]
	v_mfma_f32_16x16x32_bf16 v[120:123], v[140:143], v[194:197], v[120:123]
	v_mfma_f32_16x16x32_bf16 v[108:111], v[132:135], v[202:205], v[108:111]
	v_mfma_f32_16x16x32_bf16 v[104:107], v[140:143], v[202:205], v[104:107]
	v_mfma_f32_16x16x32_bf16 v[92:95], v[132:135], v[210:213], v[92:95]
	v_mfma_f32_16x16x32_bf16 v[88:91], v[140:143], v[210:213], v[88:91]
	v_mfma_f32_16x16x32_bf16 v[76:79], v[132:135], v[224:227], v[76:79]
	v_mfma_f32_16x16x32_bf16 v[72:75], v[140:143], v[224:227], v[72:75]
	v_mfma_f32_16x16x32_bf16 v[116:119], v[166:169], v[190:193], 0
	v_mfma_f32_16x16x32_bf16 v[112:115], v[182:185], v[190:193], 0
	v_mfma_f32_16x16x32_bf16 v[100:103], v[166:169], v[198:201], 0
	v_mfma_f32_16x16x32_bf16 v[96:99], v[182:185], v[198:201], 0
	v_mfma_f32_16x16x32_bf16 v[84:87], v[166:169], v[206:209], 0
	v_mfma_f32_16x16x32_bf16 v[80:83], v[182:185], v[206:209], 0
	v_mfma_f32_16x16x32_bf16 v[68:71], v[166:169], v[214:217], 0
	v_mfma_f32_16x16x32_bf16 v[64:67], v[182:185], v[214:217], 0
	v_mfma_f32_16x16x32_bf16 v[116:119], v[170:173], v[194:197], v[116:119]
	v_mfma_f32_16x16x32_bf16 v[112:115], v[186:189], v[194:197], v[112:115]
	v_mfma_f32_16x16x32_bf16 v[100:103], v[170:173], v[202:205], v[100:103]
	v_mfma_f32_16x16x32_bf16 v[96:99], v[186:189], v[202:205], v[96:99]
	v_mfma_f32_16x16x32_bf16 v[84:87], v[170:173], v[210:213], v[84:87]
	v_mfma_f32_16x16x32_bf16 v[80:83], v[186:189], v[210:213], v[80:83]
	v_mfma_f32_16x16x32_bf16 v[68:71], v[170:173], v[224:227], v[68:71]
	v_mfma_f32_16x16x32_bf16 v[64:67], v[186:189], v[224:227], v[64:67]
	s_barrier
	s_setprio 0
	s_add_i32 s6, s37, s59
	v_lshl_add_u64 v[220:221], s[86:87], 0, v[148:149]
	s_mov_b32 m0, s6
	ds_read_b128 v[190:193], v177 offset:16384
	ds_read_b128 v[194:197], v177 offset:17408
	ds_read_b128 v[198:201], v177 offset:18432
	ds_read_b128 v[202:205], v177 offset:19456
	ds_read_b128 v[206:209], v177 offset:20480
	ds_read_b128 v[210:213], v177 offset:21504
	ds_read_b128 v[214:217], v177 offset:22528
	ds_read_b128 v[224:227], v177 offset:23552
	global_load_lds_dwordx4 v[220:221], off
	s_add_i32 m0, s6, 0x2000
	s_add_u32 s6, s86, 0x40000
	v_lshl_add_u64 v[228:229], s[86:87], 0, v[152:153]
	s_addc_u32 s7, s87, 0
	s_add_i32 s51, s97, s59
	global_load_lds_dwordx4 v[228:229], off
	v_lshl_add_u64 v[230:231], s[6:7], 0, v[148:149]
	s_mov_b32 m0, s51
	v_lshl_add_u64 v[232:233], s[88:89], 0, v[150:151]
	global_load_lds_dwordx4 v[230:231], off
	v_lshl_add_u64 v[230:231], s[6:7], 0, v[152:153]
	s_add_i32 m0, s51, 0x2000
	v_lshl_add_u64 v[234:235], v[232:233], 0, s[68:69]
	global_load_lds_dwordx4 v[230:231], off
	s_mov_b32 m0, s61
	v_lshl_add_u64 v[230:231], s[88:89], 0, v[146:147]
	global_load_lds_dwordx4 v[230:231], off
	s_mov_b32 m0, s63
	s_nop 0
	global_load_lds_dwordx4 v[234:235], off
	s_waitcnt vmcnt(8) lgkmcnt(0)
	s_setprio 1
	s_barrier
	v_mfma_f32_16x16x32_bf16 v[60:63], v[128:131], v[190:193], 0
	v_mfma_f32_16x16x32_bf16 v[56:59], v[136:139], v[190:193], 0
	v_mfma_f32_16x16x32_bf16 v[44:47], v[128:131], v[198:201], 0
	v_mfma_f32_16x16x32_bf16 v[40:43], v[136:139], v[198:201], 0
	v_mfma_f32_16x16x32_bf16 v[28:31], v[128:131], v[206:209], 0
	v_mfma_f32_16x16x32_bf16 v[24:27], v[136:139], v[206:209], 0
	v_mfma_f32_16x16x32_bf16 v[12:15], v[128:131], v[214:217], 0
	v_mfma_f32_16x16x32_bf16 v[8:11], v[136:139], v[214:217], 0
	v_mfma_f32_16x16x32_bf16 v[60:63], v[132:135], v[194:197], v[60:63]
	v_mfma_f32_16x16x32_bf16 v[56:59], v[140:143], v[194:197], v[56:59]
	v_mfma_f32_16x16x32_bf16 v[44:47], v[132:135], v[202:205], v[44:47]
	v_mfma_f32_16x16x32_bf16 v[40:43], v[140:143], v[202:205], v[40:43]
	v_mfma_f32_16x16x32_bf16 v[28:31], v[132:135], v[210:213], v[28:31]
	v_mfma_f32_16x16x32_bf16 v[24:27], v[140:143], v[210:213], v[24:27]
	v_mfma_f32_16x16x32_bf16 v[12:15], v[132:135], v[224:227], v[12:15]
	v_mfma_f32_16x16x32_bf16 v[8:11], v[140:143], v[224:227], v[8:11]
	v_mfma_f32_16x16x32_bf16 v[52:55], v[166:169], v[190:193], 0
	v_mfma_f32_16x16x32_bf16 v[48:51], v[182:185], v[190:193], 0
	v_mfma_f32_16x16x32_bf16 v[36:39], v[166:169], v[198:201], 0
	v_mfma_f32_16x16x32_bf16 v[32:35], v[182:185], v[198:201], 0
	v_mfma_f32_16x16x32_bf16 v[20:23], v[166:169], v[206:209], 0
	v_mfma_f32_16x16x32_bf16 v[16:19], v[182:185], v[206:209], 0
	v_mfma_f32_16x16x32_bf16 v[4:7], v[166:169], v[214:217], 0
	v_mfma_f32_16x16x32_bf16 v[0:3], v[182:185], v[214:217], 0
	v_mfma_f32_16x16x32_bf16 v[52:55], v[170:173], v[194:197], v[52:55]
	v_mfma_f32_16x16x32_bf16 v[48:51], v[186:189], v[194:197], v[48:51]
	v_mfma_f32_16x16x32_bf16 v[36:39], v[170:173], v[202:205], v[36:39]
	v_mfma_f32_16x16x32_bf16 v[32:35], v[186:189], v[202:205], v[32:35]
	v_mfma_f32_16x16x32_bf16 v[20:23], v[170:173], v[210:213], v[20:23]
	v_mfma_f32_16x16x32_bf16 v[16:19], v[186:189], v[210:213], v[16:19]
	v_mfma_f32_16x16x32_bf16 v[4:7], v[170:173], v[224:227], v[4:7]
	v_mfma_f32_16x16x32_bf16 v[0:3], v[186:189], v[224:227], v[0:3]
	s_barrier
	s_setprio 0
	s_add_i32 s6, 0, 0x18000
	s_add_i32 s51, 0, 0x1c000
	v_add_u32_e32 v140, s6, v174
	v_add_u32_e32 v154, s51, v174
	ds_read_b128 v[128:131], v140
	ds_read_b128 v[132:135], v140 offset:1024
	ds_read_b128 v[136:139], v140 offset:2048
	ds_read_b128 v[140:143], v140 offset:3072
	ds_read_b128 v[166:169], v154
	ds_read_b128 v[170:173], v154 offset:1024
	ds_read_b128 v[182:185], v154 offset:2048
	ds_read_b128 v[186:189], v154 offset:3072
	s_mov_b32 m0, s65
	v_lshl_add_u64 v[234:235], v[230:231], 0, s[66:67]
	ds_read_b128 v[190:193], v177 offset:32768
	ds_read_b128 v[194:197], v177 offset:33792
	ds_read_b128 v[198:201], v177 offset:34816
	ds_read_b128 v[202:205], v177 offset:35840
	ds_read_b128 v[206:209], v177 offset:36864
	ds_read_b128 v[210:213], v177 offset:37888
	ds_read_b128 v[214:217], v177 offset:38912
	ds_read_b128 v[224:227], v177 offset:39936
	global_load_lds_dwordx4 v[234:235], off
	s_mov_b32 m0, s77
	v_lshl_add_u64 v[234:235], v[232:233], 0, s[46:47]
	global_load_lds_dwordx4 v[234:235], off
	s_waitcnt vmcnt(8) lgkmcnt(0)
	s_setprio 1
	s_barrier
	v_mfma_f32_16x16x32_bf16 v[124:127], v[128:131], v[190:193], v[124:127]
	v_mfma_f32_16x16x32_bf16 v[120:123], v[136:139], v[190:193], v[120:123]
	v_mfma_f32_16x16x32_bf16 v[108:111], v[128:131], v[198:201], v[108:111]
	v_mfma_f32_16x16x32_bf16 v[104:107], v[136:139], v[198:201], v[104:107]
	v_mfma_f32_16x16x32_bf16 v[92:95], v[128:131], v[206:209], v[92:95]
	v_mfma_f32_16x16x32_bf16 v[88:91], v[136:139], v[206:209], v[88:91]
	v_mfma_f32_16x16x32_bf16 v[76:79], v[128:131], v[214:217], v[76:79]
	v_mfma_f32_16x16x32_bf16 v[72:75], v[136:139], v[214:217], v[72:75]
	v_mfma_f32_16x16x32_bf16 v[124:127], v[132:135], v[194:197], v[124:127]
	v_mfma_f32_16x16x32_bf16 v[120:123], v[140:143], v[194:197], v[120:123]
	v_mfma_f32_16x16x32_bf16 v[108:111], v[132:135], v[202:205], v[108:111]
	v_mfma_f32_16x16x32_bf16 v[104:107], v[140:143], v[202:205], v[104:107]
	v_mfma_f32_16x16x32_bf16 v[92:95], v[132:135], v[210:213], v[92:95]
	v_mfma_f32_16x16x32_bf16 v[88:91], v[140:143], v[210:213], v[88:91]
	v_mfma_f32_16x16x32_bf16 v[76:79], v[132:135], v[224:227], v[76:79]
	v_mfma_f32_16x16x32_bf16 v[72:75], v[140:143], v[224:227], v[72:75]
	v_mfma_f32_16x16x32_bf16 v[116:119], v[166:169], v[190:193], v[116:119]
	v_mfma_f32_16x16x32_bf16 v[112:115], v[182:185], v[190:193], v[112:115]
	v_mfma_f32_16x16x32_bf16 v[100:103], v[166:169], v[198:201], v[100:103]
	v_mfma_f32_16x16x32_bf16 v[96:99], v[182:185], v[198:201], v[96:99]
	v_mfma_f32_16x16x32_bf16 v[84:87], v[166:169], v[206:209], v[84:87]
	v_mfma_f32_16x16x32_bf16 v[80:83], v[182:185], v[206:209], v[80:83]
	v_mfma_f32_16x16x32_bf16 v[68:71], v[166:169], v[214:217], v[68:71]
	v_mfma_f32_16x16x32_bf16 v[64:67], v[182:185], v[214:217], v[64:67]
	v_mfma_f32_16x16x32_bf16 v[116:119], v[170:173], v[194:197], v[116:119]
	v_mfma_f32_16x16x32_bf16 v[112:115], v[186:189], v[194:197], v[112:115]
	v_mfma_f32_16x16x32_bf16 v[100:103], v[170:173], v[202:205], v[100:103]
	v_mfma_f32_16x16x32_bf16 v[96:99], v[186:189], v[202:205], v[96:99]
	v_mfma_f32_16x16x32_bf16 v[84:87], v[170:173], v[210:213], v[84:87]
	v_mfma_f32_16x16x32_bf16 v[80:83], v[186:189], v[210:213], v[80:83]
	v_mfma_f32_16x16x32_bf16 v[68:71], v[170:173], v[224:227], v[68:71]
	v_mfma_f32_16x16x32_bf16 v[64:67], v[186:189], v[224:227], v[64:67]
	s_barrier
	s_setprio 0
	s_add_i32 s6, s6, s59
	v_lshl_add_u64 v[220:221], v[220:221], 0, s[42:43]
	s_mov_b32 m0, s6
	ds_read_b128 v[190:193], v177 offset:49152
	ds_read_b128 v[194:197], v177 offset:50176
	ds_read_b128 v[198:201], v177 offset:51200
	ds_read_b128 v[202:205], v177 offset:52224
	ds_read_b128 v[206:209], v177 offset:53248
	ds_read_b128 v[210:213], v177 offset:54272
	ds_read_b128 v[214:217], v177 offset:55296
	ds_read_b128 v[224:227], v177 offset:56320
	global_load_lds_dwordx4 v[220:221], off
	s_add_i32 m0, s6, 0x2000
	s_add_u32 s6, s86, 0x40080
	v_lshl_add_u64 v[220:221], v[228:229], 0, s[42:43]
	s_addc_u32 s7, s87, 0
	s_add_i32 s51, s51, s59
	global_load_lds_dwordx4 v[220:221], off
	s_mov_b32 m0, s51
	v_lshl_add_u64 v[220:221], s[6:7], 0, v[148:149]
	global_load_lds_dwordx4 v[220:221], off
	s_add_i32 m0, s51, 0x2000
	v_lshl_add_u64 v[220:221], s[6:7], 0, v[152:153]
	global_load_lds_dwordx4 v[220:221], off
	s_mov_b32 m0, s91
	v_lshl_add_u64 v[220:221], v[230:231], 0, s[42:43]
	global_load_lds_dwordx4 v[220:221], off
	s_mov_b32 m0, s92
	v_lshl_add_u64 v[220:221], v[232:233], 0, s[44:45]
	global_load_lds_dwordx4 v[220:221], off
	s_waitcnt vmcnt(8) lgkmcnt(0)
	s_setprio 1
	s_barrier
	v_mfma_f32_16x16x32_bf16 v[60:63], v[128:131], v[190:193], v[60:63]
	v_mfma_f32_16x16x32_bf16 v[56:59], v[136:139], v[190:193], v[56:59]
	v_mfma_f32_16x16x32_bf16 v[44:47], v[128:131], v[198:201], v[44:47]
	v_mfma_f32_16x16x32_bf16 v[40:43], v[136:139], v[198:201], v[40:43]
	v_mfma_f32_16x16x32_bf16 v[28:31], v[128:131], v[206:209], v[28:31]
	v_mfma_f32_16x16x32_bf16 v[24:27], v[136:139], v[206:209], v[24:27]
	v_mfma_f32_16x16x32_bf16 v[12:15], v[128:131], v[214:217], v[12:15]
	v_mfma_f32_16x16x32_bf16 v[8:11], v[136:139], v[214:217], v[8:11]
	v_mfma_f32_16x16x32_bf16 v[60:63], v[132:135], v[194:197], v[60:63]
	v_mfma_f32_16x16x32_bf16 v[56:59], v[140:143], v[194:197], v[56:59]
	v_mfma_f32_16x16x32_bf16 v[44:47], v[132:135], v[202:205], v[44:47]
	v_mfma_f32_16x16x32_bf16 v[40:43], v[140:143], v[202:205], v[40:43]
	v_mfma_f32_16x16x32_bf16 v[28:31], v[132:135], v[210:213], v[28:31]
	v_mfma_f32_16x16x32_bf16 v[24:27], v[140:143], v[210:213], v[24:27]
	v_mfma_f32_16x16x32_bf16 v[12:15], v[132:135], v[224:227], v[12:15]
	v_mfma_f32_16x16x32_bf16 v[8:11], v[140:143], v[224:227], v[8:11]
	v_mfma_f32_16x16x32_bf16 v[52:55], v[166:169], v[190:193], v[52:55]
	v_mfma_f32_16x16x32_bf16 v[48:51], v[182:185], v[190:193], v[48:51]
	v_mfma_f32_16x16x32_bf16 v[36:39], v[166:169], v[198:201], v[36:39]
	v_mfma_f32_16x16x32_bf16 v[32:35], v[182:185], v[198:201], v[32:35]
	v_mfma_f32_16x16x32_bf16 v[20:23], v[166:169], v[206:209], v[20:23]
	v_mfma_f32_16x16x32_bf16 v[16:19], v[182:185], v[206:209], v[16:19]
	v_mfma_f32_16x16x32_bf16 v[4:7], v[166:169], v[214:217], v[4:7]
	v_mfma_f32_16x16x32_bf16 v[0:3], v[182:185], v[214:217], v[0:3]
	v_mfma_f32_16x16x32_bf16 v[52:55], v[170:173], v[194:197], v[52:55]
	v_mfma_f32_16x16x32_bf16 v[48:51], v[186:189], v[194:197], v[48:51]
	v_mfma_f32_16x16x32_bf16 v[36:39], v[170:173], v[202:205], v[36:39]
	v_mfma_f32_16x16x32_bf16 v[32:35], v[186:189], v[202:205], v[32:35]
	v_mfma_f32_16x16x32_bf16 v[20:23], v[170:173], v[210:213], v[20:23]
	v_mfma_f32_16x16x32_bf16 v[16:19], v[186:189], v[210:213], v[16:19]
	v_mfma_f32_16x16x32_bf16 v[4:7], v[170:173], v[224:227], v[4:7]
	v_mfma_f32_16x16x32_bf16 v[0:3], v[186:189], v[224:227], v[0:3]
	s_barrier
	s_setprio 0
	s_add_i32 s50, s50, 2
	s_add_u32 s40, s40, 0x100
	s_addc_u32 s41, s41, 0
	s_cmp_gt_u32 s50, 13
	s_mov_b64 s[6:7], s[8:9]
.LBB0_142:
	ds_read_b128 v[128:131], v175
	ds_read_b128 v[132:135], v175 offset:1024
	ds_read_b128 v[136:139], v175 offset:2048
	ds_read_b128 v[140:143], v175 offset:3072
	ds_read_b128 v[166:169], v176
	ds_read_b128 v[170:173], v176 offset:1024
	ds_read_b128 v[182:185], v176 offset:2048
	ds_read_b128 v[186:189], v176 offset:3072
	s_add_u32 s8, s6, 0x100
	s_addc_u32 s9, s7, 0
	s_cmp_eq_u32 s50, 12
	s_cselect_b32 s89, s5, s9
	s_cselect_b32 s88, s22, s8
	s_cselect_b32 s87, s34, s41
	s_cselect_b32 s86, s35, s40
	v_lshl_add_u64 v[220:221], s[6:7], 0, v[158:159]
	s_add_i32 m0, s61, 0xc000
	ds_read_b128 v[190:193], v177
	ds_read_b128 v[194:197], v177 offset:1024
	ds_read_b128 v[198:201], v177 offset:2048
	ds_read_b128 v[202:205], v177 offset:3072
	ds_read_b128 v[206:209], v177 offset:4096
	ds_read_b128 v[210:213], v177 offset:5120
	ds_read_b128 v[214:217], v177 offset:6144
	ds_read_b128 v[224:227], v177 offset:7168
	global_load_lds_dwordx4 v[220:221], off
	s_add_i32 m0, s61, 0xe000
	v_lshl_add_u64 v[220:221], s[6:7], 0, v[160:161]
	global_load_lds_dwordx4 v[220:221], off
	s_waitcnt vmcnt(8) lgkmcnt(0)
	s_setprio 1
	s_barrier
	v_mfma_f32_16x16x32_bf16 v[124:127], v[128:131], v[190:193], v[124:127]
	v_mfma_f32_16x16x32_bf16 v[120:123], v[136:139], v[190:193], v[120:123]
	v_mfma_f32_16x16x32_bf16 v[108:111], v[128:131], v[198:201], v[108:111]
	v_mfma_f32_16x16x32_bf16 v[104:107], v[136:139], v[198:201], v[104:107]
	v_mfma_f32_16x16x32_bf16 v[92:95], v[128:131], v[206:209], v[92:95]
	v_mfma_f32_16x16x32_bf16 v[88:91], v[136:139], v[206:209], v[88:91]
	v_mfma_f32_16x16x32_bf16 v[76:79], v[128:131], v[214:217], v[76:79]
	v_mfma_f32_16x16x32_bf16 v[72:75], v[136:139], v[214:217], v[72:75]
	v_mfma_f32_16x16x32_bf16 v[124:127], v[132:135], v[194:197], v[124:127]
	v_mfma_f32_16x16x32_bf16 v[120:123], v[140:143], v[194:197], v[120:123]
	v_mfma_f32_16x16x32_bf16 v[108:111], v[132:135], v[202:205], v[108:111]
	v_mfma_f32_16x16x32_bf16 v[104:107], v[140:143], v[202:205], v[104:107]
	v_mfma_f32_16x16x32_bf16 v[92:95], v[132:135], v[210:213], v[92:95]
	v_mfma_f32_16x16x32_bf16 v[88:91], v[140:143], v[210:213], v[88:91]
	v_mfma_f32_16x16x32_bf16 v[76:79], v[132:135], v[224:227], v[76:79]
	v_mfma_f32_16x16x32_bf16 v[72:75], v[140:143], v[224:227], v[72:75]
	v_mfma_f32_16x16x32_bf16 v[116:119], v[166:169], v[190:193], v[116:119]
	v_mfma_f32_16x16x32_bf16 v[112:115], v[182:185], v[190:193], v[112:115]
	v_mfma_f32_16x16x32_bf16 v[100:103], v[166:169], v[198:201], v[100:103]
	v_mfma_f32_16x16x32_bf16 v[96:99], v[182:185], v[198:201], v[96:99]
	v_mfma_f32_16x16x32_bf16 v[84:87], v[166:169], v[206:209], v[84:87]
	v_mfma_f32_16x16x32_bf16 v[80:83], v[182:185], v[206:209], v[80:83]
	v_mfma_f32_16x16x32_bf16 v[68:71], v[166:169], v[214:217], v[68:71]
	v_mfma_f32_16x16x32_bf16 v[64:67], v[182:185], v[214:217], v[64:67]
	v_mfma_f32_16x16x32_bf16 v[116:119], v[170:173], v[194:197], v[116:119]
	v_mfma_f32_16x16x32_bf16 v[112:115], v[186:189], v[194:197], v[112:115]
	v_mfma_f32_16x16x32_bf16 v[100:103], v[170:173], v[202:205], v[100:103]
	v_mfma_f32_16x16x32_bf16 v[96:99], v[186:189], v[202:205], v[96:99]
	v_mfma_f32_16x16x32_bf16 v[84:87], v[170:173], v[210:213], v[84:87]
	v_mfma_f32_16x16x32_bf16 v[80:83], v[186:189], v[210:213], v[80:83]
	v_mfma_f32_16x16x32_bf16 v[68:71], v[170:173], v[224:227], v[68:71]
	v_mfma_f32_16x16x32_bf16 v[64:67], v[186:189], v[224:227], v[64:67]
	s_barrier
	s_setprio 0
	s_add_i32 s6, s37, s59
	v_lshl_add_u64 v[220:221], s[86:87], 0, v[148:149]
	s_mov_b32 m0, s6
	ds_read_b128 v[190:193], v177 offset:16384
	ds_read_b128 v[194:197], v177 offset:17408
	ds_read_b128 v[198:201], v177 offset:18432
	ds_read_b128 v[202:205], v177 offset:19456
	ds_read_b128 v[206:209], v177 offset:20480
	ds_read_b128 v[210:213], v177 offset:21504
	ds_read_b128 v[214:217], v177 offset:22528
	ds_read_b128 v[224:227], v177 offset:23552
	global_load_lds_dwordx4 v[220:221], off
	s_add_i32 m0, s6, 0x2000
	s_add_u32 s6, s86, 0x40000
	v_lshl_add_u64 v[228:229], s[86:87], 0, v[152:153]
	s_addc_u32 s7, s87, 0
	s_add_i32 s51, s97, s59
	global_load_lds_dwordx4 v[228:229], off
	v_lshl_add_u64 v[230:231], s[6:7], 0, v[148:149]
	s_mov_b32 m0, s51
	v_lshl_add_u64 v[232:233], s[88:89], 0, v[150:151]
	global_load_lds_dwordx4 v[230:231], off
	v_lshl_add_u64 v[230:231], s[6:7], 0, v[152:153]
	s_add_i32 m0, s51, 0x2000
	v_lshl_add_u64 v[234:235], v[232:233], 0, s[68:69]
	global_load_lds_dwordx4 v[230:231], off
	s_mov_b32 m0, s61
	v_lshl_add_u64 v[230:231], s[88:89], 0, v[146:147]
	global_load_lds_dwordx4 v[230:231], off
	s_mov_b32 m0, s63
	s_nop 0
	global_load_lds_dwordx4 v[234:235], off
	s_waitcnt vmcnt(8) lgkmcnt(0)
	s_setprio 1
	s_barrier
	v_mfma_f32_16x16x32_bf16 v[60:63], v[128:131], v[190:193], v[60:63]
	v_mfma_f32_16x16x32_bf16 v[56:59], v[136:139], v[190:193], v[56:59]
	v_mfma_f32_16x16x32_bf16 v[44:47], v[128:131], v[198:201], v[44:47]
	v_mfma_f32_16x16x32_bf16 v[40:43], v[136:139], v[198:201], v[40:43]
	v_mfma_f32_16x16x32_bf16 v[28:31], v[128:131], v[206:209], v[28:31]
	v_mfma_f32_16x16x32_bf16 v[24:27], v[136:139], v[206:209], v[24:27]
	v_mfma_f32_16x16x32_bf16 v[12:15], v[128:131], v[214:217], v[12:15]
	v_mfma_f32_16x16x32_bf16 v[8:11], v[136:139], v[214:217], v[8:11]
	v_mfma_f32_16x16x32_bf16 v[60:63], v[132:135], v[194:197], v[60:63]
	v_mfma_f32_16x16x32_bf16 v[56:59], v[140:143], v[194:197], v[56:59]
	v_mfma_f32_16x16x32_bf16 v[44:47], v[132:135], v[202:205], v[44:47]
	v_mfma_f32_16x16x32_bf16 v[40:43], v[140:143], v[202:205], v[40:43]
	v_mfma_f32_16x16x32_bf16 v[28:31], v[132:135], v[210:213], v[28:31]
	v_mfma_f32_16x16x32_bf16 v[24:27], v[140:143], v[210:213], v[24:27]
	v_mfma_f32_16x16x32_bf16 v[12:15], v[132:135], v[224:227], v[12:15]
	v_mfma_f32_16x16x32_bf16 v[8:11], v[140:143], v[224:227], v[8:11]
	v_mfma_f32_16x16x32_bf16 v[52:55], v[166:169], v[190:193], v[52:55]
	v_mfma_f32_16x16x32_bf16 v[48:51], v[182:185], v[190:193], v[48:51]
	v_mfma_f32_16x16x32_bf16 v[36:39], v[166:169], v[198:201], v[36:39]
	v_mfma_f32_16x16x32_bf16 v[32:35], v[182:185], v[198:201], v[32:35]
	v_mfma_f32_16x16x32_bf16 v[20:23], v[166:169], v[206:209], v[20:23]
	v_mfma_f32_16x16x32_bf16 v[16:19], v[182:185], v[206:209], v[16:19]
	v_mfma_f32_16x16x32_bf16 v[4:7], v[166:169], v[214:217], v[4:7]
	v_mfma_f32_16x16x32_bf16 v[0:3], v[182:185], v[214:217], v[0:3]
	v_mfma_f32_16x16x32_bf16 v[52:55], v[170:173], v[194:197], v[52:55]
	v_mfma_f32_16x16x32_bf16 v[48:51], v[186:189], v[194:197], v[48:51]
	v_mfma_f32_16x16x32_bf16 v[36:39], v[170:173], v[202:205], v[36:39]
	v_mfma_f32_16x16x32_bf16 v[32:35], v[186:189], v[202:205], v[32:35]
	v_mfma_f32_16x16x32_bf16 v[20:23], v[170:173], v[210:213], v[20:23]
	v_mfma_f32_16x16x32_bf16 v[16:19], v[186:189], v[210:213], v[16:19]
	v_mfma_f32_16x16x32_bf16 v[4:7], v[170:173], v[224:227], v[4:7]
	v_mfma_f32_16x16x32_bf16 v[0:3], v[186:189], v[224:227], v[0:3]
	s_barrier
	s_setprio 0
	s_add_i32 s6, 0, 0x18000
	s_add_i32 s51, 0, 0x1c000
	v_add_u32_e32 v140, s6, v174
	v_add_u32_e32 v154, s51, v174
	ds_read_b128 v[128:131], v140
	ds_read_b128 v[132:135], v140 offset:1024
	ds_read_b128 v[136:139], v140 offset:2048
	ds_read_b128 v[140:143], v140 offset:3072
	ds_read_b128 v[166:169], v154
	ds_read_b128 v[170:173], v154 offset:1024
	ds_read_b128 v[182:185], v154 offset:2048
	ds_read_b128 v[186:189], v154 offset:3072
	s_mov_b32 m0, s65
	v_lshl_add_u64 v[234:235], v[230:231], 0, s[66:67]
	ds_read_b128 v[190:193], v177 offset:32768
	ds_read_b128 v[194:197], v177 offset:33792
	ds_read_b128 v[198:201], v177 offset:34816
	ds_read_b128 v[202:205], v177 offset:35840
	ds_read_b128 v[206:209], v177 offset:36864
	ds_read_b128 v[210:213], v177 offset:37888
	ds_read_b128 v[214:217], v177 offset:38912
	ds_read_b128 v[224:227], v177 offset:39936
	global_load_lds_dwordx4 v[234:235], off
	s_mov_b32 m0, s77
	v_lshl_add_u64 v[234:235], v[232:233], 0, s[46:47]
	global_load_lds_dwordx4 v[234:235], off
	s_waitcnt vmcnt(8) lgkmcnt(0)
	s_setprio 1
	s_barrier
	v_mfma_f32_16x16x32_bf16 v[124:127], v[128:131], v[190:193], v[124:127]
	v_mfma_f32_16x16x32_bf16 v[120:123], v[136:139], v[190:193], v[120:123]
	v_mfma_f32_16x16x32_bf16 v[108:111], v[128:131], v[198:201], v[108:111]
	v_mfma_f32_16x16x32_bf16 v[104:107], v[136:139], v[198:201], v[104:107]
	v_mfma_f32_16x16x32_bf16 v[92:95], v[128:131], v[206:209], v[92:95]
	v_mfma_f32_16x16x32_bf16 v[88:91], v[136:139], v[206:209], v[88:91]
	v_mfma_f32_16x16x32_bf16 v[76:79], v[128:131], v[214:217], v[76:79]
	v_mfma_f32_16x16x32_bf16 v[72:75], v[136:139], v[214:217], v[72:75]
	v_mfma_f32_16x16x32_bf16 v[124:127], v[132:135], v[194:197], v[124:127]
	v_mfma_f32_16x16x32_bf16 v[120:123], v[140:143], v[194:197], v[120:123]
	v_mfma_f32_16x16x32_bf16 v[108:111], v[132:135], v[202:205], v[108:111]
	v_mfma_f32_16x16x32_bf16 v[104:107], v[140:143], v[202:205], v[104:107]
	v_mfma_f32_16x16x32_bf16 v[92:95], v[132:135], v[210:213], v[92:95]
	v_mfma_f32_16x16x32_bf16 v[88:91], v[140:143], v[210:213], v[88:91]
	v_mfma_f32_16x16x32_bf16 v[76:79], v[132:135], v[224:227], v[76:79]
	v_mfma_f32_16x16x32_bf16 v[72:75], v[140:143], v[224:227], v[72:75]
	v_mfma_f32_16x16x32_bf16 v[116:119], v[166:169], v[190:193], v[116:119]
	v_mfma_f32_16x16x32_bf16 v[112:115], v[182:185], v[190:193], v[112:115]
	v_mfma_f32_16x16x32_bf16 v[100:103], v[166:169], v[198:201], v[100:103]
	v_mfma_f32_16x16x32_bf16 v[96:99], v[182:185], v[198:201], v[96:99]
	v_mfma_f32_16x16x32_bf16 v[84:87], v[166:169], v[206:209], v[84:87]
	v_mfma_f32_16x16x32_bf16 v[80:83], v[182:185], v[206:209], v[80:83]
	v_mfma_f32_16x16x32_bf16 v[68:71], v[166:169], v[214:217], v[68:71]
	v_mfma_f32_16x16x32_bf16 v[64:67], v[182:185], v[214:217], v[64:67]
	v_mfma_f32_16x16x32_bf16 v[116:119], v[170:173], v[194:197], v[116:119]
	v_mfma_f32_16x16x32_bf16 v[112:115], v[186:189], v[194:197], v[112:115]
	v_mfma_f32_16x16x32_bf16 v[100:103], v[170:173], v[202:205], v[100:103]
	v_mfma_f32_16x16x32_bf16 v[96:99], v[186:189], v[202:205], v[96:99]
	v_mfma_f32_16x16x32_bf16 v[84:87], v[170:173], v[210:213], v[84:87]
	v_mfma_f32_16x16x32_bf16 v[80:83], v[186:189], v[210:213], v[80:83]
	v_mfma_f32_16x16x32_bf16 v[68:71], v[170:173], v[224:227], v[68:71]
	v_mfma_f32_16x16x32_bf16 v[64:67], v[186:189], v[224:227], v[64:67]
	s_barrier
	s_setprio 0
	s_add_i32 s6, s6, s59
	v_lshl_add_u64 v[220:221], v[220:221], 0, s[42:43]
	s_mov_b32 m0, s6
	ds_read_b128 v[190:193], v177 offset:49152
	ds_read_b128 v[194:197], v177 offset:50176
	ds_read_b128 v[198:201], v177 offset:51200
	ds_read_b128 v[202:205], v177 offset:52224
	ds_read_b128 v[206:209], v177 offset:53248
	ds_read_b128 v[210:213], v177 offset:54272
	ds_read_b128 v[214:217], v177 offset:55296
	ds_read_b128 v[224:227], v177 offset:56320
	global_load_lds_dwordx4 v[220:221], off
	s_add_i32 m0, s6, 0x2000
	s_add_u32 s6, s86, 0x40080
	v_lshl_add_u64 v[220:221], v[228:229], 0, s[42:43]
	s_addc_u32 s7, s87, 0
	s_add_i32 s51, s51, s59
	global_load_lds_dwordx4 v[220:221], off
	s_mov_b32 m0, s51
	v_lshl_add_u64 v[220:221], s[6:7], 0, v[148:149]
	global_load_lds_dwordx4 v[220:221], off
	s_add_i32 m0, s51, 0x2000
	v_lshl_add_u64 v[220:221], s[6:7], 0, v[152:153]
	global_load_lds_dwordx4 v[220:221], off
	s_mov_b32 m0, s91
	v_lshl_add_u64 v[220:221], v[230:231], 0, s[42:43]
	global_load_lds_dwordx4 v[220:221], off
	s_mov_b32 m0, s92
	v_lshl_add_u64 v[220:221], v[232:233], 0, s[44:45]
	global_load_lds_dwordx4 v[220:221], off
	s_waitcnt vmcnt(8) lgkmcnt(0)
	s_setprio 1
	s_barrier
	v_mfma_f32_16x16x32_bf16 v[60:63], v[128:131], v[190:193], v[60:63]
	v_mfma_f32_16x16x32_bf16 v[56:59], v[136:139], v[190:193], v[56:59]
	v_mfma_f32_16x16x32_bf16 v[44:47], v[128:131], v[198:201], v[44:47]
	v_mfma_f32_16x16x32_bf16 v[40:43], v[136:139], v[198:201], v[40:43]
	v_mfma_f32_16x16x32_bf16 v[28:31], v[128:131], v[206:209], v[28:31]
	v_mfma_f32_16x16x32_bf16 v[24:27], v[136:139], v[206:209], v[24:27]
	v_mfma_f32_16x16x32_bf16 v[12:15], v[128:131], v[214:217], v[12:15]
	v_mfma_f32_16x16x32_bf16 v[8:11], v[136:139], v[214:217], v[8:11]
	v_mfma_f32_16x16x32_bf16 v[60:63], v[132:135], v[194:197], v[60:63]
	v_mfma_f32_16x16x32_bf16 v[56:59], v[140:143], v[194:197], v[56:59]
	v_mfma_f32_16x16x32_bf16 v[44:47], v[132:135], v[202:205], v[44:47]
	v_mfma_f32_16x16x32_bf16 v[40:43], v[140:143], v[202:205], v[40:43]
	v_mfma_f32_16x16x32_bf16 v[28:31], v[132:135], v[210:213], v[28:31]
	v_mfma_f32_16x16x32_bf16 v[24:27], v[140:143], v[210:213], v[24:27]
	v_mfma_f32_16x16x32_bf16 v[12:15], v[132:135], v[224:227], v[12:15]
	v_mfma_f32_16x16x32_bf16 v[8:11], v[140:143], v[224:227], v[8:11]
	v_mfma_f32_16x16x32_bf16 v[52:55], v[166:169], v[190:193], v[52:55]
	v_mfma_f32_16x16x32_bf16 v[48:51], v[182:185], v[190:193], v[48:51]
	v_mfma_f32_16x16x32_bf16 v[36:39], v[166:169], v[198:201], v[36:39]
	v_mfma_f32_16x16x32_bf16 v[32:35], v[182:185], v[198:201], v[32:35]
	v_mfma_f32_16x16x32_bf16 v[20:23], v[166:169], v[206:209], v[20:23]
	v_mfma_f32_16x16x32_bf16 v[16:19], v[182:185], v[206:209], v[16:19]
	v_mfma_f32_16x16x32_bf16 v[4:7], v[166:169], v[214:217], v[4:7]
	v_mfma_f32_16x16x32_bf16 v[0:3], v[182:185], v[214:217], v[0:3]
	v_mfma_f32_16x16x32_bf16 v[52:55], v[170:173], v[194:197], v[52:55]
	v_mfma_f32_16x16x32_bf16 v[48:51], v[186:189], v[194:197], v[48:51]
	v_mfma_f32_16x16x32_bf16 v[36:39], v[170:173], v[202:205], v[36:39]
	v_mfma_f32_16x16x32_bf16 v[32:35], v[186:189], v[202:205], v[32:35]
	v_mfma_f32_16x16x32_bf16 v[20:23], v[170:173], v[210:213], v[20:23]
	v_mfma_f32_16x16x32_bf16 v[16:19], v[186:189], v[210:213], v[16:19]
	v_mfma_f32_16x16x32_bf16 v[4:7], v[170:173], v[224:227], v[4:7]
	v_mfma_f32_16x16x32_bf16 v[0:3], v[186:189], v[224:227], v[0:3]
	s_barrier
	s_setprio 0
	s_add_i32 s50, s50, 2
	s_add_u32 s40, s40, 0x100
	s_addc_u32 s41, s41, 0
	s_cmp_gt_u32 s50, 13
	s_mov_b64 s[6:7], s[8:9]
	s_cbranch_scc0 .LBB0_142
	v_readlane_b32 s6, v249, 60
	v_readlane_b32 s7, v249, 61
	s_and_b64 vcc, exec, s[6:7]
	s_cbranch_vccz .LBB0_145
	s_barrier

.LBB0_392:
	s_lshl_b32 s40, s65, 8
	v_readlane_b32 s72, v249, 0
	s_ashr_i32 s41, s40, 31
	v_readlane_b32 s84, v249, 12
	v_readlane_b32 s85, v249, 13
	s_lshl_b64 s[40:41], s[40:41], 10
	v_readlane_b32 s86, v249, 14
	v_readlane_b32 s87, v249, 15
	s_mov_b64 s[28:29], s[84:85]
	s_add_u32 s40, s28, s40
	s_addc_u32 s41, s29, s41
	s_and_b64 s[42:43], s[0:1], exec
	s_cselect_b32 s67, s41, s45
	s_cselect_b32 s72, s40, s44
	s_ashr_i32 s39, s38, 31
	s_lshl_b64 s[42:43], s[38:39], 18
	s_add_u32 s42, s10, s42
	s_addc_u32 s43, s11, s43
	s_and_b64 s[48:49], s[0:1], exec
	v_readlane_b32 s73, v249, 1
	v_readlane_b32 s74, v249, 2
	s_cselect_b32 s39, s43, s47
	s_cselect_b32 s50, s42, s46
	s_add_u32 s51, s46, 0x100
	s_addc_u32 s73, s47, 0
	s_mov_b32 s74, -2
	s_waitcnt vmcnt(0)
	s_waitcnt lgkmcnt(0)
	v_readlane_b32 s75, v249, 3
	v_readlane_b32 s76, v249, 4
	v_readlane_b32 s77, v249, 5
	v_readlane_b32 s78, v249, 6
	v_readlane_b32 s79, v249, 7
	v_readlane_b32 s80, v249, 8
	v_readlane_b32 s81, v249, 9
	v_readlane_b32 s82, v249, 10
	v_readlane_b32 s83, v249, 11
	s_mov_b64 s[30:31], s[86:87]
	ds_read_b128 v[144:147], v153
	ds_read_b128 v[156:159], v153 offset:1024
	ds_read_b128 v[160:163], v153 offset:2048
	ds_read_b128 v[164:167], v153 offset:3072
	ds_read_b128 v[168:171], v154
	ds_read_b128 v[172:175], v154 offset:1024
	ds_read_b128 v[176:179], v154 offset:2048
	ds_read_b128 v[180:183], v154 offset:3072
	s_add_u32 s46, s44, 0x100
	s_addc_u32 s47, s45, 0
	s_cmp_eq_u32 s74, 4
	s_cselect_b32 s77, s67, s47
	s_cselect_b32 s76, s72, s46
	s_cselect_b32 s49, s39, s73
	s_cselect_b32 s48, s50, s51
	v_lshl_add_u64 v[148:149], s[44:45], 0, v[136:137]
	s_add_i32 m0, s52, 0xc000
	ds_read_b128 v[184:187], v155
	ds_read_b128 v[188:191], v155 offset:1024
	ds_read_b128 v[192:195], v155 offset:2048
	ds_read_b128 v[196:199], v155 offset:3072
	ds_read_b128 v[200:203], v155 offset:4096
	ds_read_b128 v[204:207], v155 offset:5120
	ds_read_b128 v[208:211], v155 offset:6144
	ds_read_b128 v[212:215], v155 offset:7168
	global_load_lds_dwordx4 v[148:149], off
	s_add_i32 m0, s52, 0xe000
	v_lshl_add_u64 v[148:149], s[44:45], 0, v[138:139]
	global_load_lds_dwordx4 v[148:149], off
	s_waitcnt vmcnt(8) lgkmcnt(0)
	s_setprio 1
	s_barrier
	v_mfma_f32_16x16x32_bf16 v[124:127], v[144:147], v[184:187], 0
	v_mfma_f32_16x16x32_bf16 v[120:123], v[160:163], v[184:187], 0
	v_mfma_f32_16x16x32_bf16 v[108:111], v[144:147], v[192:195], 0
	v_mfma_f32_16x16x32_bf16 v[104:107], v[160:163], v[192:195], 0
	v_mfma_f32_16x16x32_bf16 v[92:95], v[144:147], v[200:203], 0
	v_mfma_f32_16x16x32_bf16 v[88:91], v[160:163], v[200:203], 0
	v_mfma_f32_16x16x32_bf16 v[76:79], v[144:147], v[208:211], 0
	v_mfma_f32_16x16x32_bf16 v[72:75], v[160:163], v[208:211], 0
	v_mfma_f32_16x16x32_bf16 v[124:127], v[156:159], v[188:191], v[124:127]
	v_mfma_f32_16x16x32_bf16 v[120:123], v[164:167], v[188:191], v[120:123]
	v_mfma_f32_16x16x32_bf16 v[108:111], v[156:159], v[196:199], v[108:111]
	v_mfma_f32_16x16x32_bf16 v[104:107], v[164:167], v[196:199], v[104:107]
	v_mfma_f32_16x16x32_bf16 v[92:95], v[156:159], v[204:207], v[92:95]
	v_mfma_f32_16x16x32_bf16 v[88:91], v[164:167], v[204:207], v[88:91]
	v_mfma_f32_16x16x32_bf16 v[76:79], v[156:159], v[212:215], v[76:79]
	v_mfma_f32_16x16x32_bf16 v[72:75], v[164:167], v[212:215], v[72:75]
	v_mfma_f32_16x16x32_bf16 v[116:119], v[168:171], v[184:187], 0
	v_mfma_f32_16x16x32_bf16 v[112:115], v[176:179], v[184:187], 0
	v_mfma_f32_16x16x32_bf16 v[100:103], v[168:171], v[192:195], 0
	v_mfma_f32_16x16x32_bf16 v[96:99], v[176:179], v[192:195], 0
	v_mfma_f32_16x16x32_bf16 v[84:87], v[168:171], v[200:203], 0
	v_mfma_f32_16x16x32_bf16 v[80:83], v[176:179], v[200:203], 0
	v_mfma_f32_16x16x32_bf16 v[68:71], v[168:171], v[208:211], 0
	v_mfma_f32_16x16x32_bf16 v[64:67], v[176:179], v[208:211], 0
	v_mfma_f32_16x16x32_bf16 v[116:119], v[172:175], v[188:191], v[116:119]
	v_mfma_f32_16x16x32_bf16 v[112:115], v[180:183], v[188:191], v[112:115]
	v_mfma_f32_16x16x32_bf16 v[100:103], v[172:175], v[196:199], v[100:103]
	v_mfma_f32_16x16x32_bf16 v[96:99], v[180:183], v[196:199], v[96:99]
	v_mfma_f32_16x16x32_bf16 v[84:87], v[172:175], v[204:207], v[84:87]
	v_mfma_f32_16x16x32_bf16 v[80:83], v[180:183], v[204:207], v[80:83]
	v_mfma_f32_16x16x32_bf16 v[68:71], v[172:175], v[212:215], v[68:71]
	v_mfma_f32_16x16x32_bf16 v[64:67], v[180:183], v[212:215], v[64:67]
	s_barrier
	s_setprio 0
	s_add_i32 s44, s61, s33
	v_lshl_add_u64 v[148:149], s[48:49], 0, v[132:133]
	s_mov_b32 m0, s44
	ds_read_b128 v[184:187], v155 offset:16384
	ds_read_b128 v[188:191], v155 offset:17408
	ds_read_b128 v[192:195], v155 offset:18432
	ds_read_b128 v[196:199], v155 offset:19456
	ds_read_b128 v[200:203], v155 offset:20480
	ds_read_b128 v[204:207], v155 offset:21504
	ds_read_b128 v[208:211], v155 offset:22528
	ds_read_b128 v[212:215], v155 offset:23552
	global_load_lds_dwordx4 v[148:149], off
	s_add_i32 m0, s44, 0x2000
	s_add_u32 s44, s48, 0x20000
	v_lshl_add_u64 v[216:217], s[48:49], 0, v[128:129]
	s_addc_u32 s45, s49, 0
	s_add_i32 s68, s62, s33
	global_load_lds_dwordx4 v[216:217], off
	v_lshl_add_u64 v[220:221], s[44:45], 0, v[132:133]
	s_mov_b32 m0, s68
	v_lshl_add_u64 v[224:225], s[76:77], 0, v[130:131]
	global_load_lds_dwordx4 v[220:221], off
	v_lshl_add_u64 v[220:221], s[44:45], 0, v[128:129]
	s_add_i32 m0, s68, 0x2000
	v_lshl_add_u64 v[226:227], v[224:225], 0, s[8:9]
	global_load_lds_dwordx4 v[220:221], off
	s_mov_b32 m0, s52
	v_lshl_add_u64 v[220:221], s[76:77], 0, v[134:135]
	global_load_lds_dwordx4 v[220:221], off
	s_mov_b32 m0, s53
	s_nop 0
	global_load_lds_dwordx4 v[226:227], off
	s_waitcnt vmcnt(8) lgkmcnt(0)
	s_setprio 1
	s_barrier
	v_mfma_f32_16x16x32_bf16 v[60:63], v[144:147], v[184:187], 0
	v_mfma_f32_16x16x32_bf16 v[56:59], v[160:163], v[184:187], 0
	v_mfma_f32_16x16x32_bf16 v[44:47], v[144:147], v[192:195], 0
	v_mfma_f32_16x16x32_bf16 v[40:43], v[160:163], v[192:195], 0
	v_mfma_f32_16x16x32_bf16 v[28:31], v[144:147], v[200:203], 0
	v_mfma_f32_16x16x32_bf16 v[24:27], v[160:163], v[200:203], 0
	v_mfma_f32_16x16x32_bf16 v[12:15], v[144:147], v[208:211], 0
	v_mfma_f32_16x16x32_bf16 v[8:11], v[160:163], v[208:211], 0
	v_mfma_f32_16x16x32_bf16 v[60:63], v[156:159], v[188:191], v[60:63]
	v_mfma_f32_16x16x32_bf16 v[56:59], v[164:167], v[188:191], v[56:59]
	v_mfma_f32_16x16x32_bf16 v[44:47], v[156:159], v[196:199], v[44:47]
	v_mfma_f32_16x16x32_bf16 v[40:43], v[164:167], v[196:199], v[40:43]
	v_mfma_f32_16x16x32_bf16 v[28:31], v[156:159], v[204:207], v[28:31]
	v_mfma_f32_16x16x32_bf16 v[24:27], v[164:167], v[204:207], v[24:27]
	v_mfma_f32_16x16x32_bf16 v[12:15], v[156:159], v[212:215], v[12:15]
	v_mfma_f32_16x16x32_bf16 v[8:11], v[164:167], v[212:215], v[8:11]
	v_mfma_f32_16x16x32_bf16 v[52:55], v[168:171], v[184:187], 0
	v_mfma_f32_16x16x32_bf16 v[48:51], v[176:179], v[184:187], 0
	v_mfma_f32_16x16x32_bf16 v[36:39], v[168:171], v[192:195], 0
	v_mfma_f32_16x16x32_bf16 v[32:35], v[176:179], v[192:195], 0
	v_mfma_f32_16x16x32_bf16 v[20:23], v[168:171], v[200:203], 0
	v_mfma_f32_16x16x32_bf16 v[16:19], v[176:179], v[200:203], 0
	v_mfma_f32_16x16x32_bf16 v[4:7], v[168:171], v[208:211], 0
	v_mfma_f32_16x16x32_bf16 v[0:3], v[176:179], v[208:211], 0
	v_mfma_f32_16x16x32_bf16 v[52:55], v[172:175], v[188:191], v[52:55]
	v_mfma_f32_16x16x32_bf16 v[48:51], v[180:183], v[188:191], v[48:51]
	v_mfma_f32_16x16x32_bf16 v[36:39], v[172:175], v[196:199], v[36:39]
	v_mfma_f32_16x16x32_bf16 v[32:35], v[180:183], v[196:199], v[32:35]
	v_mfma_f32_16x16x32_bf16 v[20:23], v[172:175], v[204:207], v[20:23]
	v_mfma_f32_16x16x32_bf16 v[16:19], v[180:183], v[204:207], v[16:19]
	v_mfma_f32_16x16x32_bf16 v[4:7], v[172:175], v[212:215], v[4:7]
	v_mfma_f32_16x16x32_bf16 v[0:3], v[180:183], v[212:215], v[0:3]
	s_barrier
	s_setprio 0
	s_add_i32 s44, 0, 0x18000
	s_add_i32 s68, 0, 0x1c000
	v_add_u32_e32 v164, s44, v151
	v_add_u32_e32 v180, s68, v151
	ds_read_b128 v[144:147], v164
	ds_read_b128 v[156:159], v164 offset:1024
	ds_read_b128 v[160:163], v164 offset:2048
	ds_read_b128 v[164:167], v164 offset:3072
	ds_read_b128 v[168:171], v180
	ds_read_b128 v[172:175], v180 offset:1024
	ds_read_b128 v[176:179], v180 offset:2048
	ds_read_b128 v[180:183], v180 offset:3072
	s_mov_b32 m0, s54
	v_lshl_add_u64 v[226:227], v[220:221], 0, s[6:7]
	ds_read_b128 v[184:187], v155 offset:32768
	ds_read_b128 v[188:191], v155 offset:33792
	ds_read_b128 v[192:195], v155 offset:34816
	ds_read_b128 v[196:199], v155 offset:35840
	ds_read_b128 v[200:203], v155 offset:36864
	ds_read_b128 v[204:207], v155 offset:37888
	ds_read_b128 v[208:211], v155 offset:38912
	ds_read_b128 v[212:215], v155 offset:39936
	global_load_lds_dwordx4 v[226:227], off
	s_mov_b32 m0, s55
	v_lshl_add_u64 v[226:227], v[224:225], 0, s[12:13]
	global_load_lds_dwordx4 v[226:227], off
	s_waitcnt vmcnt(8) lgkmcnt(0)
	s_setprio 1
	s_barrier
	v_mfma_f32_16x16x32_bf16 v[124:127], v[144:147], v[184:187], v[124:127]
	v_mfma_f32_16x16x32_bf16 v[120:123], v[160:163], v[184:187], v[120:123]
	v_mfma_f32_16x16x32_bf16 v[108:111], v[144:147], v[192:195], v[108:111]
	v_mfma_f32_16x16x32_bf16 v[104:107], v[160:163], v[192:195], v[104:107]
	v_mfma_f32_16x16x32_bf16 v[92:95], v[144:147], v[200:203], v[92:95]
	v_mfma_f32_16x16x32_bf16 v[88:91], v[160:163], v[200:203], v[88:91]
	v_mfma_f32_16x16x32_bf16 v[76:79], v[144:147], v[208:211], v[76:79]
	v_mfma_f32_16x16x32_bf16 v[72:75], v[160:163], v[208:211], v[72:75]
	v_mfma_f32_16x16x32_bf16 v[124:127], v[156:159], v[188:191], v[124:127]
	v_mfma_f32_16x16x32_bf16 v[120:123], v[164:167], v[188:191], v[120:123]
	v_mfma_f32_16x16x32_bf16 v[108:111], v[156:159], v[196:199], v[108:111]
	v_mfma_f32_16x16x32_bf16 v[104:107], v[164:167], v[196:199], v[104:107]
	v_mfma_f32_16x16x32_bf16 v[92:95], v[156:159], v[204:207], v[92:95]
	v_mfma_f32_16x16x32_bf16 v[88:91], v[164:167], v[204:207], v[88:91]
	v_mfma_f32_16x16x32_bf16 v[76:79], v[156:159], v[212:215], v[76:79]
	v_mfma_f32_16x16x32_bf16 v[72:75], v[164:167], v[212:215], v[72:75]
	v_mfma_f32_16x16x32_bf16 v[116:119], v[168:171], v[184:187], v[116:119]
	v_mfma_f32_16x16x32_bf16 v[112:115], v[176:179], v[184:187], v[112:115]
	v_mfma_f32_16x16x32_bf16 v[100:103], v[168:171], v[192:195], v[100:103]
	v_mfma_f32_16x16x32_bf16 v[96:99], v[176:179], v[192:195], v[96:99]
	v_mfma_f32_16x16x32_bf16 v[84:87], v[168:171], v[200:203], v[84:87]
	v_mfma_f32_16x16x32_bf16 v[80:83], v[176:179], v[200:203], v[80:83]
	v_mfma_f32_16x16x32_bf16 v[68:71], v[168:171], v[208:211], v[68:71]
	v_mfma_f32_16x16x32_bf16 v[64:67], v[176:179], v[208:211], v[64:67]
	v_mfma_f32_16x16x32_bf16 v[116:119], v[172:175], v[188:191], v[116:119]
	v_mfma_f32_16x16x32_bf16 v[112:115], v[180:183], v[188:191], v[112:115]
	v_mfma_f32_16x16x32_bf16 v[100:103], v[172:175], v[196:199], v[100:103]
	v_mfma_f32_16x16x32_bf16 v[96:99], v[180:183], v[196:199], v[96:99]
	v_mfma_f32_16x16x32_bf16 v[84:87], v[172:175], v[204:207], v[84:87]
	v_mfma_f32_16x16x32_bf16 v[80:83], v[180:183], v[204:207], v[80:83]
	v_mfma_f32_16x16x32_bf16 v[68:71], v[172:175], v[212:215], v[68:71]
	v_mfma_f32_16x16x32_bf16 v[64:67], v[180:183], v[212:215], v[64:67]
	s_barrier
	s_setprio 0
	s_add_i32 s44, s44, s33
	v_lshl_add_u64 v[148:149], v[148:149], 0, s[22:23]
	s_mov_b32 m0, s44
	ds_read_b128 v[184:187], v155 offset:49152
	ds_read_b128 v[188:191], v155 offset:50176
	ds_read_b128 v[192:195], v155 offset:51200
	ds_read_b128 v[196:199], v155 offset:52224
	ds_read_b128 v[200:203], v155 offset:53248
	ds_read_b128 v[204:207], v155 offset:54272
	ds_read_b128 v[208:211], v155 offset:55296
	ds_read_b128 v[212:215], v155 offset:56320
	global_load_lds_dwordx4 v[148:149], off
	s_add_i32 m0, s44, 0x2000
	s_add_u32 s44, s48, 0x20080
	v_lshl_add_u64 v[148:149], v[216:217], 0, s[22:23]
	s_addc_u32 s45, s49, 0
	s_add_i32 s48, s68, s33
	global_load_lds_dwordx4 v[148:149], off
	s_mov_b32 m0, s48
	v_lshl_add_u64 v[148:149], s[44:45], 0, v[132:133]
	global_load_lds_dwordx4 v[148:149], off
	s_add_i32 m0, s48, 0x2000
	v_lshl_add_u64 v[148:149], s[44:45], 0, v[128:129]
	global_load_lds_dwordx4 v[148:149], off
	s_mov_b32 m0, s57
	v_lshl_add_u64 v[148:149], v[220:221], 0, s[22:23]
	global_load_lds_dwordx4 v[148:149], off
	s_mov_b32 m0, s58
	v_lshl_add_u64 v[148:149], v[224:225], 0, s[24:25]
	global_load_lds_dwordx4 v[148:149], off
	s_waitcnt vmcnt(8) lgkmcnt(0)
	s_setprio 1
	s_barrier
	v_mfma_f32_16x16x32_bf16 v[60:63], v[144:147], v[184:187], v[60:63]
	v_mfma_f32_16x16x32_bf16 v[56:59], v[160:163], v[184:187], v[56:59]
	v_mfma_f32_16x16x32_bf16 v[44:47], v[144:147], v[192:195], v[44:47]
	v_mfma_f32_16x16x32_bf16 v[40:43], v[160:163], v[192:195], v[40:43]
	v_mfma_f32_16x16x32_bf16 v[28:31], v[144:147], v[200:203], v[28:31]
	v_mfma_f32_16x16x32_bf16 v[24:27], v[160:163], v[200:203], v[24:27]
	v_mfma_f32_16x16x32_bf16 v[12:15], v[144:147], v[208:211], v[12:15]
	v_mfma_f32_16x16x32_bf16 v[8:11], v[160:163], v[208:211], v[8:11]
	v_mfma_f32_16x16x32_bf16 v[60:63], v[156:159], v[188:191], v[60:63]
	v_mfma_f32_16x16x32_bf16 v[56:59], v[164:167], v[188:191], v[56:59]
	v_mfma_f32_16x16x32_bf16 v[44:47], v[156:159], v[196:199], v[44:47]
	v_mfma_f32_16x16x32_bf16 v[40:43], v[164:167], v[196:199], v[40:43]
	v_mfma_f32_16x16x32_bf16 v[28:31], v[156:159], v[204:207], v[28:31]
	v_mfma_f32_16x16x32_bf16 v[24:27], v[164:167], v[204:207], v[24:27]
	v_mfma_f32_16x16x32_bf16 v[12:15], v[156:159], v[212:215], v[12:15]
	v_mfma_f32_16x16x32_bf16 v[8:11], v[164:167], v[212:215], v[8:11]
	v_mfma_f32_16x16x32_bf16 v[52:55], v[168:171], v[184:187], v[52:55]
	v_mfma_f32_16x16x32_bf16 v[48:51], v[176:179], v[184:187], v[48:51]
	v_mfma_f32_16x16x32_bf16 v[36:39], v[168:171], v[192:195], v[36:39]
	v_mfma_f32_16x16x32_bf16 v[32:35], v[176:179], v[192:195], v[32:35]
	v_mfma_f32_16x16x32_bf16 v[20:23], v[168:171], v[200:203], v[20:23]
	v_mfma_f32_16x16x32_bf16 v[16:19], v[176:179], v[200:203], v[16:19]
	v_mfma_f32_16x16x32_bf16 v[4:7], v[168:171], v[208:211], v[4:7]
	v_mfma_f32_16x16x32_bf16 v[0:3], v[176:179], v[208:211], v[0:3]
	v_mfma_f32_16x16x32_bf16 v[52:55], v[172:175], v[188:191], v[52:55]
	v_mfma_f32_16x16x32_bf16 v[48:51], v[180:183], v[188:191], v[48:51]
	v_mfma_f32_16x16x32_bf16 v[36:39], v[172:175], v[196:199], v[36:39]
	v_mfma_f32_16x16x32_bf16 v[32:35], v[180:183], v[196:199], v[32:35]
	v_mfma_f32_16x16x32_bf16 v[20:23], v[172:175], v[204:207], v[20:23]
	v_mfma_f32_16x16x32_bf16 v[16:19], v[180:183], v[204:207], v[16:19]
	v_mfma_f32_16x16x32_bf16 v[4:7], v[172:175], v[212:215], v[4:7]
	v_mfma_f32_16x16x32_bf16 v[0:3], v[180:183], v[212:215], v[0:3]
	s_barrier
	s_setprio 0
	s_add_i32 s74, s74, 2
	s_add_u32 s51, s51, 0x100
	s_addc_u32 s73, s73, 0
	s_cmp_gt_u32 s74, 5
	s_mov_b64 s[44:45], s[46:47]
.LBB0_393:
	ds_read_b128 v[144:147], v153
	ds_read_b128 v[156:159], v153 offset:1024
	ds_read_b128 v[160:163], v153 offset:2048
	ds_read_b128 v[164:167], v153 offset:3072
	ds_read_b128 v[168:171], v154
	ds_read_b128 v[172:175], v154 offset:1024
	ds_read_b128 v[176:179], v154 offset:2048
	ds_read_b128 v[180:183], v154 offset:3072
	s_add_u32 s46, s44, 0x100
	s_addc_u32 s47, s45, 0
	s_cmp_eq_u32 s74, 4
	s_cselect_b32 s77, s67, s47
	s_cselect_b32 s76, s72, s46
	s_cselect_b32 s49, s39, s73
	s_cselect_b32 s48, s50, s51
	v_lshl_add_u64 v[148:149], s[44:45], 0, v[136:137]
	s_add_i32 m0, s52, 0xc000
	ds_read_b128 v[184:187], v155
	ds_read_b128 v[188:191], v155 offset:1024
	ds_read_b128 v[192:195], v155 offset:2048
	ds_read_b128 v[196:199], v155 offset:3072
	ds_read_b128 v[200:203], v155 offset:4096
	ds_read_b128 v[204:207], v155 offset:5120
	ds_read_b128 v[208:211], v155 offset:6144
	ds_read_b128 v[212:215], v155 offset:7168
	global_load_lds_dwordx4 v[148:149], off
	s_add_i32 m0, s52, 0xe000
	v_lshl_add_u64 v[148:149], s[44:45], 0, v[138:139]
	global_load_lds_dwordx4 v[148:149], off
	s_waitcnt vmcnt(8) lgkmcnt(0)
	s_setprio 1
	s_barrier
	v_mfma_f32_16x16x32_bf16 v[124:127], v[144:147], v[184:187], v[124:127]
	v_mfma_f32_16x16x32_bf16 v[120:123], v[160:163], v[184:187], v[120:123]
	v_mfma_f32_16x16x32_bf16 v[108:111], v[144:147], v[192:195], v[108:111]
	v_mfma_f32_16x16x32_bf16 v[104:107], v[160:163], v[192:195], v[104:107]
	v_mfma_f32_16x16x32_bf16 v[92:95], v[144:147], v[200:203], v[92:95]
	v_mfma_f32_16x16x32_bf16 v[88:91], v[160:163], v[200:203], v[88:91]
	v_mfma_f32_16x16x32_bf16 v[76:79], v[144:147], v[208:211], v[76:79]
	v_mfma_f32_16x16x32_bf16 v[72:75], v[160:163], v[208:211], v[72:75]
	v_mfma_f32_16x16x32_bf16 v[124:127], v[156:159], v[188:191], v[124:127]
	v_mfma_f32_16x16x32_bf16 v[120:123], v[164:167], v[188:191], v[120:123]
	v_mfma_f32_16x16x32_bf16 v[108:111], v[156:159], v[196:199], v[108:111]
	v_mfma_f32_16x16x32_bf16 v[104:107], v[164:167], v[196:199], v[104:107]
	v_mfma_f32_16x16x32_bf16 v[92:95], v[156:159], v[204:207], v[92:95]
	v_mfma_f32_16x16x32_bf16 v[88:91], v[164:167], v[204:207], v[88:91]
	v_mfma_f32_16x16x32_bf16 v[76:79], v[156:159], v[212:215], v[76:79]
	v_mfma_f32_16x16x32_bf16 v[72:75], v[164:167], v[212:215], v[72:75]
	v_mfma_f32_16x16x32_bf16 v[116:119], v[168:171], v[184:187], v[116:119]
	v_mfma_f32_16x16x32_bf16 v[112:115], v[176:179], v[184:187], v[112:115]
	v_mfma_f32_16x16x32_bf16 v[100:103], v[168:171], v[192:195], v[100:103]
	v_mfma_f32_16x16x32_bf16 v[96:99], v[176:179], v[192:195], v[96:99]
	v_mfma_f32_16x16x32_bf16 v[84:87], v[168:171], v[200:203], v[84:87]
	v_mfma_f32_16x16x32_bf16 v[80:83], v[176:179], v[200:203], v[80:83]
	v_mfma_f32_16x16x32_bf16 v[68:71], v[168:171], v[208:211], v[68:71]
	v_mfma_f32_16x16x32_bf16 v[64:67], v[176:179], v[208:211], v[64:67]
	v_mfma_f32_16x16x32_bf16 v[116:119], v[172:175], v[188:191], v[116:119]
	v_mfma_f32_16x16x32_bf16 v[112:115], v[180:183], v[188:191], v[112:115]
	v_mfma_f32_16x16x32_bf16 v[100:103], v[172:175], v[196:199], v[100:103]
	v_mfma_f32_16x16x32_bf16 v[96:99], v[180:183], v[196:199], v[96:99]
	v_mfma_f32_16x16x32_bf16 v[84:87], v[172:175], v[204:207], v[84:87]
	v_mfma_f32_16x16x32_bf16 v[80:83], v[180:183], v[204:207], v[80:83]
	v_mfma_f32_16x16x32_bf16 v[68:71], v[172:175], v[212:215], v[68:71]
	v_mfma_f32_16x16x32_bf16 v[64:67], v[180:183], v[212:215], v[64:67]
	s_barrier
	s_setprio 0
	s_add_i32 s44, s61, s33
	v_lshl_add_u64 v[148:149], s[48:49], 0, v[132:133]
	s_mov_b32 m0, s44
	ds_read_b128 v[184:187], v155 offset:16384
	ds_read_b128 v[188:191], v155 offset:17408
	ds_read_b128 v[192:195], v155 offset:18432
	ds_read_b128 v[196:199], v155 offset:19456
	ds_read_b128 v[200:203], v155 offset:20480
	ds_read_b128 v[204:207], v155 offset:21504
	ds_read_b128 v[208:211], v155 offset:22528
	ds_read_b128 v[212:215], v155 offset:23552
	global_load_lds_dwordx4 v[148:149], off
	s_add_i32 m0, s44, 0x2000
	s_add_u32 s44, s48, 0x20000
	v_lshl_add_u64 v[216:217], s[48:49], 0, v[128:129]
	s_addc_u32 s45, s49, 0
	s_add_i32 s68, s62, s33
	global_load_lds_dwordx4 v[216:217], off
	v_lshl_add_u64 v[220:221], s[44:45], 0, v[132:133]
	s_mov_b32 m0, s68
	v_lshl_add_u64 v[224:225], s[76:77], 0, v[130:131]
	global_load_lds_dwordx4 v[220:221], off
	v_lshl_add_u64 v[220:221], s[44:45], 0, v[128:129]
	s_add_i32 m0, s68, 0x2000
	v_lshl_add_u64 v[226:227], v[224:225], 0, s[8:9]
	global_load_lds_dwordx4 v[220:221], off
	s_mov_b32 m0, s52
	v_lshl_add_u64 v[220:221], s[76:77], 0, v[134:135]
	global_load_lds_dwordx4 v[220:221], off
	s_mov_b32 m0, s53
	s_nop 0
	global_load_lds_dwordx4 v[226:227], off
	s_waitcnt vmcnt(8) lgkmcnt(0)
	s_setprio 1
	s_barrier
	v_mfma_f32_16x16x32_bf16 v[60:63], v[144:147], v[184:187], v[60:63]
	v_mfma_f32_16x16x32_bf16 v[56:59], v[160:163], v[184:187], v[56:59]
	v_mfma_f32_16x16x32_bf16 v[44:47], v[144:147], v[192:195], v[44:47]
	v_mfma_f32_16x16x32_bf16 v[40:43], v[160:163], v[192:195], v[40:43]
	v_mfma_f32_16x16x32_bf16 v[28:31], v[144:147], v[200:203], v[28:31]
	v_mfma_f32_16x16x32_bf16 v[24:27], v[160:163], v[200:203], v[24:27]
	v_mfma_f32_16x16x32_bf16 v[12:15], v[144:147], v[208:211], v[12:15]
	v_mfma_f32_16x16x32_bf16 v[8:11], v[160:163], v[208:211], v[8:11]
	v_mfma_f32_16x16x32_bf16 v[60:63], v[156:159], v[188:191], v[60:63]
	v_mfma_f32_16x16x32_bf16 v[56:59], v[164:167], v[188:191], v[56:59]
	v_mfma_f32_16x16x32_bf16 v[44:47], v[156:159], v[196:199], v[44:47]
	v_mfma_f32_16x16x32_bf16 v[40:43], v[164:167], v[196:199], v[40:43]
	v_mfma_f32_16x16x32_bf16 v[28:31], v[156:159], v[204:207], v[28:31]
	v_mfma_f32_16x16x32_bf16 v[24:27], v[164:167], v[204:207], v[24:27]
	v_mfma_f32_16x16x32_bf16 v[12:15], v[156:159], v[212:215], v[12:15]
	v_mfma_f32_16x16x32_bf16 v[8:11], v[164:167], v[212:215], v[8:11]
	v_mfma_f32_16x16x32_bf16 v[52:55], v[168:171], v[184:187], v[52:55]
	v_mfma_f32_16x16x32_bf16 v[48:51], v[176:179], v[184:187], v[48:51]
	v_mfma_f32_16x16x32_bf16 v[36:39], v[168:171], v[192:195], v[36:39]
	v_mfma_f32_16x16x32_bf16 v[32:35], v[176:179], v[192:195], v[32:35]
	v_mfma_f32_16x16x32_bf16 v[20:23], v[168:171], v[200:203], v[20:23]
	v_mfma_f32_16x16x32_bf16 v[16:19], v[176:179], v[200:203], v[16:19]
	v_mfma_f32_16x16x32_bf16 v[4:7], v[168:171], v[208:211], v[4:7]
	v_mfma_f32_16x16x32_bf16 v[0:3], v[176:179], v[208:211], v[0:3]
	v_mfma_f32_16x16x32_bf16 v[52:55], v[172:175], v[188:191], v[52:55]
	v_mfma_f32_16x16x32_bf16 v[48:51], v[180:183], v[188:191], v[48:51]
	v_mfma_f32_16x16x32_bf16 v[36:39], v[172:175], v[196:199], v[36:39]
	v_mfma_f32_16x16x32_bf16 v[32:35], v[180:183], v[196:199], v[32:35]
	v_mfma_f32_16x16x32_bf16 v[20:23], v[172:175], v[204:207], v[20:23]
	v_mfma_f32_16x16x32_bf16 v[16:19], v[180:183], v[204:207], v[16:19]
	v_mfma_f32_16x16x32_bf16 v[4:7], v[172:175], v[212:215], v[4:7]
	v_mfma_f32_16x16x32_bf16 v[0:3], v[180:183], v[212:215], v[0:3]
	s_barrier
	s_setprio 0
	s_add_i32 s44, 0, 0x18000
	s_add_i32 s68, 0, 0x1c000
	v_add_u32_e32 v164, s44, v151
	v_add_u32_e32 v180, s68, v151
	ds_read_b128 v[144:147], v164
	ds_read_b128 v[156:159], v164 offset:1024
	ds_read_b128 v[160:163], v164 offset:2048
	ds_read_b128 v[164:167], v164 offset:3072
	ds_read_b128 v[168:171], v180
	ds_read_b128 v[172:175], v180 offset:1024
	ds_read_b128 v[176:179], v180 offset:2048
	ds_read_b128 v[180:183], v180 offset:3072
	s_mov_b32 m0, s54
	v_lshl_add_u64 v[226:227], v[220:221], 0, s[6:7]
	ds_read_b128 v[184:187], v155 offset:32768
	ds_read_b128 v[188:191], v155 offset:33792
	ds_read_b128 v[192:195], v155 offset:34816
	ds_read_b128 v[196:199], v155 offset:35840
	ds_read_b128 v[200:203], v155 offset:36864
	ds_read_b128 v[204:207], v155 offset:37888
	ds_read_b128 v[208:211], v155 offset:38912
	ds_read_b128 v[212:215], v155 offset:39936
	global_load_lds_dwordx4 v[226:227], off
	s_mov_b32 m0, s55
	v_lshl_add_u64 v[226:227], v[224:225], 0, s[12:13]
	global_load_lds_dwordx4 v[226:227], off
	s_waitcnt vmcnt(8) lgkmcnt(0)
	s_setprio 1
	s_barrier
	v_mfma_f32_16x16x32_bf16 v[124:127], v[144:147], v[184:187], v[124:127]
	v_mfma_f32_16x16x32_bf16 v[120:123], v[160:163], v[184:187], v[120:123]
	v_mfma_f32_16x16x32_bf16 v[108:111], v[144:147], v[192:195], v[108:111]
	v_mfma_f32_16x16x32_bf16 v[104:107], v[160:163], v[192:195], v[104:107]
	v_mfma_f32_16x16x32_bf16 v[92:95], v[144:147], v[200:203], v[92:95]
	v_mfma_f32_16x16x32_bf16 v[88:91], v[160:163], v[200:203], v[88:91]
	v_mfma_f32_16x16x32_bf16 v[76:79], v[144:147], v[208:211], v[76:79]
	v_mfma_f32_16x16x32_bf16 v[72:75], v[160:163], v[208:211], v[72:75]
	v_mfma_f32_16x16x32_bf16 v[124:127], v[156:159], v[188:191], v[124:127]
	v_mfma_f32_16x16x32_bf16 v[120:123], v[164:167], v[188:191], v[120:123]
	v_mfma_f32_16x16x32_bf16 v[108:111], v[156:159], v[196:199], v[108:111]
	v_mfma_f32_16x16x32_bf16 v[104:107], v[164:167], v[196:199], v[104:107]
	v_mfma_f32_16x16x32_bf16 v[92:95], v[156:159], v[204:207], v[92:95]
	v_mfma_f32_16x16x32_bf16 v[88:91], v[164:167], v[204:207], v[88:91]
	v_mfma_f32_16x16x32_bf16 v[76:79], v[156:159], v[212:215], v[76:79]
	v_mfma_f32_16x16x32_bf16 v[72:75], v[164:167], v[212:215], v[72:75]
	v_mfma_f32_16x16x32_bf16 v[116:119], v[168:171], v[184:187], v[116:119]
	v_mfma_f32_16x16x32_bf16 v[112:115], v[176:179], v[184:187], v[112:115]
	v_mfma_f32_16x16x32_bf16 v[100:103], v[168:171], v[192:195], v[100:103]
	v_mfma_f32_16x16x32_bf16 v[96:99], v[176:179], v[192:195], v[96:99]
	v_mfma_f32_16x16x32_bf16 v[84:87], v[168:171], v[200:203], v[84:87]
	v_mfma_f32_16x16x32_bf16 v[80:83], v[176:179], v[200:203], v[80:83]
	v_mfma_f32_16x16x32_bf16 v[68:71], v[168:171], v[208:211], v[68:71]
	v_mfma_f32_16x16x32_bf16 v[64:67], v[176:179], v[208:211], v[64:67]
	v_mfma_f32_16x16x32_bf16 v[116:119], v[172:175], v[188:191], v[116:119]
	v_mfma_f32_16x16x32_bf16 v[112:115], v[180:183], v[188:191], v[112:115]
	v_mfma_f32_16x16x32_bf16 v[100:103], v[172:175], v[196:199], v[100:103]
	v_mfma_f32_16x16x32_bf16 v[96:99], v[180:183], v[196:199], v[96:99]
	v_mfma_f32_16x16x32_bf16 v[84:87], v[172:175], v[204:207], v[84:87]
	v_mfma_f32_16x16x32_bf16 v[80:83], v[180:183], v[204:207], v[80:83]
	v_mfma_f32_16x16x32_bf16 v[68:71], v[172:175], v[212:215], v[68:71]
	v_mfma_f32_16x16x32_bf16 v[64:67], v[180:183], v[212:215], v[64:67]
	s_barrier
	s_setprio 0
	s_add_i32 s44, s44, s33
	v_lshl_add_u64 v[148:149], v[148:149], 0, s[22:23]
	s_mov_b32 m0, s44
	ds_read_b128 v[184:187], v155 offset:49152
	ds_read_b128 v[188:191], v155 offset:50176
	ds_read_b128 v[192:195], v155 offset:51200
	ds_read_b128 v[196:199], v155 offset:52224
	ds_read_b128 v[200:203], v155 offset:53248
	ds_read_b128 v[204:207], v155 offset:54272
	ds_read_b128 v[208:211], v155 offset:55296
	ds_read_b128 v[212:215], v155 offset:56320
	global_load_lds_dwordx4 v[148:149], off
	s_add_i32 m0, s44, 0x2000
	s_add_u32 s44, s48, 0x20080
	v_lshl_add_u64 v[148:149], v[216:217], 0, s[22:23]
	s_addc_u32 s45, s49, 0
	s_add_i32 s48, s68, s33
	global_load_lds_dwordx4 v[148:149], off
	s_mov_b32 m0, s48
	v_lshl_add_u64 v[148:149], s[44:45], 0, v[132:133]
	global_load_lds_dwordx4 v[148:149], off
	s_add_i32 m0, s48, 0x2000
	v_lshl_add_u64 v[148:149], s[44:45], 0, v[128:129]
	global_load_lds_dwordx4 v[148:149], off
	s_mov_b32 m0, s57
	v_lshl_add_u64 v[148:149], v[220:221], 0, s[22:23]
	global_load_lds_dwordx4 v[148:149], off
	s_mov_b32 m0, s58
	v_lshl_add_u64 v[148:149], v[224:225], 0, s[24:25]
	global_load_lds_dwordx4 v[148:149], off
	s_waitcnt vmcnt(8) lgkmcnt(0)
	s_setprio 1
	s_barrier
	v_mfma_f32_16x16x32_bf16 v[60:63], v[144:147], v[184:187], v[60:63]
	v_mfma_f32_16x16x32_bf16 v[56:59], v[160:163], v[184:187], v[56:59]
	v_mfma_f32_16x16x32_bf16 v[44:47], v[144:147], v[192:195], v[44:47]
	v_mfma_f32_16x16x32_bf16 v[40:43], v[160:163], v[192:195], v[40:43]
	v_mfma_f32_16x16x32_bf16 v[28:31], v[144:147], v[200:203], v[28:31]
	v_mfma_f32_16x16x32_bf16 v[24:27], v[160:163], v[200:203], v[24:27]
	v_mfma_f32_16x16x32_bf16 v[12:15], v[144:147], v[208:211], v[12:15]
	v_mfma_f32_16x16x32_bf16 v[8:11], v[160:163], v[208:211], v[8:11]
	v_mfma_f32_16x16x32_bf16 v[60:63], v[156:159], v[188:191], v[60:63]
	v_mfma_f32_16x16x32_bf16 v[56:59], v[164:167], v[188:191], v[56:59]
	v_mfma_f32_16x16x32_bf16 v[44:47], v[156:159], v[196:199], v[44:47]
	v_mfma_f32_16x16x32_bf16 v[40:43], v[164:167], v[196:199], v[40:43]
	v_mfma_f32_16x16x32_bf16 v[28:31], v[156:159], v[204:207], v[28:31]
	v_mfma_f32_16x16x32_bf16 v[24:27], v[164:167], v[204:207], v[24:27]
	v_mfma_f32_16x16x32_bf16 v[12:15], v[156:159], v[212:215], v[12:15]
	v_mfma_f32_16x16x32_bf16 v[8:11], v[164:167], v[212:215], v[8:11]
	v_mfma_f32_16x16x32_bf16 v[52:55], v[168:171], v[184:187], v[52:55]
	v_mfma_f32_16x16x32_bf16 v[48:51], v[176:179], v[184:187], v[48:51]
	v_mfma_f32_16x16x32_bf16 v[36:39], v[168:171], v[192:195], v[36:39]
	v_mfma_f32_16x16x32_bf16 v[32:35], v[176:179], v[192:195], v[32:35]
	v_mfma_f32_16x16x32_bf16 v[20:23], v[168:171], v[200:203], v[20:23]
	v_mfma_f32_16x16x32_bf16 v[16:19], v[176:179], v[200:203], v[16:19]
	v_mfma_f32_16x16x32_bf16 v[4:7], v[168:171], v[208:211], v[4:7]
	v_mfma_f32_16x16x32_bf16 v[0:3], v[176:179], v[208:211], v[0:3]
	v_mfma_f32_16x16x32_bf16 v[52:55], v[172:175], v[188:191], v[52:55]
	v_mfma_f32_16x16x32_bf16 v[48:51], v[180:183], v[188:191], v[48:51]
	v_mfma_f32_16x16x32_bf16 v[36:39], v[172:175], v[196:199], v[36:39]
	v_mfma_f32_16x16x32_bf16 v[32:35], v[180:183], v[196:199], v[32:35]
	v_mfma_f32_16x16x32_bf16 v[20:23], v[172:175], v[204:207], v[20:23]
	v_mfma_f32_16x16x32_bf16 v[16:19], v[180:183], v[204:207], v[16:19]
	v_mfma_f32_16x16x32_bf16 v[4:7], v[172:175], v[212:215], v[4:7]
	v_mfma_f32_16x16x32_bf16 v[0:3], v[180:183], v[212:215], v[0:3]
	s_barrier
	s_setprio 0
	s_add_i32 s74, s74, 2
	s_add_u32 s51, s51, 0x100
	s_addc_u32 s73, s73, 0
	s_cmp_gt_u32 s74, 5
	s_mov_b64 s[44:45], s[46:47]
	s_cbranch_scc0 .LBB0_393
	s_and_b64 vcc, exec, s[36:37]
	s_cbranch_vccz .LBB0_396
	s_barrier

.LBB0_465:
	s_lshl_b32 s42, s73, 8
	s_ashr_i32 s43, s42, 31
	s_lshl_b64 s[42:43], s[42:43], 11
	s_add_u32 s42, s10, s42
	s_addc_u32 s43, s11, s43
	s_and_b64 s[44:45], s[4:5], exec
	s_cselect_b32 s47, s43, s49
	s_cselect_b32 s74, s42, s48
	s_ashr_i32 s41, s40, 31
	s_lshl_b64 s[44:45], s[40:41], 19
	s_add_u32 s44, s33, s44
	s_addc_u32 s45, s34, s45
	s_and_b64 s[50:51], s[4:5], exec
	s_cselect_b32 s41, s45, s53
	s_cselect_b32 s50, s44, s52
	s_add_u32 s51, s52, 0x100
	s_addc_u32 s75, s53, 0
	s_mov_b32 s76, -2
	s_waitcnt lgkmcnt(0)
	s_waitcnt vmcnt(0)
	s_waitcnt lgkmcnt(0)
	ds_read_b128 v[144:147], v151
	ds_read_b128 v[156:159], v151 offset:1024
	ds_read_b128 v[160:163], v151 offset:2048
	ds_read_b128 v[164:167], v151 offset:3072
	ds_read_b128 v[168:171], v152
	ds_read_b128 v[172:175], v152 offset:1024
	ds_read_b128 v[176:179], v152 offset:2048
	ds_read_b128 v[180:183], v152 offset:3072
	s_add_u32 s52, s48, 0x100
	s_addc_u32 s53, s49, 0
	s_cmp_eq_u32 s76, 12
	s_cselect_b32 s79, s47, s53
	s_cselect_b32 s78, s74, s52
	s_cselect_b32 s55, s41, s75
	s_cselect_b32 s54, s50, s51
	v_lshl_add_u64 v[216:217], s[48:49], 0, v[136:137]
	s_add_i32 m0, s56, 0xc000
	ds_read_b128 v[184:187], v153
	ds_read_b128 v[188:191], v153 offset:1024
	ds_read_b128 v[192:195], v153 offset:2048
	ds_read_b128 v[196:199], v153 offset:3072
	ds_read_b128 v[200:203], v153 offset:4096
	ds_read_b128 v[204:207], v153 offset:5120
	ds_read_b128 v[208:211], v153 offset:6144
	ds_read_b128 v[212:215], v153 offset:7168
	global_load_lds_dwordx4 v[216:217], off
	s_add_i32 m0, s56, 0xe000
	v_lshl_add_u64 v[216:217], s[48:49], 0, v[138:139]
	global_load_lds_dwordx4 v[216:217], off
	s_waitcnt vmcnt(8) lgkmcnt(0)
	s_setprio 1
	s_barrier
	v_mfma_f32_16x16x32_bf16 v[124:127], v[144:147], v[184:187], 0
	v_mfma_f32_16x16x32_bf16 v[120:123], v[160:163], v[184:187], 0
	v_mfma_f32_16x16x32_bf16 v[108:111], v[144:147], v[192:195], 0
	v_mfma_f32_16x16x32_bf16 v[104:107], v[160:163], v[192:195], 0
	v_mfma_f32_16x16x32_bf16 v[92:95], v[144:147], v[200:203], 0
	v_mfma_f32_16x16x32_bf16 v[88:91], v[160:163], v[200:203], 0
	v_mfma_f32_16x16x32_bf16 v[76:79], v[144:147], v[208:211], 0
	v_mfma_f32_16x16x32_bf16 v[72:75], v[160:163], v[208:211], 0
	v_mfma_f32_16x16x32_bf16 v[124:127], v[156:159], v[188:191], v[124:127]
	v_mfma_f32_16x16x32_bf16 v[120:123], v[164:167], v[188:191], v[120:123]
	v_mfma_f32_16x16x32_bf16 v[108:111], v[156:159], v[196:199], v[108:111]
	v_mfma_f32_16x16x32_bf16 v[104:107], v[164:167], v[196:199], v[104:107]
	v_mfma_f32_16x16x32_bf16 v[92:95], v[156:159], v[204:207], v[92:95]
	v_mfma_f32_16x16x32_bf16 v[88:91], v[164:167], v[204:207], v[88:91]
	v_mfma_f32_16x16x32_bf16 v[76:79], v[156:159], v[212:215], v[76:79]
	v_mfma_f32_16x16x32_bf16 v[72:75], v[164:167], v[212:215], v[72:75]
	v_mfma_f32_16x16x32_bf16 v[116:119], v[168:171], v[184:187], 0
	v_mfma_f32_16x16x32_bf16 v[112:115], v[176:179], v[184:187], 0
	v_mfma_f32_16x16x32_bf16 v[100:103], v[168:171], v[192:195], 0
	v_mfma_f32_16x16x32_bf16 v[96:99], v[176:179], v[192:195], 0
	v_mfma_f32_16x16x32_bf16 v[84:87], v[168:171], v[200:203], 0
	v_mfma_f32_16x16x32_bf16 v[80:83], v[176:179], v[200:203], 0
	v_mfma_f32_16x16x32_bf16 v[68:71], v[168:171], v[208:211], 0
	v_mfma_f32_16x16x32_bf16 v[64:67], v[176:179], v[208:211], 0
	v_mfma_f32_16x16x32_bf16 v[116:119], v[172:175], v[188:191], v[116:119]
	v_mfma_f32_16x16x32_bf16 v[112:115], v[180:183], v[188:191], v[112:115]
	v_mfma_f32_16x16x32_bf16 v[100:103], v[172:175], v[196:199], v[100:103]
	v_mfma_f32_16x16x32_bf16 v[96:99], v[180:183], v[196:199], v[96:99]
	v_mfma_f32_16x16x32_bf16 v[84:87], v[172:175], v[204:207], v[84:87]
	v_mfma_f32_16x16x32_bf16 v[80:83], v[180:183], v[204:207], v[80:83]
	v_mfma_f32_16x16x32_bf16 v[68:71], v[172:175], v[212:215], v[68:71]
	v_mfma_f32_16x16x32_bf16 v[64:67], v[180:183], v[212:215], v[64:67]
	s_barrier
	s_setprio 0
	s_add_i32 s48, s67, s35
	v_lshl_add_u64 v[216:217], s[54:55], 0, v[130:131]
	s_mov_b32 m0, s48
	ds_read_b128 v[184:187], v153 offset:16384
	ds_read_b128 v[188:191], v153 offset:17408
	ds_read_b128 v[192:195], v153 offset:18432
	ds_read_b128 v[196:199], v153 offset:19456
	ds_read_b128 v[200:203], v153 offset:20480
	ds_read_b128 v[204:207], v153 offset:21504
	ds_read_b128 v[208:211], v153 offset:22528
	ds_read_b128 v[212:215], v153 offset:23552
	global_load_lds_dwordx4 v[216:217], off
	s_add_i32 m0, s48, 0x2000
	s_add_u32 s48, s54, 0x40000
	v_lshl_add_u64 v[220:221], s[54:55], 0, v[134:135]
	s_addc_u32 s49, s55, 0
	s_add_i32 s68, s72, s35
	global_load_lds_dwordx4 v[220:221], off
	v_lshl_add_u64 v[224:225], s[48:49], 0, v[130:131]
	s_mov_b32 m0, s68
	v_lshl_add_u64 v[226:227], s[78:79], 0, v[132:133]
	global_load_lds_dwordx4 v[224:225], off
	v_lshl_add_u64 v[224:225], s[48:49], 0, v[134:135]
	s_add_i32 m0, s68, 0x2000
	v_lshl_add_u64 v[228:229], v[226:227], 0, s[12:13]
	global_load_lds_dwordx4 v[224:225], off
	s_mov_b32 m0, s56
	v_lshl_add_u64 v[224:225], s[78:79], 0, v[128:129]
	global_load_lds_dwordx4 v[224:225], off
	s_mov_b32 m0, s57
	s_nop 0
	global_load_lds_dwordx4 v[228:229], off
	s_waitcnt vmcnt(8) lgkmcnt(0)
	s_setprio 1
	s_barrier
	v_mfma_f32_16x16x32_bf16 v[60:63], v[144:147], v[184:187], 0
	v_mfma_f32_16x16x32_bf16 v[56:59], v[160:163], v[184:187], 0
	v_mfma_f32_16x16x32_bf16 v[44:47], v[144:147], v[192:195], 0
	v_mfma_f32_16x16x32_bf16 v[40:43], v[160:163], v[192:195], 0
	v_mfma_f32_16x16x32_bf16 v[28:31], v[144:147], v[200:203], 0
	v_mfma_f32_16x16x32_bf16 v[24:27], v[160:163], v[200:203], 0
	v_mfma_f32_16x16x32_bf16 v[12:15], v[144:147], v[208:211], 0
	v_mfma_f32_16x16x32_bf16 v[8:11], v[160:163], v[208:211], 0
	v_mfma_f32_16x16x32_bf16 v[60:63], v[156:159], v[188:191], v[60:63]
	v_mfma_f32_16x16x32_bf16 v[56:59], v[164:167], v[188:191], v[56:59]
	v_mfma_f32_16x16x32_bf16 v[44:47], v[156:159], v[196:199], v[44:47]
	v_mfma_f32_16x16x32_bf16 v[40:43], v[164:167], v[196:199], v[40:43]
	v_mfma_f32_16x16x32_bf16 v[28:31], v[156:159], v[204:207], v[28:31]
	v_mfma_f32_16x16x32_bf16 v[24:27], v[164:167], v[204:207], v[24:27]
	v_mfma_f32_16x16x32_bf16 v[12:15], v[156:159], v[212:215], v[12:15]
	v_mfma_f32_16x16x32_bf16 v[8:11], v[164:167], v[212:215], v[8:11]
	v_mfma_f32_16x16x32_bf16 v[52:55], v[168:171], v[184:187], 0
	v_mfma_f32_16x16x32_bf16 v[48:51], v[176:179], v[184:187], 0
	v_mfma_f32_16x16x32_bf16 v[36:39], v[168:171], v[192:195], 0
	v_mfma_f32_16x16x32_bf16 v[32:35], v[176:179], v[192:195], 0
	v_mfma_f32_16x16x32_bf16 v[20:23], v[168:171], v[200:203], 0
	v_mfma_f32_16x16x32_bf16 v[16:19], v[176:179], v[200:203], 0
	v_mfma_f32_16x16x32_bf16 v[4:7], v[168:171], v[208:211], 0
	v_mfma_f32_16x16x32_bf16 v[0:3], v[176:179], v[208:211], 0
	v_mfma_f32_16x16x32_bf16 v[52:55], v[172:175], v[188:191], v[52:55]
	v_mfma_f32_16x16x32_bf16 v[48:51], v[180:183], v[188:191], v[48:51]
	v_mfma_f32_16x16x32_bf16 v[36:39], v[172:175], v[196:199], v[36:39]
	v_mfma_f32_16x16x32_bf16 v[32:35], v[180:183], v[196:199], v[32:35]
	v_mfma_f32_16x16x32_bf16 v[20:23], v[172:175], v[204:207], v[20:23]
	v_mfma_f32_16x16x32_bf16 v[16:19], v[180:183], v[204:207], v[16:19]
	v_mfma_f32_16x16x32_bf16 v[4:7], v[172:175], v[212:215], v[4:7]
	v_mfma_f32_16x16x32_bf16 v[0:3], v[180:183], v[212:215], v[0:3]
	s_barrier
	s_setprio 0
	s_add_i32 s48, 0, 0x18000
	v_add_u32_e32 v155, s48, v149
	s_add_i32 s68, 0, 0x1c000
	ds_read_b128 v[144:147], v155
	ds_read_b128 v[156:159], v155 offset:1024
	ds_read_b128 v[160:163], v155 offset:2048
	ds_read_b128 v[164:167], v155 offset:3072
	v_add_u32_e32 v155, s68, v149
	ds_read_b128 v[168:171], v155
	ds_read_b128 v[172:175], v155 offset:1024
	ds_read_b128 v[176:179], v155 offset:2048
	ds_read_b128 v[180:183], v155 offset:3072
	s_mov_b32 m0, s58
	v_lshl_add_u64 v[228:229], v[224:225], 0, s[8:9]
	ds_read_b128 v[184:187], v153 offset:32768
	ds_read_b128 v[188:191], v153 offset:33792
	ds_read_b128 v[192:195], v153 offset:34816
	ds_read_b128 v[196:199], v153 offset:35840
	ds_read_b128 v[200:203], v153 offset:36864
	ds_read_b128 v[204:207], v153 offset:37888
	ds_read_b128 v[208:211], v153 offset:38912
	ds_read_b128 v[212:215], v153 offset:39936
	global_load_lds_dwordx4 v[228:229], off
	s_mov_b32 m0, s59
	v_lshl_add_u64 v[228:229], v[226:227], 0, s[14:15]
	global_load_lds_dwordx4 v[228:229], off
	s_waitcnt vmcnt(8) lgkmcnt(0)
	s_setprio 1
	s_barrier
	v_mfma_f32_16x16x32_bf16 v[124:127], v[144:147], v[184:187], v[124:127]
	v_mfma_f32_16x16x32_bf16 v[120:123], v[160:163], v[184:187], v[120:123]
	v_mfma_f32_16x16x32_bf16 v[108:111], v[144:147], v[192:195], v[108:111]
	v_mfma_f32_16x16x32_bf16 v[104:107], v[160:163], v[192:195], v[104:107]
	v_mfma_f32_16x16x32_bf16 v[92:95], v[144:147], v[200:203], v[92:95]
	v_mfma_f32_16x16x32_bf16 v[88:91], v[160:163], v[200:203], v[88:91]
	v_mfma_f32_16x16x32_bf16 v[76:79], v[144:147], v[208:211], v[76:79]
	v_mfma_f32_16x16x32_bf16 v[72:75], v[160:163], v[208:211], v[72:75]
	v_mfma_f32_16x16x32_bf16 v[124:127], v[156:159], v[188:191], v[124:127]
	v_mfma_f32_16x16x32_bf16 v[120:123], v[164:167], v[188:191], v[120:123]
	v_mfma_f32_16x16x32_bf16 v[108:111], v[156:159], v[196:199], v[108:111]
	v_mfma_f32_16x16x32_bf16 v[104:107], v[164:167], v[196:199], v[104:107]
	v_mfma_f32_16x16x32_bf16 v[92:95], v[156:159], v[204:207], v[92:95]
	v_mfma_f32_16x16x32_bf16 v[88:91], v[164:167], v[204:207], v[88:91]
	v_mfma_f32_16x16x32_bf16 v[76:79], v[156:159], v[212:215], v[76:79]
	v_mfma_f32_16x16x32_bf16 v[72:75], v[164:167], v[212:215], v[72:75]
	v_mfma_f32_16x16x32_bf16 v[116:119], v[168:171], v[184:187], v[116:119]
	v_mfma_f32_16x16x32_bf16 v[112:115], v[176:179], v[184:187], v[112:115]
	v_mfma_f32_16x16x32_bf16 v[100:103], v[168:171], v[192:195], v[100:103]
	v_mfma_f32_16x16x32_bf16 v[96:99], v[176:179], v[192:195], v[96:99]
	v_mfma_f32_16x16x32_bf16 v[84:87], v[168:171], v[200:203], v[84:87]
	v_mfma_f32_16x16x32_bf16 v[80:83], v[176:179], v[200:203], v[80:83]
	v_mfma_f32_16x16x32_bf16 v[68:71], v[168:171], v[208:211], v[68:71]
	v_mfma_f32_16x16x32_bf16 v[64:67], v[176:179], v[208:211], v[64:67]
	v_mfma_f32_16x16x32_bf16 v[116:119], v[172:175], v[188:191], v[116:119]
	v_mfma_f32_16x16x32_bf16 v[112:115], v[180:183], v[188:191], v[112:115]
	v_mfma_f32_16x16x32_bf16 v[100:103], v[172:175], v[196:199], v[100:103]
	v_mfma_f32_16x16x32_bf16 v[96:99], v[180:183], v[196:199], v[96:99]
	v_mfma_f32_16x16x32_bf16 v[84:87], v[172:175], v[204:207], v[84:87]
	v_mfma_f32_16x16x32_bf16 v[80:83], v[180:183], v[204:207], v[80:83]
	v_mfma_f32_16x16x32_bf16 v[68:71], v[172:175], v[212:215], v[68:71]
	v_mfma_f32_16x16x32_bf16 v[64:67], v[180:183], v[212:215], v[64:67]
	s_barrier
	s_setprio 0
	s_add_i32 s48, s48, s35
	v_lshl_add_u64 v[216:217], v[216:217], 0, s[24:25]
	s_mov_b32 m0, s48
	ds_read_b128 v[184:187], v153 offset:49152
	ds_read_b128 v[188:191], v153 offset:50176
	ds_read_b128 v[192:195], v153 offset:51200
	ds_read_b128 v[196:199], v153 offset:52224
	ds_read_b128 v[200:203], v153 offset:53248
	ds_read_b128 v[204:207], v153 offset:54272
	ds_read_b128 v[208:211], v153 offset:55296
	ds_read_b128 v[212:215], v153 offset:56320
	global_load_lds_dwordx4 v[216:217], off
	s_add_i32 m0, s48, 0x2000
	s_add_u32 s48, s54, 0x40080
	v_lshl_add_u64 v[216:217], v[220:221], 0, s[24:25]
	s_addc_u32 s49, s55, 0
	s_add_i32 s54, s68, s35
	global_load_lds_dwordx4 v[216:217], off
	s_mov_b32 m0, s54
	v_lshl_add_u64 v[216:217], s[48:49], 0, v[130:131]
	global_load_lds_dwordx4 v[216:217], off
	s_add_i32 m0, s54, 0x2000
	v_lshl_add_u64 v[216:217], s[48:49], 0, v[134:135]
	global_load_lds_dwordx4 v[216:217], off
	s_mov_b32 m0, s61
	v_lshl_add_u64 v[216:217], v[224:225], 0, s[24:25]
	global_load_lds_dwordx4 v[216:217], off
	s_mov_b32 m0, s62
	v_lshl_add_u64 v[216:217], v[226:227], 0, s[36:37]
	global_load_lds_dwordx4 v[216:217], off
	s_waitcnt vmcnt(8) lgkmcnt(0)
	s_setprio 1
	s_barrier
	v_mfma_f32_16x16x32_bf16 v[60:63], v[144:147], v[184:187], v[60:63]
	v_mfma_f32_16x16x32_bf16 v[56:59], v[160:163], v[184:187], v[56:59]
	v_mfma_f32_16x16x32_bf16 v[44:47], v[144:147], v[192:195], v[44:47]
	v_mfma_f32_16x16x32_bf16 v[40:43], v[160:163], v[192:195], v[40:43]
	v_mfma_f32_16x16x32_bf16 v[28:31], v[144:147], v[200:203], v[28:31]
	v_mfma_f32_16x16x32_bf16 v[24:27], v[160:163], v[200:203], v[24:27]
	v_mfma_f32_16x16x32_bf16 v[12:15], v[144:147], v[208:211], v[12:15]
	v_mfma_f32_16x16x32_bf16 v[8:11], v[160:163], v[208:211], v[8:11]
	v_mfma_f32_16x16x32_bf16 v[60:63], v[156:159], v[188:191], v[60:63]
	v_mfma_f32_16x16x32_bf16 v[56:59], v[164:167], v[188:191], v[56:59]
	v_mfma_f32_16x16x32_bf16 v[44:47], v[156:159], v[196:199], v[44:47]
	v_mfma_f32_16x16x32_bf16 v[40:43], v[164:167], v[196:199], v[40:43]
	v_mfma_f32_16x16x32_bf16 v[28:31], v[156:159], v[204:207], v[28:31]
	v_mfma_f32_16x16x32_bf16 v[24:27], v[164:167], v[204:207], v[24:27]
	v_mfma_f32_16x16x32_bf16 v[12:15], v[156:159], v[212:215], v[12:15]
	v_mfma_f32_16x16x32_bf16 v[8:11], v[164:167], v[212:215], v[8:11]
	v_mfma_f32_16x16x32_bf16 v[52:55], v[168:171], v[184:187], v[52:55]
	v_mfma_f32_16x16x32_bf16 v[48:51], v[176:179], v[184:187], v[48:51]
	v_mfma_f32_16x16x32_bf16 v[36:39], v[168:171], v[192:195], v[36:39]
	v_mfma_f32_16x16x32_bf16 v[32:35], v[176:179], v[192:195], v[32:35]
	v_mfma_f32_16x16x32_bf16 v[20:23], v[168:171], v[200:203], v[20:23]
	v_mfma_f32_16x16x32_bf16 v[16:19], v[176:179], v[200:203], v[16:19]
	v_mfma_f32_16x16x32_bf16 v[4:7], v[168:171], v[208:211], v[4:7]
	v_mfma_f32_16x16x32_bf16 v[0:3], v[176:179], v[208:211], v[0:3]
	v_mfma_f32_16x16x32_bf16 v[52:55], v[172:175], v[188:191], v[52:55]
	v_mfma_f32_16x16x32_bf16 v[48:51], v[180:183], v[188:191], v[48:51]
	v_mfma_f32_16x16x32_bf16 v[36:39], v[172:175], v[196:199], v[36:39]
	v_mfma_f32_16x16x32_bf16 v[32:35], v[180:183], v[196:199], v[32:35]
	v_mfma_f32_16x16x32_bf16 v[20:23], v[172:175], v[204:207], v[20:23]
	v_mfma_f32_16x16x32_bf16 v[16:19], v[180:183], v[204:207], v[16:19]
	v_mfma_f32_16x16x32_bf16 v[4:7], v[172:175], v[212:215], v[4:7]
	v_mfma_f32_16x16x32_bf16 v[0:3], v[180:183], v[212:215], v[0:3]
	s_barrier
	s_setprio 0
	s_add_i32 s76, s76, 2
	s_add_u32 s51, s51, 0x100
	s_addc_u32 s75, s75, 0
	s_cmp_gt_u32 s76, 13
	s_mov_b64 s[48:49], s[52:53]
.LBB0_466:
	ds_read_b128 v[144:147], v151
	ds_read_b128 v[156:159], v151 offset:1024
	ds_read_b128 v[160:163], v151 offset:2048
	ds_read_b128 v[164:167], v151 offset:3072
	ds_read_b128 v[168:171], v152
	ds_read_b128 v[172:175], v152 offset:1024
	ds_read_b128 v[176:179], v152 offset:2048
	ds_read_b128 v[180:183], v152 offset:3072
	s_add_u32 s52, s48, 0x100
	s_addc_u32 s53, s49, 0
	s_cmp_eq_u32 s76, 12
	s_cselect_b32 s79, s47, s53
	s_cselect_b32 s78, s74, s52
	s_cselect_b32 s55, s41, s75
	s_cselect_b32 s54, s50, s51
	v_lshl_add_u64 v[216:217], s[48:49], 0, v[136:137]
	s_add_i32 m0, s56, 0xc000
	ds_read_b128 v[184:187], v153
	ds_read_b128 v[188:191], v153 offset:1024
	ds_read_b128 v[192:195], v153 offset:2048
	ds_read_b128 v[196:199], v153 offset:3072
	ds_read_b128 v[200:203], v153 offset:4096
	ds_read_b128 v[204:207], v153 offset:5120
	ds_read_b128 v[208:211], v153 offset:6144
	ds_read_b128 v[212:215], v153 offset:7168
	global_load_lds_dwordx4 v[216:217], off
	s_add_i32 m0, s56, 0xe000
	v_lshl_add_u64 v[216:217], s[48:49], 0, v[138:139]
	global_load_lds_dwordx4 v[216:217], off
	s_waitcnt vmcnt(8) lgkmcnt(0)
	s_setprio 1
	s_barrier
	v_mfma_f32_16x16x32_bf16 v[124:127], v[144:147], v[184:187], v[124:127]
	v_mfma_f32_16x16x32_bf16 v[120:123], v[160:163], v[184:187], v[120:123]
	v_mfma_f32_16x16x32_bf16 v[108:111], v[144:147], v[192:195], v[108:111]
	v_mfma_f32_16x16x32_bf16 v[104:107], v[160:163], v[192:195], v[104:107]
	v_mfma_f32_16x16x32_bf16 v[92:95], v[144:147], v[200:203], v[92:95]
	v_mfma_f32_16x16x32_bf16 v[88:91], v[160:163], v[200:203], v[88:91]
	v_mfma_f32_16x16x32_bf16 v[76:79], v[144:147], v[208:211], v[76:79]
	v_mfma_f32_16x16x32_bf16 v[72:75], v[160:163], v[208:211], v[72:75]
	v_mfma_f32_16x16x32_bf16 v[124:127], v[156:159], v[188:191], v[124:127]
	v_mfma_f32_16x16x32_bf16 v[120:123], v[164:167], v[188:191], v[120:123]
	v_mfma_f32_16x16x32_bf16 v[108:111], v[156:159], v[196:199], v[108:111]
	v_mfma_f32_16x16x32_bf16 v[104:107], v[164:167], v[196:199], v[104:107]
	v_mfma_f32_16x16x32_bf16 v[92:95], v[156:159], v[204:207], v[92:95]
	v_mfma_f32_16x16x32_bf16 v[88:91], v[164:167], v[204:207], v[88:91]
	v_mfma_f32_16x16x32_bf16 v[76:79], v[156:159], v[212:215], v[76:79]
	v_mfma_f32_16x16x32_bf16 v[72:75], v[164:167], v[212:215], v[72:75]
	v_mfma_f32_16x16x32_bf16 v[116:119], v[168:171], v[184:187], v[116:119]
	v_mfma_f32_16x16x32_bf16 v[112:115], v[176:179], v[184:187], v[112:115]
	v_mfma_f32_16x16x32_bf16 v[100:103], v[168:171], v[192:195], v[100:103]
	v_mfma_f32_16x16x32_bf16 v[96:99], v[176:179], v[192:195], v[96:99]
	v_mfma_f32_16x16x32_bf16 v[84:87], v[168:171], v[200:203], v[84:87]
	v_mfma_f32_16x16x32_bf16 v[80:83], v[176:179], v[200:203], v[80:83]
	v_mfma_f32_16x16x32_bf16 v[68:71], v[168:171], v[208:211], v[68:71]
	v_mfma_f32_16x16x32_bf16 v[64:67], v[176:179], v[208:211], v[64:67]
	v_mfma_f32_16x16x32_bf16 v[116:119], v[172:175], v[188:191], v[116:119]
	v_mfma_f32_16x16x32_bf16 v[112:115], v[180:183], v[188:191], v[112:115]
	v_mfma_f32_16x16x32_bf16 v[100:103], v[172:175], v[196:199], v[100:103]
	v_mfma_f32_16x16x32_bf16 v[96:99], v[180:183], v[196:199], v[96:99]
	v_mfma_f32_16x16x32_bf16 v[84:87], v[172:175], v[204:207], v[84:87]
	v_mfma_f32_16x16x32_bf16 v[80:83], v[180:183], v[204:207], v[80:83]
	v_mfma_f32_16x16x32_bf16 v[68:71], v[172:175], v[212:215], v[68:71]
	v_mfma_f32_16x16x32_bf16 v[64:67], v[180:183], v[212:215], v[64:67]
	s_barrier
	s_setprio 0
	s_add_i32 s48, s67, s35
	v_lshl_add_u64 v[216:217], s[54:55], 0, v[130:131]
	s_mov_b32 m0, s48
	ds_read_b128 v[184:187], v153 offset:16384
	ds_read_b128 v[188:191], v153 offset:17408
	ds_read_b128 v[192:195], v153 offset:18432
	ds_read_b128 v[196:199], v153 offset:19456
	ds_read_b128 v[200:203], v153 offset:20480
	ds_read_b128 v[204:207], v153 offset:21504
	ds_read_b128 v[208:211], v153 offset:22528
	ds_read_b128 v[212:215], v153 offset:23552
	global_load_lds_dwordx4 v[216:217], off
	s_add_i32 m0, s48, 0x2000
	s_add_u32 s48, s54, 0x40000
	v_lshl_add_u64 v[220:221], s[54:55], 0, v[134:135]
	s_addc_u32 s49, s55, 0
	s_add_i32 s68, s72, s35
	global_load_lds_dwordx4 v[220:221], off
	v_lshl_add_u64 v[224:225], s[48:49], 0, v[130:131]
	s_mov_b32 m0, s68
	v_lshl_add_u64 v[226:227], s[78:79], 0, v[132:133]
	global_load_lds_dwordx4 v[224:225], off
	v_lshl_add_u64 v[224:225], s[48:49], 0, v[134:135]
	s_add_i32 m0, s68, 0x2000
	v_lshl_add_u64 v[228:229], v[226:227], 0, s[12:13]
	global_load_lds_dwordx4 v[224:225], off
	s_mov_b32 m0, s56
	v_lshl_add_u64 v[224:225], s[78:79], 0, v[128:129]
	global_load_lds_dwordx4 v[224:225], off
	s_mov_b32 m0, s57
	s_nop 0
	global_load_lds_dwordx4 v[228:229], off
	s_waitcnt vmcnt(8) lgkmcnt(0)
	s_setprio 1
	s_barrier
	v_mfma_f32_16x16x32_bf16 v[60:63], v[144:147], v[184:187], v[60:63]
	v_mfma_f32_16x16x32_bf16 v[56:59], v[160:163], v[184:187], v[56:59]
	v_mfma_f32_16x16x32_bf16 v[44:47], v[144:147], v[192:195], v[44:47]
	v_mfma_f32_16x16x32_bf16 v[40:43], v[160:163], v[192:195], v[40:43]
	v_mfma_f32_16x16x32_bf16 v[28:31], v[144:147], v[200:203], v[28:31]
	v_mfma_f32_16x16x32_bf16 v[24:27], v[160:163], v[200:203], v[24:27]
	v_mfma_f32_16x16x32_bf16 v[12:15], v[144:147], v[208:211], v[12:15]
	v_mfma_f32_16x16x32_bf16 v[8:11], v[160:163], v[208:211], v[8:11]
	v_mfma_f32_16x16x32_bf16 v[60:63], v[156:159], v[188:191], v[60:63]
	v_mfma_f32_16x16x32_bf16 v[56:59], v[164:167], v[188:191], v[56:59]
	v_mfma_f32_16x16x32_bf16 v[44:47], v[156:159], v[196:199], v[44:47]
	v_mfma_f32_16x16x32_bf16 v[40:43], v[164:167], v[196:199], v[40:43]
	v_mfma_f32_16x16x32_bf16 v[28:31], v[156:159], v[204:207], v[28:31]
	v_mfma_f32_16x16x32_bf16 v[24:27], v[164:167], v[204:207], v[24:27]
	v_mfma_f32_16x16x32_bf16 v[12:15], v[156:159], v[212:215], v[12:15]
	v_mfma_f32_16x16x32_bf16 v[8:11], v[164:167], v[212:215], v[8:11]
	v_mfma_f32_16x16x32_bf16 v[52:55], v[168:171], v[184:187], v[52:55]
	v_mfma_f32_16x16x32_bf16 v[48:51], v[176:179], v[184:187], v[48:51]
	v_mfma_f32_16x16x32_bf16 v[36:39], v[168:171], v[192:195], v[36:39]
	v_mfma_f32_16x16x32_bf16 v[32:35], v[176:179], v[192:195], v[32:35]
	v_mfma_f32_16x16x32_bf16 v[20:23], v[168:171], v[200:203], v[20:23]
	v_mfma_f32_16x16x32_bf16 v[16:19], v[176:179], v[200:203], v[16:19]
	v_mfma_f32_16x16x32_bf16 v[4:7], v[168:171], v[208:211], v[4:7]
	v_mfma_f32_16x16x32_bf16 v[0:3], v[176:179], v[208:211], v[0:3]
	v_mfma_f32_16x16x32_bf16 v[52:55], v[172:175], v[188:191], v[52:55]
	v_mfma_f32_16x16x32_bf16 v[48:51], v[180:183], v[188:191], v[48:51]
	v_mfma_f32_16x16x32_bf16 v[36:39], v[172:175], v[196:199], v[36:39]
	v_mfma_f32_16x16x32_bf16 v[32:35], v[180:183], v[196:199], v[32:35]
	v_mfma_f32_16x16x32_bf16 v[20:23], v[172:175], v[204:207], v[20:23]
	v_mfma_f32_16x16x32_bf16 v[16:19], v[180:183], v[204:207], v[16:19]
	v_mfma_f32_16x16x32_bf16 v[4:7], v[172:175], v[212:215], v[4:7]
	v_mfma_f32_16x16x32_bf16 v[0:3], v[180:183], v[212:215], v[0:3]
	s_barrier
	s_setprio 0
	s_add_i32 s48, 0, 0x18000
	v_add_u32_e32 v155, s48, v149
	s_add_i32 s68, 0, 0x1c000
	ds_read_b128 v[144:147], v155
	ds_read_b128 v[156:159], v155 offset:1024
	ds_read_b128 v[160:163], v155 offset:2048
	ds_read_b128 v[164:167], v155 offset:3072
	v_add_u32_e32 v155, s68, v149
	ds_read_b128 v[168:171], v155
	ds_read_b128 v[172:175], v155 offset:1024
	ds_read_b128 v[176:179], v155 offset:2048
	ds_read_b128 v[180:183], v155 offset:3072
	s_mov_b32 m0, s58
	v_lshl_add_u64 v[228:229], v[224:225], 0, s[8:9]
	ds_read_b128 v[184:187], v153 offset:32768
	ds_read_b128 v[188:191], v153 offset:33792
	ds_read_b128 v[192:195], v153 offset:34816
	ds_read_b128 v[196:199], v153 offset:35840
	ds_read_b128 v[200:203], v153 offset:36864
	ds_read_b128 v[204:207], v153 offset:37888
	ds_read_b128 v[208:211], v153 offset:38912
	ds_read_b128 v[212:215], v153 offset:39936
	global_load_lds_dwordx4 v[228:229], off
	s_mov_b32 m0, s59
	v_lshl_add_u64 v[228:229], v[226:227], 0, s[14:15]
	global_load_lds_dwordx4 v[228:229], off
	s_waitcnt vmcnt(8) lgkmcnt(0)
	s_setprio 1
	s_barrier
	v_mfma_f32_16x16x32_bf16 v[124:127], v[144:147], v[184:187], v[124:127]
	v_mfma_f32_16x16x32_bf16 v[120:123], v[160:163], v[184:187], v[120:123]
	v_mfma_f32_16x16x32_bf16 v[108:111], v[144:147], v[192:195], v[108:111]
	v_mfma_f32_16x16x32_bf16 v[104:107], v[160:163], v[192:195], v[104:107]
	v_mfma_f32_16x16x32_bf16 v[92:95], v[144:147], v[200:203], v[92:95]
	v_mfma_f32_16x16x32_bf16 v[88:91], v[160:163], v[200:203], v[88:91]
	v_mfma_f32_16x16x32_bf16 v[76:79], v[144:147], v[208:211], v[76:79]
	v_mfma_f32_16x16x32_bf16 v[72:75], v[160:163], v[208:211], v[72:75]
	v_mfma_f32_16x16x32_bf16 v[124:127], v[156:159], v[188:191], v[124:127]
	v_mfma_f32_16x16x32_bf16 v[120:123], v[164:167], v[188:191], v[120:123]
	v_mfma_f32_16x16x32_bf16 v[108:111], v[156:159], v[196:199], v[108:111]
	v_mfma_f32_16x16x32_bf16 v[104:107], v[164:167], v[196:199], v[104:107]
	v_mfma_f32_16x16x32_bf16 v[92:95], v[156:159], v[204:207], v[92:95]
	v_mfma_f32_16x16x32_bf16 v[88:91], v[164:167], v[204:207], v[88:91]
	v_mfma_f32_16x16x32_bf16 v[76:79], v[156:159], v[212:215], v[76:79]
	v_mfma_f32_16x16x32_bf16 v[72:75], v[164:167], v[212:215], v[72:75]
	v_mfma_f32_16x16x32_bf16 v[116:119], v[168:171], v[184:187], v[116:119]
	v_mfma_f32_16x16x32_bf16 v[112:115], v[176:179], v[184:187], v[112:115]
	v_mfma_f32_16x16x32_bf16 v[100:103], v[168:171], v[192:195], v[100:103]
	v_mfma_f32_16x16x32_bf16 v[96:99], v[176:179], v[192:195], v[96:99]
	v_mfma_f32_16x16x32_bf16 v[84:87], v[168:171], v[200:203], v[84:87]
	v_mfma_f32_16x16x32_bf16 v[80:83], v[176:179], v[200:203], v[80:83]
	v_mfma_f32_16x16x32_bf16 v[68:71], v[168:171], v[208:211], v[68:71]
	v_mfma_f32_16x16x32_bf16 v[64:67], v[176:179], v[208:211], v[64:67]
	v_mfma_f32_16x16x32_bf16 v[116:119], v[172:175], v[188:191], v[116:119]
	v_mfma_f32_16x16x32_bf16 v[112:115], v[180:183], v[188:191], v[112:115]
	v_mfma_f32_16x16x32_bf16 v[100:103], v[172:175], v[196:199], v[100:103]
	v_mfma_f32_16x16x32_bf16 v[96:99], v[180:183], v[196:199], v[96:99]
	v_mfma_f32_16x16x32_bf16 v[84:87], v[172:175], v[204:207], v[84:87]
	v_mfma_f32_16x16x32_bf16 v[80:83], v[180:183], v[204:207], v[80:83]
	v_mfma_f32_16x16x32_bf16 v[68:71], v[172:175], v[212:215], v[68:71]
	v_mfma_f32_16x16x32_bf16 v[64:67], v[180:183], v[212:215], v[64:67]
	s_barrier
	s_setprio 0
	s_add_i32 s48, s48, s35
	v_lshl_add_u64 v[216:217], v[216:217], 0, s[24:25]
	s_mov_b32 m0, s48
	ds_read_b128 v[184:187], v153 offset:49152
	ds_read_b128 v[188:191], v153 offset:50176
	ds_read_b128 v[192:195], v153 offset:51200
	ds_read_b128 v[196:199], v153 offset:52224
	ds_read_b128 v[200:203], v153 offset:53248
	ds_read_b128 v[204:207], v153 offset:54272
	ds_read_b128 v[208:211], v153 offset:55296
	ds_read_b128 v[212:215], v153 offset:56320
	global_load_lds_dwordx4 v[216:217], off
	s_add_i32 m0, s48, 0x2000
	s_add_u32 s48, s54, 0x40080
	v_lshl_add_u64 v[216:217], v[220:221], 0, s[24:25]
	s_addc_u32 s49, s55, 0
	s_add_i32 s54, s68, s35
	global_load_lds_dwordx4 v[216:217], off
	s_mov_b32 m0, s54
	v_lshl_add_u64 v[216:217], s[48:49], 0, v[130:131]
	global_load_lds_dwordx4 v[216:217], off
	s_add_i32 m0, s54, 0x2000
	v_lshl_add_u64 v[216:217], s[48:49], 0, v[134:135]
	global_load_lds_dwordx4 v[216:217], off
	s_mov_b32 m0, s61
	v_lshl_add_u64 v[216:217], v[224:225], 0, s[24:25]
	global_load_lds_dwordx4 v[216:217], off
	s_mov_b32 m0, s62
	v_lshl_add_u64 v[216:217], v[226:227], 0, s[36:37]
	global_load_lds_dwordx4 v[216:217], off
	s_waitcnt vmcnt(8) lgkmcnt(0)
	s_setprio 1
	s_barrier
	v_mfma_f32_16x16x32_bf16 v[60:63], v[144:147], v[184:187], v[60:63]
	v_mfma_f32_16x16x32_bf16 v[56:59], v[160:163], v[184:187], v[56:59]
	v_mfma_f32_16x16x32_bf16 v[44:47], v[144:147], v[192:195], v[44:47]
	v_mfma_f32_16x16x32_bf16 v[40:43], v[160:163], v[192:195], v[40:43]
	v_mfma_f32_16x16x32_bf16 v[28:31], v[144:147], v[200:203], v[28:31]
	v_mfma_f32_16x16x32_bf16 v[24:27], v[160:163], v[200:203], v[24:27]
	v_mfma_f32_16x16x32_bf16 v[12:15], v[144:147], v[208:211], v[12:15]
	v_mfma_f32_16x16x32_bf16 v[8:11], v[160:163], v[208:211], v[8:11]
	v_mfma_f32_16x16x32_bf16 v[60:63], v[156:159], v[188:191], v[60:63]
	v_mfma_f32_16x16x32_bf16 v[56:59], v[164:167], v[188:191], v[56:59]
	v_mfma_f32_16x16x32_bf16 v[44:47], v[156:159], v[196:199], v[44:47]
	v_mfma_f32_16x16x32_bf16 v[40:43], v[164:167], v[196:199], v[40:43]
	v_mfma_f32_16x16x32_bf16 v[28:31], v[156:159], v[204:207], v[28:31]
	v_mfma_f32_16x16x32_bf16 v[24:27], v[164:167], v[204:207], v[24:27]
	v_mfma_f32_16x16x32_bf16 v[12:15], v[156:159], v[212:215], v[12:15]
	v_mfma_f32_16x16x32_bf16 v[8:11], v[164:167], v[212:215], v[8:11]
	v_mfma_f32_16x16x32_bf16 v[52:55], v[168:171], v[184:187], v[52:55]
	v_mfma_f32_16x16x32_bf16 v[48:51], v[176:179], v[184:187], v[48:51]
	v_mfma_f32_16x16x32_bf16 v[36:39], v[168:171], v[192:195], v[36:39]
	v_mfma_f32_16x16x32_bf16 v[32:35], v[176:179], v[192:195], v[32:35]
	v_mfma_f32_16x16x32_bf16 v[20:23], v[168:171], v[200:203], v[20:23]
	v_mfma_f32_16x16x32_bf16 v[16:19], v[176:179], v[200:203], v[16:19]
	v_mfma_f32_16x16x32_bf16 v[4:7], v[168:171], v[208:211], v[4:7]
	v_mfma_f32_16x16x32_bf16 v[0:3], v[176:179], v[208:211], v[0:3]
	v_mfma_f32_16x16x32_bf16 v[52:55], v[172:175], v[188:191], v[52:55]
	v_mfma_f32_16x16x32_bf16 v[48:51], v[180:183], v[188:191], v[48:51]
	v_mfma_f32_16x16x32_bf16 v[36:39], v[172:175], v[196:199], v[36:39]
	v_mfma_f32_16x16x32_bf16 v[32:35], v[180:183], v[196:199], v[32:35]
	v_mfma_f32_16x16x32_bf16 v[20:23], v[172:175], v[204:207], v[20:23]
	v_mfma_f32_16x16x32_bf16 v[16:19], v[180:183], v[204:207], v[16:19]
	v_mfma_f32_16x16x32_bf16 v[4:7], v[172:175], v[212:215], v[4:7]
	v_mfma_f32_16x16x32_bf16 v[0:3], v[180:183], v[212:215], v[0:3]
	s_barrier
	s_setprio 0
	s_add_i32 s76, s76, 2
	s_add_u32 s51, s51, 0x100
	s_addc_u32 s75, s75, 0
	s_cmp_gt_u32 s76, 13
	s_mov_b64 s[48:49], s[52:53]
	s_cbranch_scc0 .LBB0_466
	s_and_b64 vcc, exec, s[38:39]
	s_cbranch_vccz .LBB0_469
	s_barrier

.LBB0_564:
	s_ashr_i32 s77, s76, 31
	s_lshl_b64 s[50:51], s[76:77], 19
	s_add_u32 s82, s49, s50
	s_addc_u32 s83, s53, s51
	s_and_b64 s[0:1], s[0:1], exec
	s_cselect_b32 s13, s83, s89
	s_cselect_b32 s77, s82, s88
	v_lshl_add_u64 v[92:93], s[84:85], 0, v[168:169]
	s_add_u32 vcc_lo, s88, 0x100
	v_lshl_add_u64 v[130:131], v[92:93], 0, s[86:87]
	s_addc_u32 vcc_hi, s89, 0
	s_mov_b32 s50, -2
	s_mov_b64 s[0:1], 0
	s_waitcnt vmcnt(0)
	ds_read_b128 v[132:135], v207
	ds_read_b128 v[136:139], v207 offset:1024
	ds_read_b128 v[140:143], v207 offset:2048
	ds_read_b128 v[144:147], v207 offset:3072
	ds_read_b128 v[148:151], v208
	ds_read_b128 v[152:155], v208 offset:1024
	ds_read_b128 v[156:159], v208 offset:2048
	ds_read_b128 v[174:177], v208 offset:3072
	s_add_u32 s51, s84, s0
	s_addc_u32 s68, s85, s1
	s_add_u32 s51, s51, 0x100
	s_addc_u32 s68, s68, 0
	s_add_u32 s69, vcc_lo, s0
	s_addc_u32 s70, vcc_hi, s1
	s_cmpk_eq_i32 s0, 0x700
	s_cselect_b32 s91, s79, s68
	s_cselect_b32 s90, s78, s51
	s_cselect_b32 s51, s81, s87
	s_cselect_b32 s71, s80, s86
	s_cselect_b32 s89, s13, s70
	s_cselect_b32 s88, s77, s69
	v_lshl_add_u64 v[160:161], v[92:93], 0, s[0:1]
	s_add_i32 m0, s59, 0xc000
	ds_read_b128 v[194:197], v209
	ds_read_b128 v[198:201], v209 offset:1024
	ds_read_b128 v[212:215], v209 offset:2048
	ds_read_b128 v[224:227], v209 offset:3072
	ds_read_b128 v[228:231], v209 offset:4096
	ds_read_b128 v[232:235], v209 offset:5120
	ds_read_b128 v[236:239], v209 offset:6144
	ds_read_b128 v[240:243], v209 offset:7168
	global_load_lds_dwordx4 v[160:161], off
	s_add_i32 m0, s59, 0xe000
	v_lshl_add_u64 v[160:161], v[130:131], 0, s[0:1]
	global_load_lds_dwordx4 v[160:161], off
	s_waitcnt vmcnt(8) lgkmcnt(0)
	s_setprio 1
	s_barrier
	v_mfma_f32_16x16x32_bf16 v[126:129], v[132:135], v[194:197], 0
	v_mfma_f32_16x16x32_bf16 v[60:63], v[140:143], v[194:197], 0
	v_mfma_f32_16x16x32_bf16 v[118:121], v[132:135], v[212:215], 0
	v_mfma_f32_16x16x32_bf16 v[52:55], v[140:143], v[212:215], 0
	v_mfma_f32_16x16x32_bf16 v[110:113], v[132:135], v[228:231], 0
	v_mfma_f32_16x16x32_bf16 v[44:47], v[140:143], v[228:231], 0
	v_mfma_f32_16x16x32_bf16 v[94:97], v[132:135], v[236:239], 0
	v_mfma_f32_16x16x32_bf16 v[28:31], v[140:143], v[236:239], 0
	v_mfma_f32_16x16x32_bf16 v[126:129], v[136:139], v[198:201], v[126:129]
	v_mfma_f32_16x16x32_bf16 v[60:63], v[144:147], v[198:201], v[60:63]
	v_mfma_f32_16x16x32_bf16 v[118:121], v[136:139], v[224:227], v[118:121]
	v_mfma_f32_16x16x32_bf16 v[52:55], v[144:147], v[224:227], v[52:55]
	v_mfma_f32_16x16x32_bf16 v[110:113], v[136:139], v[232:235], v[110:113]
	v_mfma_f32_16x16x32_bf16 v[44:47], v[144:147], v[232:235], v[44:47]
	v_mfma_f32_16x16x32_bf16 v[94:97], v[136:139], v[240:243], v[94:97]
	v_mfma_f32_16x16x32_bf16 v[28:31], v[144:147], v[240:243], v[28:31]
	v_mfma_f32_16x16x32_bf16 v[122:125], v[148:151], v[194:197], 0
	v_mfma_f32_16x16x32_bf16 v[56:59], v[156:159], v[194:197], 0
	v_mfma_f32_16x16x32_bf16 v[114:117], v[148:151], v[212:215], 0
	v_mfma_f32_16x16x32_bf16 v[48:51], v[156:159], v[212:215], 0
	v_mfma_f32_16x16x32_bf16 v[102:105], v[148:151], v[228:231], 0
	v_mfma_f32_16x16x32_bf16 v[36:39], v[156:159], v[228:231], 0
	v_mfma_f32_16x16x32_bf16 v[88:91], v[148:151], v[236:239], 0
	v_mfma_f32_16x16x32_bf16 v[24:27], v[156:159], v[236:239], 0
	v_mfma_f32_16x16x32_bf16 v[122:125], v[152:155], v[198:201], v[122:125]
	v_mfma_f32_16x16x32_bf16 v[56:59], v[174:177], v[198:201], v[56:59]
	v_mfma_f32_16x16x32_bf16 v[114:117], v[152:155], v[224:227], v[114:117]
	v_mfma_f32_16x16x32_bf16 v[48:51], v[174:177], v[224:227], v[48:51]
	v_mfma_f32_16x16x32_bf16 v[102:105], v[152:155], v[232:235], v[102:105]
	v_mfma_f32_16x16x32_bf16 v[36:39], v[174:177], v[232:235], v[36:39]
	v_mfma_f32_16x16x32_bf16 v[88:91], v[152:155], v[240:243], v[88:91]
	v_mfma_f32_16x16x32_bf16 v[24:27], v[174:177], v[240:243], v[24:27]
	s_barrier
	s_setprio 0
	s_add_i32 s68, s95, s57
	v_lshl_add_u64 v[160:161], s[88:89], 0, v[164:165]
	s_mov_b32 m0, s68
	ds_read_b128 v[194:197], v209 offset:16384
	ds_read_b128 v[198:201], v209 offset:17408
	ds_read_b128 v[212:215], v209 offset:18432
	ds_read_b128 v[224:227], v209 offset:19456
	ds_read_b128 v[228:231], v209 offset:20480
	ds_read_b128 v[232:235], v209 offset:21504
	ds_read_b128 v[236:239], v209 offset:22528
	ds_read_b128 v[240:243], v209 offset:23552
	global_load_lds_dwordx4 v[160:161], off
	s_add_i32 m0, s68, 0x2000
	s_add_u32 s68, s88, 0x40000
	v_lshl_add_u64 v[216:217], s[88:89], 0, v[166:167]
	s_addc_u32 s69, s89, 0
	s_add_i32 s70, s96, s57
	global_load_lds_dwordx4 v[216:217], off
	s_mov_b32 m0, s70
	v_lshl_add_u64 v[220:221], s[68:69], 0, v[164:165]
	global_load_lds_dwordx4 v[220:221], off
	s_add_i32 m0, s70, 0x2000
	v_lshl_add_u64 v[220:221], s[68:69], 0, v[166:167]
	s_add_u32 s68, s90, s71
	global_load_lds_dwordx4 v[220:221], off
	v_lshl_add_u64 v[220:221], s[90:91], 0, v[162:163]
	s_mov_b32 m0, s59
	s_addc_u32 s69, s91, s51
	global_load_lds_dwordx4 v[220:221], off
	s_mov_b32 m0, s61
	v_lshl_add_u64 v[244:245], s[68:69], 0, v[162:163]
	global_load_lds_dwordx4 v[244:245], off
	s_waitcnt vmcnt(8) lgkmcnt(0)
	s_setprio 1
	s_barrier
	v_mfma_f32_16x16x32_bf16 v[84:87], v[132:135], v[194:197], 0
	v_mfma_f32_16x16x32_bf16 v[20:23], v[140:143], v[194:197], 0
	v_mfma_f32_16x16x32_bf16 v[76:79], v[132:135], v[212:215], 0
	v_mfma_f32_16x16x32_bf16 v[12:15], v[140:143], v[212:215], 0
	v_mfma_f32_16x16x32_bf16 v[68:71], v[132:135], v[228:231], 0
	v_mfma_f32_16x16x32_bf16 v[4:7], v[140:143], v[228:231], 0
	v_mfma_f32_16x16x32_bf16 v[106:109], v[132:135], v[236:239], 0
	v_mfma_f32_16x16x32_bf16 v[40:43], v[140:143], v[236:239], 0
	v_mfma_f32_16x16x32_bf16 v[84:87], v[136:139], v[198:201], v[84:87]
	v_mfma_f32_16x16x32_bf16 v[20:23], v[144:147], v[198:201], v[20:23]
	v_mfma_f32_16x16x32_bf16 v[76:79], v[136:139], v[224:227], v[76:79]
	v_mfma_f32_16x16x32_bf16 v[12:15], v[144:147], v[224:227], v[12:15]
	v_mfma_f32_16x16x32_bf16 v[68:71], v[136:139], v[232:235], v[68:71]
	v_mfma_f32_16x16x32_bf16 v[4:7], v[144:147], v[232:235], v[4:7]
	v_mfma_f32_16x16x32_bf16 v[106:109], v[136:139], v[240:243], v[106:109]
	v_mfma_f32_16x16x32_bf16 v[40:43], v[144:147], v[240:243], v[40:43]
	v_mfma_f32_16x16x32_bf16 v[80:83], v[148:151], v[194:197], 0
	v_mfma_f32_16x16x32_bf16 v[16:19], v[156:159], v[194:197], 0
	v_mfma_f32_16x16x32_bf16 v[72:75], v[148:151], v[212:215], 0
	v_mfma_f32_16x16x32_bf16 v[8:11], v[156:159], v[212:215], 0
	v_mfma_f32_16x16x32_bf16 v[64:67], v[148:151], v[228:231], 0
	v_mfma_f32_16x16x32_bf16 v[0:3], v[156:159], v[228:231], 0
	v_mfma_f32_16x16x32_bf16 v[98:101], v[148:151], v[236:239], 0
	v_mfma_f32_16x16x32_bf16 v[32:35], v[156:159], v[236:239], 0
	v_mfma_f32_16x16x32_bf16 v[80:83], v[152:155], v[198:201], v[80:83]
	v_mfma_f32_16x16x32_bf16 v[16:19], v[174:177], v[198:201], v[16:19]
	v_mfma_f32_16x16x32_bf16 v[72:75], v[152:155], v[224:227], v[72:75]
	v_mfma_f32_16x16x32_bf16 v[8:11], v[174:177], v[224:227], v[8:11]
	v_mfma_f32_16x16x32_bf16 v[64:67], v[152:155], v[232:235], v[64:67]
	v_mfma_f32_16x16x32_bf16 v[0:3], v[174:177], v[232:235], v[0:3]
	v_mfma_f32_16x16x32_bf16 v[98:101], v[152:155], v[240:243], v[98:101]
	v_mfma_f32_16x16x32_bf16 v[32:35], v[174:177], v[240:243], v[32:35]
	s_barrier
	s_setprio 0
	s_add_i32 s70, 0, 0x18000
	s_add_i32 s14, 0, 0x1c000
	v_add_u32_e32 v144, s70, v203
	v_add_u32_e32 v174, s14, v203
	ds_read_b128 v[132:135], v144
	ds_read_b128 v[136:139], v144 offset:1024
	ds_read_b128 v[140:143], v144 offset:2048
	ds_read_b128 v[144:147], v144 offset:3072
	ds_read_b128 v[148:151], v174
	ds_read_b128 v[152:155], v174 offset:1024
	ds_read_b128 v[156:159], v174 offset:2048
	ds_read_b128 v[174:177], v174 offset:3072
	s_add_u32 s68, s90, 0x2000
	s_addc_u32 s69, s91, 0
	v_lshl_add_u64 v[246:247], s[68:69], 0, v[162:163]
	s_add_u32 s68, s68, s71
	s_mov_b32 m0, s63
	s_addc_u32 s69, s69, s51
	ds_read_b128 v[194:197], v209 offset:32768
	ds_read_b128 v[198:201], v209 offset:33792
	ds_read_b128 v[212:215], v209 offset:34816
	ds_read_b128 v[224:227], v209 offset:35840
	ds_read_b128 v[228:231], v209 offset:36864
	ds_read_b128 v[232:235], v209 offset:37888
	ds_read_b128 v[236:239], v209 offset:38912
	ds_read_b128 v[240:243], v209 offset:39936
	global_load_lds_dwordx4 v[246:247], off
	s_mov_b32 m0, s67
	v_lshl_add_u64 v[246:247], s[68:69], 0, v[162:163]
	global_load_lds_dwordx4 v[246:247], off
	s_waitcnt vmcnt(8) lgkmcnt(0)
	s_setprio 1
	s_barrier
	v_mfma_f32_16x16x32_bf16 v[126:129], v[132:135], v[194:197], v[126:129]
	v_mfma_f32_16x16x32_bf16 v[60:63], v[140:143], v[194:197], v[60:63]
	v_mfma_f32_16x16x32_bf16 v[118:121], v[132:135], v[212:215], v[118:121]
	v_mfma_f32_16x16x32_bf16 v[52:55], v[140:143], v[212:215], v[52:55]
	v_mfma_f32_16x16x32_bf16 v[110:113], v[132:135], v[228:231], v[110:113]
	v_mfma_f32_16x16x32_bf16 v[44:47], v[140:143], v[228:231], v[44:47]
	v_mfma_f32_16x16x32_bf16 v[94:97], v[132:135], v[236:239], v[94:97]
	v_mfma_f32_16x16x32_bf16 v[28:31], v[140:143], v[236:239], v[28:31]
	v_mfma_f32_16x16x32_bf16 v[126:129], v[136:139], v[198:201], v[126:129]
	v_mfma_f32_16x16x32_bf16 v[60:63], v[144:147], v[198:201], v[60:63]
	v_mfma_f32_16x16x32_bf16 v[118:121], v[136:139], v[224:227], v[118:121]
	v_mfma_f32_16x16x32_bf16 v[52:55], v[144:147], v[224:227], v[52:55]
	v_mfma_f32_16x16x32_bf16 v[110:113], v[136:139], v[232:235], v[110:113]
	v_mfma_f32_16x16x32_bf16 v[44:47], v[144:147], v[232:235], v[44:47]
	v_mfma_f32_16x16x32_bf16 v[94:97], v[136:139], v[240:243], v[94:97]
	v_mfma_f32_16x16x32_bf16 v[28:31], v[144:147], v[240:243], v[28:31]
	v_mfma_f32_16x16x32_bf16 v[122:125], v[148:151], v[194:197], v[122:125]
	v_mfma_f32_16x16x32_bf16 v[56:59], v[156:159], v[194:197], v[56:59]
	v_mfma_f32_16x16x32_bf16 v[114:117], v[148:151], v[212:215], v[114:117]
	v_mfma_f32_16x16x32_bf16 v[48:51], v[156:159], v[212:215], v[48:51]
	v_mfma_f32_16x16x32_bf16 v[102:105], v[148:151], v[228:231], v[102:105]
	v_mfma_f32_16x16x32_bf16 v[36:39], v[156:159], v[228:231], v[36:39]
	v_mfma_f32_16x16x32_bf16 v[88:91], v[148:151], v[236:239], v[88:91]
	v_mfma_f32_16x16x32_bf16 v[24:27], v[156:159], v[236:239], v[24:27]
	v_mfma_f32_16x16x32_bf16 v[122:125], v[152:155], v[198:201], v[122:125]
	v_mfma_f32_16x16x32_bf16 v[56:59], v[174:177], v[198:201], v[56:59]
	v_mfma_f32_16x16x32_bf16 v[114:117], v[152:155], v[224:227], v[114:117]
	v_mfma_f32_16x16x32_bf16 v[48:51], v[174:177], v[224:227], v[48:51]
	v_mfma_f32_16x16x32_bf16 v[102:105], v[152:155], v[232:235], v[102:105]
	v_mfma_f32_16x16x32_bf16 v[36:39], v[174:177], v[232:235], v[36:39]
	v_mfma_f32_16x16x32_bf16 v[88:91], v[152:155], v[240:243], v[88:91]
	v_mfma_f32_16x16x32_bf16 v[24:27], v[174:177], v[240:243], v[24:27]
	s_barrier
	s_setprio 0
	s_add_i32 s15, s70, s57
	v_lshl_add_u64 v[160:161], v[160:161], 0, s[22:23]
	s_mov_b32 m0, s15
	ds_read_b128 v[194:197], v209 offset:49152
	ds_read_b128 v[198:201], v209 offset:50176
	ds_read_b128 v[212:215], v209 offset:51200
	ds_read_b128 v[224:227], v209 offset:52224
	ds_read_b128 v[228:231], v209 offset:53248
	ds_read_b128 v[232:235], v209 offset:54272
	ds_read_b128 v[236:239], v209 offset:55296
	ds_read_b128 v[240:243], v209 offset:56320
	global_load_lds_dwordx4 v[160:161], off
	s_add_i32 m0, s15, 0x2000
	s_add_u32 s68, s88, 0x40080
	v_lshl_add_u64 v[160:161], v[216:217], 0, s[22:23]
	s_addc_u32 s69, s89, 0
	s_add_i32 s14, s14, s57
	global_load_lds_dwordx4 v[160:161], off
	s_mov_b32 m0, s14
	v_lshl_add_u64 v[160:161], s[68:69], 0, v[164:165]
	global_load_lds_dwordx4 v[160:161], off
	s_add_i32 m0, s14, 0x2000
	v_lshl_add_u64 v[160:161], s[68:69], 0, v[166:167]
	global_load_lds_dwordx4 v[160:161], off
	s_mov_b32 m0, s75
	v_lshl_add_u64 v[160:161], v[220:221], 0, s[22:23]
	global_load_lds_dwordx4 v[160:161], off
	s_mov_b32 m0, s92
	v_lshl_add_u64 v[160:161], v[244:245], 0, s[22:23]
	global_load_lds_dwordx4 v[160:161], off
	s_waitcnt vmcnt(8) lgkmcnt(0)
	s_setprio 1
	s_barrier
	v_mfma_f32_16x16x32_bf16 v[84:87], v[132:135], v[194:197], v[84:87]
	v_mfma_f32_16x16x32_bf16 v[20:23], v[140:143], v[194:197], v[20:23]
	v_mfma_f32_16x16x32_bf16 v[76:79], v[132:135], v[212:215], v[76:79]
	v_mfma_f32_16x16x32_bf16 v[12:15], v[140:143], v[212:215], v[12:15]
	v_mfma_f32_16x16x32_bf16 v[68:71], v[132:135], v[228:231], v[68:71]
	v_mfma_f32_16x16x32_bf16 v[4:7], v[140:143], v[228:231], v[4:7]
	v_mfma_f32_16x16x32_bf16 v[106:109], v[132:135], v[236:239], v[106:109]
	v_mfma_f32_16x16x32_bf16 v[40:43], v[140:143], v[236:239], v[40:43]
	v_mfma_f32_16x16x32_bf16 v[84:87], v[136:139], v[198:201], v[84:87]
	v_mfma_f32_16x16x32_bf16 v[20:23], v[144:147], v[198:201], v[20:23]
	v_mfma_f32_16x16x32_bf16 v[76:79], v[136:139], v[224:227], v[76:79]
	v_mfma_f32_16x16x32_bf16 v[12:15], v[144:147], v[224:227], v[12:15]
	v_mfma_f32_16x16x32_bf16 v[68:71], v[136:139], v[232:235], v[68:71]
	v_mfma_f32_16x16x32_bf16 v[4:7], v[144:147], v[232:235], v[4:7]
	v_mfma_f32_16x16x32_bf16 v[106:109], v[136:139], v[240:243], v[106:109]
	v_mfma_f32_16x16x32_bf16 v[40:43], v[144:147], v[240:243], v[40:43]
	v_mfma_f32_16x16x32_bf16 v[80:83], v[148:151], v[194:197], v[80:83]
	v_mfma_f32_16x16x32_bf16 v[16:19], v[156:159], v[194:197], v[16:19]
	v_mfma_f32_16x16x32_bf16 v[72:75], v[148:151], v[212:215], v[72:75]
	v_mfma_f32_16x16x32_bf16 v[8:11], v[156:159], v[212:215], v[8:11]
	v_mfma_f32_16x16x32_bf16 v[64:67], v[148:151], v[228:231], v[64:67]
	v_mfma_f32_16x16x32_bf16 v[0:3], v[156:159], v[228:231], v[0:3]
	v_mfma_f32_16x16x32_bf16 v[98:101], v[148:151], v[236:239], v[98:101]
	v_mfma_f32_16x16x32_bf16 v[32:35], v[156:159], v[236:239], v[32:35]
	v_mfma_f32_16x16x32_bf16 v[80:83], v[152:155], v[198:201], v[80:83]
	v_mfma_f32_16x16x32_bf16 v[16:19], v[174:177], v[198:201], v[16:19]
	v_mfma_f32_16x16x32_bf16 v[72:75], v[152:155], v[224:227], v[72:75]
	v_mfma_f32_16x16x32_bf16 v[8:11], v[174:177], v[224:227], v[8:11]
	v_mfma_f32_16x16x32_bf16 v[64:67], v[152:155], v[232:235], v[64:67]
	v_mfma_f32_16x16x32_bf16 v[0:3], v[174:177], v[232:235], v[0:3]
	v_mfma_f32_16x16x32_bf16 v[98:101], v[152:155], v[240:243], v[98:101]
	v_mfma_f32_16x16x32_bf16 v[32:35], v[174:177], v[240:243], v[32:35]
	s_barrier
	s_setprio 0
	s_add_i32 s50, s50, 2
	s_add_u32 s0, s0, 0x100
	s_addc_u32 s1, s1, 0
	s_cmp_gt_u32 s50, 13
.LBB0_565:
	ds_read_b128 v[132:135], v207
	ds_read_b128 v[136:139], v207 offset:1024
	ds_read_b128 v[140:143], v207 offset:2048
	ds_read_b128 v[144:147], v207 offset:3072
	ds_read_b128 v[148:151], v208
	ds_read_b128 v[152:155], v208 offset:1024
	ds_read_b128 v[156:159], v208 offset:2048
	ds_read_b128 v[174:177], v208 offset:3072
	s_add_u32 s51, s84, s0
	s_addc_u32 s68, s85, s1
	s_add_u32 s51, s51, 0x100
	s_addc_u32 s68, s68, 0
	s_add_u32 s69, vcc_lo, s0
	s_addc_u32 s70, vcc_hi, s1
	s_cmpk_eq_i32 s0, 0x700
	s_cselect_b32 s91, s79, s68
	s_cselect_b32 s90, s78, s51
	s_cselect_b32 s51, s81, s87
	s_cselect_b32 s71, s80, s86
	s_cselect_b32 s89, s13, s70
	s_cselect_b32 s88, s77, s69
	v_lshl_add_u64 v[160:161], v[92:93], 0, s[0:1]
	s_add_i32 m0, s59, 0xc000
	ds_read_b128 v[194:197], v209
	ds_read_b128 v[198:201], v209 offset:1024
	ds_read_b128 v[212:215], v209 offset:2048
	ds_read_b128 v[224:227], v209 offset:3072
	ds_read_b128 v[228:231], v209 offset:4096
	ds_read_b128 v[232:235], v209 offset:5120
	ds_read_b128 v[236:239], v209 offset:6144
	ds_read_b128 v[240:243], v209 offset:7168
	global_load_lds_dwordx4 v[160:161], off
	s_add_i32 m0, s59, 0xe000
	v_lshl_add_u64 v[160:161], v[130:131], 0, s[0:1]
	global_load_lds_dwordx4 v[160:161], off
	s_waitcnt vmcnt(8) lgkmcnt(0)
	s_setprio 1
	s_barrier
	v_mfma_f32_16x16x32_bf16 v[126:129], v[132:135], v[194:197], v[126:129]
	v_mfma_f32_16x16x32_bf16 v[60:63], v[140:143], v[194:197], v[60:63]
	v_mfma_f32_16x16x32_bf16 v[118:121], v[132:135], v[212:215], v[118:121]
	v_mfma_f32_16x16x32_bf16 v[52:55], v[140:143], v[212:215], v[52:55]
	v_mfma_f32_16x16x32_bf16 v[110:113], v[132:135], v[228:231], v[110:113]
	v_mfma_f32_16x16x32_bf16 v[44:47], v[140:143], v[228:231], v[44:47]
	v_mfma_f32_16x16x32_bf16 v[94:97], v[132:135], v[236:239], v[94:97]
	v_mfma_f32_16x16x32_bf16 v[28:31], v[140:143], v[236:239], v[28:31]
	v_mfma_f32_16x16x32_bf16 v[126:129], v[136:139], v[198:201], v[126:129]
	v_mfma_f32_16x16x32_bf16 v[60:63], v[144:147], v[198:201], v[60:63]
	v_mfma_f32_16x16x32_bf16 v[118:121], v[136:139], v[224:227], v[118:121]
	v_mfma_f32_16x16x32_bf16 v[52:55], v[144:147], v[224:227], v[52:55]
	v_mfma_f32_16x16x32_bf16 v[110:113], v[136:139], v[232:235], v[110:113]
	v_mfma_f32_16x16x32_bf16 v[44:47], v[144:147], v[232:235], v[44:47]
	v_mfma_f32_16x16x32_bf16 v[94:97], v[136:139], v[240:243], v[94:97]
	v_mfma_f32_16x16x32_bf16 v[28:31], v[144:147], v[240:243], v[28:31]
	v_mfma_f32_16x16x32_bf16 v[122:125], v[148:151], v[194:197], v[122:125]
	v_mfma_f32_16x16x32_bf16 v[56:59], v[156:159], v[194:197], v[56:59]
	v_mfma_f32_16x16x32_bf16 v[114:117], v[148:151], v[212:215], v[114:117]
	v_mfma_f32_16x16x32_bf16 v[48:51], v[156:159], v[212:215], v[48:51]
	v_mfma_f32_16x16x32_bf16 v[102:105], v[148:151], v[228:231], v[102:105]
	v_mfma_f32_16x16x32_bf16 v[36:39], v[156:159], v[228:231], v[36:39]
	v_mfma_f32_16x16x32_bf16 v[88:91], v[148:151], v[236:239], v[88:91]
	v_mfma_f32_16x16x32_bf16 v[24:27], v[156:159], v[236:239], v[24:27]
	v_mfma_f32_16x16x32_bf16 v[122:125], v[152:155], v[198:201], v[122:125]
	v_mfma_f32_16x16x32_bf16 v[56:59], v[174:177], v[198:201], v[56:59]
	v_mfma_f32_16x16x32_bf16 v[114:117], v[152:155], v[224:227], v[114:117]
	v_mfma_f32_16x16x32_bf16 v[48:51], v[174:177], v[224:227], v[48:51]
	v_mfma_f32_16x16x32_bf16 v[102:105], v[152:155], v[232:235], v[102:105]
	v_mfma_f32_16x16x32_bf16 v[36:39], v[174:177], v[232:235], v[36:39]
	v_mfma_f32_16x16x32_bf16 v[88:91], v[152:155], v[240:243], v[88:91]
	v_mfma_f32_16x16x32_bf16 v[24:27], v[174:177], v[240:243], v[24:27]
	s_barrier
	s_setprio 0
	s_add_i32 s68, s95, s57
	v_lshl_add_u64 v[160:161], s[88:89], 0, v[164:165]
	s_mov_b32 m0, s68
	ds_read_b128 v[194:197], v209 offset:16384
	ds_read_b128 v[198:201], v209 offset:17408
	ds_read_b128 v[212:215], v209 offset:18432
	ds_read_b128 v[224:227], v209 offset:19456
	ds_read_b128 v[228:231], v209 offset:20480
	ds_read_b128 v[232:235], v209 offset:21504
	ds_read_b128 v[236:239], v209 offset:22528
	ds_read_b128 v[240:243], v209 offset:23552
	global_load_lds_dwordx4 v[160:161], off
	s_add_i32 m0, s68, 0x2000
	s_add_u32 s68, s88, 0x40000
	v_lshl_add_u64 v[216:217], s[88:89], 0, v[166:167]
	s_addc_u32 s69, s89, 0
	s_add_i32 s70, s96, s57
	global_load_lds_dwordx4 v[216:217], off
	s_mov_b32 m0, s70
	v_lshl_add_u64 v[220:221], s[68:69], 0, v[164:165]
	global_load_lds_dwordx4 v[220:221], off
	s_add_i32 m0, s70, 0x2000
	v_lshl_add_u64 v[220:221], s[68:69], 0, v[166:167]
	s_add_u32 s68, s90, s71
	global_load_lds_dwordx4 v[220:221], off
	v_lshl_add_u64 v[220:221], s[90:91], 0, v[162:163]
	s_mov_b32 m0, s59
	s_addc_u32 s69, s91, s51
	global_load_lds_dwordx4 v[220:221], off
	s_mov_b32 m0, s61
	v_lshl_add_u64 v[244:245], s[68:69], 0, v[162:163]
	global_load_lds_dwordx4 v[244:245], off
	s_waitcnt vmcnt(8) lgkmcnt(0)
	s_setprio 1
	s_barrier
	v_mfma_f32_16x16x32_bf16 v[84:87], v[132:135], v[194:197], v[84:87]
	v_mfma_f32_16x16x32_bf16 v[20:23], v[140:143], v[194:197], v[20:23]
	v_mfma_f32_16x16x32_bf16 v[76:79], v[132:135], v[212:215], v[76:79]
	v_mfma_f32_16x16x32_bf16 v[12:15], v[140:143], v[212:215], v[12:15]
	v_mfma_f32_16x16x32_bf16 v[68:71], v[132:135], v[228:231], v[68:71]
	v_mfma_f32_16x16x32_bf16 v[4:7], v[140:143], v[228:231], v[4:7]
	v_mfma_f32_16x16x32_bf16 v[106:109], v[132:135], v[236:239], v[106:109]
	v_mfma_f32_16x16x32_bf16 v[40:43], v[140:143], v[236:239], v[40:43]
	v_mfma_f32_16x16x32_bf16 v[84:87], v[136:139], v[198:201], v[84:87]
	v_mfma_f32_16x16x32_bf16 v[20:23], v[144:147], v[198:201], v[20:23]
	v_mfma_f32_16x16x32_bf16 v[76:79], v[136:139], v[224:227], v[76:79]
	v_mfma_f32_16x16x32_bf16 v[12:15], v[144:147], v[224:227], v[12:15]
	v_mfma_f32_16x16x32_bf16 v[68:71], v[136:139], v[232:235], v[68:71]
	v_mfma_f32_16x16x32_bf16 v[4:7], v[144:147], v[232:235], v[4:7]
	v_mfma_f32_16x16x32_bf16 v[106:109], v[136:139], v[240:243], v[106:109]
	v_mfma_f32_16x16x32_bf16 v[40:43], v[144:147], v[240:243], v[40:43]
	v_mfma_f32_16x16x32_bf16 v[80:83], v[148:151], v[194:197], v[80:83]
	v_mfma_f32_16x16x32_bf16 v[16:19], v[156:159], v[194:197], v[16:19]
	v_mfma_f32_16x16x32_bf16 v[72:75], v[148:151], v[212:215], v[72:75]
	v_mfma_f32_16x16x32_bf16 v[8:11], v[156:159], v[212:215], v[8:11]
	v_mfma_f32_16x16x32_bf16 v[64:67], v[148:151], v[228:231], v[64:67]
	v_mfma_f32_16x16x32_bf16 v[0:3], v[156:159], v[228:231], v[0:3]
	v_mfma_f32_16x16x32_bf16 v[98:101], v[148:151], v[236:239], v[98:101]
	v_mfma_f32_16x16x32_bf16 v[32:35], v[156:159], v[236:239], v[32:35]
	v_mfma_f32_16x16x32_bf16 v[80:83], v[152:155], v[198:201], v[80:83]
	v_mfma_f32_16x16x32_bf16 v[16:19], v[174:177], v[198:201], v[16:19]
	v_mfma_f32_16x16x32_bf16 v[72:75], v[152:155], v[224:227], v[72:75]
	v_mfma_f32_16x16x32_bf16 v[8:11], v[174:177], v[224:227], v[8:11]
	v_mfma_f32_16x16x32_bf16 v[64:67], v[152:155], v[232:235], v[64:67]
	v_mfma_f32_16x16x32_bf16 v[0:3], v[174:177], v[232:235], v[0:3]
	v_mfma_f32_16x16x32_bf16 v[98:101], v[152:155], v[240:243], v[98:101]
	v_mfma_f32_16x16x32_bf16 v[32:35], v[174:177], v[240:243], v[32:35]
	s_barrier
	s_setprio 0
	s_add_i32 s70, 0, 0x18000
	s_add_i32 s14, 0, 0x1c000
	v_add_u32_e32 v144, s70, v203
	v_add_u32_e32 v174, s14, v203
	ds_read_b128 v[132:135], v144
	ds_read_b128 v[136:139], v144 offset:1024
	ds_read_b128 v[140:143], v144 offset:2048
	ds_read_b128 v[144:147], v144 offset:3072
	ds_read_b128 v[148:151], v174
	ds_read_b128 v[152:155], v174 offset:1024
	ds_read_b128 v[156:159], v174 offset:2048
	ds_read_b128 v[174:177], v174 offset:3072
	s_add_u32 s68, s90, 0x2000
	s_addc_u32 s69, s91, 0
	v_lshl_add_u64 v[246:247], s[68:69], 0, v[162:163]
	s_add_u32 s68, s68, s71
	s_mov_b32 m0, s63
	s_addc_u32 s69, s69, s51
	ds_read_b128 v[194:197], v209 offset:32768
	ds_read_b128 v[198:201], v209 offset:33792
	ds_read_b128 v[212:215], v209 offset:34816
	ds_read_b128 v[224:227], v209 offset:35840
	ds_read_b128 v[228:231], v209 offset:36864
	ds_read_b128 v[232:235], v209 offset:37888
	ds_read_b128 v[236:239], v209 offset:38912
	ds_read_b128 v[240:243], v209 offset:39936
	global_load_lds_dwordx4 v[246:247], off
	s_mov_b32 m0, s67
	v_lshl_add_u64 v[246:247], s[68:69], 0, v[162:163]
	global_load_lds_dwordx4 v[246:247], off
	s_waitcnt vmcnt(8) lgkmcnt(0)
	s_setprio 1
	s_barrier
	v_mfma_f32_16x16x32_bf16 v[126:129], v[132:135], v[194:197], v[126:129]
	v_mfma_f32_16x16x32_bf16 v[60:63], v[140:143], v[194:197], v[60:63]
	v_mfma_f32_16x16x32_bf16 v[118:121], v[132:135], v[212:215], v[118:121]
	v_mfma_f32_16x16x32_bf16 v[52:55], v[140:143], v[212:215], v[52:55]
	v_mfma_f32_16x16x32_bf16 v[110:113], v[132:135], v[228:231], v[110:113]
	v_mfma_f32_16x16x32_bf16 v[44:47], v[140:143], v[228:231], v[44:47]
	v_mfma_f32_16x16x32_bf16 v[94:97], v[132:135], v[236:239], v[94:97]
	v_mfma_f32_16x16x32_bf16 v[28:31], v[140:143], v[236:239], v[28:31]
	v_mfma_f32_16x16x32_bf16 v[126:129], v[136:139], v[198:201], v[126:129]
	v_mfma_f32_16x16x32_bf16 v[60:63], v[144:147], v[198:201], v[60:63]
	v_mfma_f32_16x16x32_bf16 v[118:121], v[136:139], v[224:227], v[118:121]
	v_mfma_f32_16x16x32_bf16 v[52:55], v[144:147], v[224:227], v[52:55]
	v_mfma_f32_16x16x32_bf16 v[110:113], v[136:139], v[232:235], v[110:113]
	v_mfma_f32_16x16x32_bf16 v[44:47], v[144:147], v[232:235], v[44:47]
	v_mfma_f32_16x16x32_bf16 v[94:97], v[136:139], v[240:243], v[94:97]
	v_mfma_f32_16x16x32_bf16 v[28:31], v[144:147], v[240:243], v[28:31]
	v_mfma_f32_16x16x32_bf16 v[122:125], v[148:151], v[194:197], v[122:125]
	v_mfma_f32_16x16x32_bf16 v[56:59], v[156:159], v[194:197], v[56:59]
	v_mfma_f32_16x16x32_bf16 v[114:117], v[148:151], v[212:215], v[114:117]
	v_mfma_f32_16x16x32_bf16 v[48:51], v[156:159], v[212:215], v[48:51]
	v_mfma_f32_16x16x32_bf16 v[102:105], v[148:151], v[228:231], v[102:105]
	v_mfma_f32_16x16x32_bf16 v[36:39], v[156:159], v[228:231], v[36:39]
	v_mfma_f32_16x16x32_bf16 v[88:91], v[148:151], v[236:239], v[88:91]
	v_mfma_f32_16x16x32_bf16 v[24:27], v[156:159], v[236:239], v[24:27]
	v_mfma_f32_16x16x32_bf16 v[122:125], v[152:155], v[198:201], v[122:125]
	v_mfma_f32_16x16x32_bf16 v[56:59], v[174:177], v[198:201], v[56:59]
	v_mfma_f32_16x16x32_bf16 v[114:117], v[152:155], v[224:227], v[114:117]
	v_mfma_f32_16x16x32_bf16 v[48:51], v[174:177], v[224:227], v[48:51]
	v_mfma_f32_16x16x32_bf16 v[102:105], v[152:155], v[232:235], v[102:105]
	v_mfma_f32_16x16x32_bf16 v[36:39], v[174:177], v[232:235], v[36:39]
	v_mfma_f32_16x16x32_bf16 v[88:91], v[152:155], v[240:243], v[88:91]
	v_mfma_f32_16x16x32_bf16 v[24:27], v[174:177], v[240:243], v[24:27]
	s_barrier
	s_setprio 0
	s_add_i32 s15, s70, s57
	v_lshl_add_u64 v[160:161], v[160:161], 0, s[22:23]
	s_mov_b32 m0, s15
	ds_read_b128 v[194:197], v209 offset:49152
	ds_read_b128 v[198:201], v209 offset:50176
	ds_read_b128 v[212:215], v209 offset:51200
	ds_read_b128 v[224:227], v209 offset:52224
	ds_read_b128 v[228:231], v209 offset:53248
	ds_read_b128 v[232:235], v209 offset:54272
	ds_read_b128 v[236:239], v209 offset:55296
	ds_read_b128 v[240:243], v209 offset:56320
	global_load_lds_dwordx4 v[160:161], off
	s_add_i32 m0, s15, 0x2000
	s_add_u32 s68, s88, 0x40080
	v_lshl_add_u64 v[160:161], v[216:217], 0, s[22:23]
	s_addc_u32 s69, s89, 0
	s_add_i32 s14, s14, s57
	global_load_lds_dwordx4 v[160:161], off
	s_mov_b32 m0, s14
	v_lshl_add_u64 v[160:161], s[68:69], 0, v[164:165]
	global_load_lds_dwordx4 v[160:161], off
	s_add_i32 m0, s14, 0x2000
	v_lshl_add_u64 v[160:161], s[68:69], 0, v[166:167]
	global_load_lds_dwordx4 v[160:161], off
	s_mov_b32 m0, s75
	v_lshl_add_u64 v[160:161], v[220:221], 0, s[22:23]
	global_load_lds_dwordx4 v[160:161], off
	s_mov_b32 m0, s92
	v_lshl_add_u64 v[160:161], v[244:245], 0, s[22:23]
	global_load_lds_dwordx4 v[160:161], off
	s_waitcnt vmcnt(8) lgkmcnt(0)
	s_setprio 1
	s_barrier
	v_mfma_f32_16x16x32_bf16 v[84:87], v[132:135], v[194:197], v[84:87]
	v_mfma_f32_16x16x32_bf16 v[20:23], v[140:143], v[194:197], v[20:23]
	v_mfma_f32_16x16x32_bf16 v[76:79], v[132:135], v[212:215], v[76:79]
	v_mfma_f32_16x16x32_bf16 v[12:15], v[140:143], v[212:215], v[12:15]
	v_mfma_f32_16x16x32_bf16 v[68:71], v[132:135], v[228:231], v[68:71]
	v_mfma_f32_16x16x32_bf16 v[4:7], v[140:143], v[228:231], v[4:7]
	v_mfma_f32_16x16x32_bf16 v[106:109], v[132:135], v[236:239], v[106:109]
	v_mfma_f32_16x16x32_bf16 v[40:43], v[140:143], v[236:239], v[40:43]
	v_mfma_f32_16x16x32_bf16 v[84:87], v[136:139], v[198:201], v[84:87]
	v_mfma_f32_16x16x32_bf16 v[20:23], v[144:147], v[198:201], v[20:23]
	v_mfma_f32_16x16x32_bf16 v[76:79], v[136:139], v[224:227], v[76:79]
	v_mfma_f32_16x16x32_bf16 v[12:15], v[144:147], v[224:227], v[12:15]
	v_mfma_f32_16x16x32_bf16 v[68:71], v[136:139], v[232:235], v[68:71]
	v_mfma_f32_16x16x32_bf16 v[4:7], v[144:147], v[232:235], v[4:7]
	v_mfma_f32_16x16x32_bf16 v[106:109], v[136:139], v[240:243], v[106:109]
	v_mfma_f32_16x16x32_bf16 v[40:43], v[144:147], v[240:243], v[40:43]
	v_mfma_f32_16x16x32_bf16 v[80:83], v[148:151], v[194:197], v[80:83]
	v_mfma_f32_16x16x32_bf16 v[16:19], v[156:159], v[194:197], v[16:19]
	v_mfma_f32_16x16x32_bf16 v[72:75], v[148:151], v[212:215], v[72:75]
	v_mfma_f32_16x16x32_bf16 v[8:11], v[156:159], v[212:215], v[8:11]
	v_mfma_f32_16x16x32_bf16 v[64:67], v[148:151], v[228:231], v[64:67]
	v_mfma_f32_16x16x32_bf16 v[0:3], v[156:159], v[228:231], v[0:3]
	v_mfma_f32_16x16x32_bf16 v[98:101], v[148:151], v[236:239], v[98:101]
	v_mfma_f32_16x16x32_bf16 v[32:35], v[156:159], v[236:239], v[32:35]
	v_mfma_f32_16x16x32_bf16 v[80:83], v[152:155], v[198:201], v[80:83]
	v_mfma_f32_16x16x32_bf16 v[16:19], v[174:177], v[198:201], v[16:19]
	v_mfma_f32_16x16x32_bf16 v[72:75], v[152:155], v[224:227], v[72:75]
	v_mfma_f32_16x16x32_bf16 v[8:11], v[174:177], v[224:227], v[8:11]
	v_mfma_f32_16x16x32_bf16 v[64:67], v[152:155], v[232:235], v[64:67]
	v_mfma_f32_16x16x32_bf16 v[0:3], v[174:177], v[232:235], v[0:3]
	v_mfma_f32_16x16x32_bf16 v[98:101], v[152:155], v[240:243], v[98:101]
	v_mfma_f32_16x16x32_bf16 v[32:35], v[174:177], v[240:243], v[32:35]
	s_barrier
	s_setprio 0
	s_add_i32 s50, s50, 2
	s_add_u32 s0, s0, 0x100
	s_addc_u32 s1, s1, 0
	s_cmp_gt_u32 s50, 13
	s_cbranch_scc0 .LBB0_565
	s_and_b64 vcc, exec, s[30:31]
	s_cbranch_vccz .LBB0_568
	s_barrier

.LBB0_585:
	s_add_u32 s58, s46, s52
	s_addc_u32 s59, s47, s53
	s_add_u32 s56, s58, 0x100
	s_addc_u32 s57, s59, 0
	s_and_b64 s[54:55], s[50:51], exec
	s_cselect_b32 s54, s81, s56
	s_cselect_b32 s55, s13, s57
	s_add_u32 s52, s44, s52
	s_addc_u32 s53, s45, s53
	s_add_u32 s52, s52, 0x100
	ds_read_b128 v[148:151], v145
	ds_read_b128 v[152:155], v145 offset:1024
	ds_read_b128 v[156:159], v145 offset:2048
	ds_read_b128 v[160:163], v145 offset:3072
	ds_read_b128 v[164:167], v146
	ds_read_b128 v[168:171], v146 offset:1024
	ds_read_b128 v[172:175], v146 offset:2048
	ds_read_b128 v[176:179], v146 offset:3072
	s_addc_u32 s53, s53, 0
	s_and_b64 s[50:51], s[50:51], exec
	s_cselect_b32 s53, s39, s53
	s_cselect_b32 s52, s82, s52
	s_add_i32 s92, s75, s35
	s_add_i32 m0, s62, 0xc000
	s_add_i32 s93, s62, 0xe000
	s_add_i32 s89, s92, 0x2000
	s_add_u32 s56, s52, 0x10000
	s_addc_u32 s57, s53, 0
	s_add_i32 s88, 0, 0x18000
	s_add_i32 s91, s76, s35
	s_add_i32 s86, s88, s35
	s_add_i32 s90, s91, 0x2000
	s_add_i32 s87, 0, 0x1c000
	s_add_i32 s84, s86, 0x2000
	s_add_u32 s50, s52, 0x10080
	s_addc_u32 s51, s53, 0
	s_add_i32 s85, s87, s35
	s_add_i32 s83, s85, 0x2000
	v_lshl_add_u64 v[140:141], s[58:59], 0, v[134:135]
	v_lshl_add_u64 v[140:141], v[140:141], 0, s[68:69]
	ds_read_b128 v[180:183], v147
	ds_read_b128 v[184:187], v147 offset:1024
	ds_read_b128 v[188:191], v147 offset:2048
	ds_read_b128 v[192:195], v147 offset:3072
	ds_read_b128 v[196:199], v147 offset:4096
	ds_read_b128 v[200:203], v147 offset:5120
	ds_read_b128 v[204:207], v147 offset:6144
	ds_read_b128 v[208:211], v147 offset:7168
	global_load_lds_dwordx4 v[140:141], off
	v_lshl_add_u64 v[140:141], s[58:59], 0, v[130:131]
	s_mov_b64 s[58:59], 0x18080
	s_mov_b32 m0, s93
	v_lshl_add_u64 v[140:141], v[140:141], 0, s[58:59]
	global_load_lds_dwordx4 v[140:141], off
	s_waitcnt vmcnt(8) lgkmcnt(0)
	s_setprio 1
	s_barrier
	v_mfma_f32_16x16x32_bf16 v[124:127], v[148:151], v[180:183], v[124:127]
	v_mfma_f32_16x16x32_bf16 v[120:123], v[156:159], v[180:183], v[120:123]
	v_mfma_f32_16x16x32_bf16 v[112:115], v[148:151], v[188:191], v[112:115]
	v_mfma_f32_16x16x32_bf16 v[104:107], v[156:159], v[188:191], v[104:107]
	v_mfma_f32_16x16x32_bf16 v[96:99], v[148:151], v[196:199], v[96:99]
	v_mfma_f32_16x16x32_bf16 v[88:91], v[156:159], v[196:199], v[88:91]
	v_mfma_f32_16x16x32_bf16 v[80:83], v[148:151], v[204:207], v[80:83]
	v_mfma_f32_16x16x32_bf16 v[72:75], v[156:159], v[204:207], v[72:75]
	v_mfma_f32_16x16x32_bf16 v[124:127], v[152:155], v[184:187], v[124:127]
	v_mfma_f32_16x16x32_bf16 v[120:123], v[160:163], v[184:187], v[120:123]
	v_mfma_f32_16x16x32_bf16 v[112:115], v[152:155], v[192:195], v[112:115]
	v_mfma_f32_16x16x32_bf16 v[104:107], v[160:163], v[192:195], v[104:107]
	v_mfma_f32_16x16x32_bf16 v[96:99], v[152:155], v[200:203], v[96:99]
	v_mfma_f32_16x16x32_bf16 v[88:91], v[160:163], v[200:203], v[88:91]
	v_mfma_f32_16x16x32_bf16 v[80:83], v[152:155], v[208:211], v[80:83]
	v_mfma_f32_16x16x32_bf16 v[72:75], v[160:163], v[208:211], v[72:75]
	v_mfma_f32_16x16x32_bf16 v[116:119], v[164:167], v[180:183], v[116:119]
	v_mfma_f32_16x16x32_bf16 v[108:111], v[172:175], v[180:183], v[108:111]
	v_mfma_f32_16x16x32_bf16 v[100:103], v[164:167], v[188:191], v[100:103]
	v_mfma_f32_16x16x32_bf16 v[92:95], v[172:175], v[188:191], v[92:95]
	v_mfma_f32_16x16x32_bf16 v[84:87], v[164:167], v[196:199], v[84:87]
	v_mfma_f32_16x16x32_bf16 v[76:79], v[172:175], v[196:199], v[76:79]
	v_mfma_f32_16x16x32_bf16 v[68:71], v[164:167], v[204:207], v[68:71]
	v_mfma_f32_16x16x32_bf16 v[64:67], v[172:175], v[204:207], v[64:67]
	v_mfma_f32_16x16x32_bf16 v[116:119], v[168:171], v[184:187], v[116:119]
	v_mfma_f32_16x16x32_bf16 v[108:111], v[176:179], v[184:187], v[108:111]
	v_mfma_f32_16x16x32_bf16 v[100:103], v[168:171], v[192:195], v[100:103]
	v_mfma_f32_16x16x32_bf16 v[92:95], v[176:179], v[192:195], v[92:95]
	v_mfma_f32_16x16x32_bf16 v[84:87], v[168:171], v[200:203], v[84:87]
	v_mfma_f32_16x16x32_bf16 v[76:79], v[176:179], v[200:203], v[76:79]
	v_mfma_f32_16x16x32_bf16 v[68:71], v[168:171], v[208:211], v[68:71]
	v_mfma_f32_16x16x32_bf16 v[64:67], v[176:179], v[208:211], v[64:67]
	s_barrier
	s_setprio 0
	s_mov_b32 m0, s92
	v_lshl_add_u64 v[140:141], s[52:53], 0, v[132:133]
	ds_read_b128 v[180:183], v147 offset:16384
	ds_read_b128 v[184:187], v147 offset:17408
	ds_read_b128 v[188:191], v147 offset:18432
	ds_read_b128 v[192:195], v147 offset:19456
	ds_read_b128 v[196:199], v147 offset:20480
	ds_read_b128 v[200:203], v147 offset:21504
	ds_read_b128 v[204:207], v147 offset:22528
	ds_read_b128 v[208:211], v147 offset:23552
	global_load_lds_dwordx4 v[140:141], off
	v_lshl_add_u64 v[212:213], s[52:53], 0, v[128:129]
	s_mov_b32 m0, s89
	v_lshl_add_u64 v[214:215], s[56:57], 0, v[132:133]
	global_load_lds_dwordx4 v[212:213], off
	s_mov_b32 m0, s91
	v_lshl_add_u64 v[216:217], s[54:55], 0, v[130:131]
	global_load_lds_dwordx4 v[214:215], off
	v_lshl_add_u64 v[214:215], s[56:57], 0, v[128:129]
	s_mov_b32 m0, s90
	v_lshl_add_u64 v[220:221], v[216:217], 0, s[6:7]
	global_load_lds_dwordx4 v[214:215], off
	s_mov_b32 m0, s62
	v_lshl_add_u64 v[214:215], s[54:55], 0, v[134:135]
	global_load_lds_dwordx4 v[214:215], off
	s_mov_b32 m0, s63
	s_nop 0
	global_load_lds_dwordx4 v[220:221], off
	s_waitcnt vmcnt(8) lgkmcnt(0)
	s_setprio 1
	s_barrier
	v_mfma_f32_16x16x32_bf16 v[60:63], v[148:151], v[180:183], v[60:63]
	v_mfma_f32_16x16x32_bf16 v[56:59], v[156:159], v[180:183], v[56:59]
	v_mfma_f32_16x16x32_bf16 v[52:55], v[148:151], v[188:191], v[52:55]
	v_mfma_f32_16x16x32_bf16 v[44:47], v[156:159], v[188:191], v[44:47]
	v_mfma_f32_16x16x32_bf16 v[36:39], v[148:151], v[196:199], v[36:39]
	v_mfma_f32_16x16x32_bf16 v[28:31], v[156:159], v[196:199], v[28:31]
	v_mfma_f32_16x16x32_bf16 v[20:23], v[148:151], v[204:207], v[20:23]
	v_mfma_f32_16x16x32_bf16 v[12:15], v[156:159], v[204:207], v[12:15]
	v_mfma_f32_16x16x32_bf16 v[60:63], v[152:155], v[184:187], v[60:63]
	v_mfma_f32_16x16x32_bf16 v[56:59], v[160:163], v[184:187], v[56:59]
	v_mfma_f32_16x16x32_bf16 v[52:55], v[152:155], v[192:195], v[52:55]
	v_mfma_f32_16x16x32_bf16 v[44:47], v[160:163], v[192:195], v[44:47]
	v_mfma_f32_16x16x32_bf16 v[36:39], v[152:155], v[200:203], v[36:39]
	v_mfma_f32_16x16x32_bf16 v[28:31], v[160:163], v[200:203], v[28:31]
	v_mfma_f32_16x16x32_bf16 v[20:23], v[152:155], v[208:211], v[20:23]
	v_mfma_f32_16x16x32_bf16 v[12:15], v[160:163], v[208:211], v[12:15]
	v_mfma_f32_16x16x32_bf16 v[48:51], v[164:167], v[180:183], v[48:51]
	v_mfma_f32_16x16x32_bf16 v[40:43], v[172:175], v[180:183], v[40:43]
	v_mfma_f32_16x16x32_bf16 v[32:35], v[164:167], v[188:191], v[32:35]
	v_mfma_f32_16x16x32_bf16 v[24:27], v[172:175], v[188:191], v[24:27]
	v_mfma_f32_16x16x32_bf16 v[16:19], v[164:167], v[196:199], v[16:19]
	v_mfma_f32_16x16x32_bf16 v[8:11], v[172:175], v[196:199], v[8:11]
	v_mfma_f32_16x16x32_bf16 v[4:7], v[164:167], v[204:207], v[4:7]
	v_mfma_f32_16x16x32_bf16 v[0:3], v[172:175], v[204:207], v[0:3]
	v_mfma_f32_16x16x32_bf16 v[48:51], v[168:171], v[184:187], v[48:51]
	v_mfma_f32_16x16x32_bf16 v[40:43], v[176:179], v[184:187], v[40:43]
	v_mfma_f32_16x16x32_bf16 v[32:35], v[168:171], v[192:195], v[32:35]
	v_mfma_f32_16x16x32_bf16 v[24:27], v[176:179], v[192:195], v[24:27]
	v_mfma_f32_16x16x32_bf16 v[16:19], v[168:171], v[200:203], v[16:19]
	v_mfma_f32_16x16x32_bf16 v[8:11], v[176:179], v[200:203], v[8:11]
	v_mfma_f32_16x16x32_bf16 v[4:7], v[168:171], v[208:211], v[4:7]
	v_mfma_f32_16x16x32_bf16 v[0:3], v[176:179], v[208:211], v[0:3]
	s_barrier
	s_setprio 0
	v_add_u32_e32 v160, s88, v143
	v_add_u32_e32 v176, s87, v143
	ds_read_b128 v[148:151], v160
	ds_read_b128 v[152:155], v160 offset:1024
	ds_read_b128 v[156:159], v160 offset:2048
	ds_read_b128 v[160:163], v160 offset:3072
	ds_read_b128 v[164:167], v176
	ds_read_b128 v[168:171], v176 offset:1024
	ds_read_b128 v[172:175], v176 offset:2048
	ds_read_b128 v[176:179], v176 offset:3072
	s_mov_b32 m0, s64
	v_lshl_add_u64 v[220:221], v[214:215], 0, s[4:5]
	ds_read_b128 v[180:183], v147 offset:32768
	ds_read_b128 v[184:187], v147 offset:33792
	ds_read_b128 v[188:191], v147 offset:34816
	ds_read_b128 v[192:195], v147 offset:35840
	ds_read_b128 v[196:199], v147 offset:36864
	ds_read_b128 v[200:203], v147 offset:37888
	ds_read_b128 v[204:207], v147 offset:38912
	ds_read_b128 v[208:211], v147 offset:39936
	global_load_lds_dwordx4 v[220:221], off
	s_mov_b32 m0, s65
	v_lshl_add_u64 v[220:221], v[216:217], 0, s[8:9]
	global_load_lds_dwordx4 v[220:221], off
	s_waitcnt vmcnt(8) lgkmcnt(0)
	s_setprio 1
	s_barrier
	v_mfma_f32_16x16x32_bf16 v[124:127], v[148:151], v[180:183], v[124:127]
	v_mfma_f32_16x16x32_bf16 v[120:123], v[156:159], v[180:183], v[120:123]
	v_mfma_f32_16x16x32_bf16 v[112:115], v[148:151], v[188:191], v[112:115]
	v_mfma_f32_16x16x32_bf16 v[104:107], v[156:159], v[188:191], v[104:107]
	v_mfma_f32_16x16x32_bf16 v[96:99], v[148:151], v[196:199], v[96:99]
	v_mfma_f32_16x16x32_bf16 v[88:91], v[156:159], v[196:199], v[88:91]
	v_mfma_f32_16x16x32_bf16 v[80:83], v[148:151], v[204:207], v[80:83]
	v_mfma_f32_16x16x32_bf16 v[72:75], v[156:159], v[204:207], v[72:75]
	v_mfma_f32_16x16x32_bf16 v[124:127], v[152:155], v[184:187], v[124:127]
	v_mfma_f32_16x16x32_bf16 v[120:123], v[160:163], v[184:187], v[120:123]
	v_mfma_f32_16x16x32_bf16 v[112:115], v[152:155], v[192:195], v[112:115]
	v_mfma_f32_16x16x32_bf16 v[104:107], v[160:163], v[192:195], v[104:107]
	v_mfma_f32_16x16x32_bf16 v[96:99], v[152:155], v[200:203], v[96:99]
	v_mfma_f32_16x16x32_bf16 v[88:91], v[160:163], v[200:203], v[88:91]
	v_mfma_f32_16x16x32_bf16 v[80:83], v[152:155], v[208:211], v[80:83]
	v_mfma_f32_16x16x32_bf16 v[72:75], v[160:163], v[208:211], v[72:75]
	v_mfma_f32_16x16x32_bf16 v[116:119], v[164:167], v[180:183], v[116:119]
	v_mfma_f32_16x16x32_bf16 v[108:111], v[172:175], v[180:183], v[108:111]
	v_mfma_f32_16x16x32_bf16 v[100:103], v[164:167], v[188:191], v[100:103]
	v_mfma_f32_16x16x32_bf16 v[92:95], v[172:175], v[188:191], v[92:95]
	v_mfma_f32_16x16x32_bf16 v[84:87], v[164:167], v[196:199], v[84:87]
	v_mfma_f32_16x16x32_bf16 v[76:79], v[172:175], v[196:199], v[76:79]
	v_mfma_f32_16x16x32_bf16 v[68:71], v[164:167], v[204:207], v[68:71]
	v_mfma_f32_16x16x32_bf16 v[64:67], v[172:175], v[204:207], v[64:67]
	v_mfma_f32_16x16x32_bf16 v[116:119], v[168:171], v[184:187], v[116:119]
	v_mfma_f32_16x16x32_bf16 v[108:111], v[176:179], v[184:187], v[108:111]
	v_mfma_f32_16x16x32_bf16 v[100:103], v[168:171], v[192:195], v[100:103]
	v_mfma_f32_16x16x32_bf16 v[92:95], v[176:179], v[192:195], v[92:95]
	v_mfma_f32_16x16x32_bf16 v[84:87], v[168:171], v[200:203], v[84:87]
	v_mfma_f32_16x16x32_bf16 v[76:79], v[176:179], v[200:203], v[76:79]
	v_mfma_f32_16x16x32_bf16 v[68:71], v[168:171], v[208:211], v[68:71]
	v_mfma_f32_16x16x32_bf16 v[64:67], v[176:179], v[208:211], v[64:67]
	s_barrier
	s_setprio 0
	s_mov_b32 m0, s86
	v_lshl_add_u64 v[140:141], v[140:141], 0, s[18:19]
	ds_read_b128 v[180:183], v147 offset:49152
	ds_read_b128 v[184:187], v147 offset:50176
	ds_read_b128 v[188:191], v147 offset:51200
	ds_read_b128 v[192:195], v147 offset:52224
	ds_read_b128 v[196:199], v147 offset:53248
	ds_read_b128 v[200:203], v147 offset:54272
	ds_read_b128 v[204:207], v147 offset:55296
	ds_read_b128 v[208:211], v147 offset:56320
	global_load_lds_dwordx4 v[140:141], off
	s_mov_b32 m0, s84
	v_lshl_add_u64 v[140:141], v[212:213], 0, s[18:19]
	global_load_lds_dwordx4 v[140:141], off
	s_mov_b32 m0, s85
	v_lshl_add_u64 v[140:141], s[50:51], 0, v[132:133]
	global_load_lds_dwordx4 v[140:141], off
	s_mov_b32 m0, s83
	v_lshl_add_u64 v[140:141], s[50:51], 0, v[128:129]
	global_load_lds_dwordx4 v[140:141], off
	s_mov_b32 m0, s67
	v_lshl_add_u64 v[140:141], v[214:215], 0, s[18:19]
	global_load_lds_dwordx4 v[140:141], off
	s_mov_b32 m0, s72
	v_lshl_add_u64 v[140:141], v[216:217], 0, s[20:21]
	global_load_lds_dwordx4 v[140:141], off
	s_waitcnt vmcnt(8) lgkmcnt(0)
	s_setprio 1
	s_barrier
	v_mfma_f32_16x16x32_bf16 v[60:63], v[148:151], v[180:183], v[60:63]
	v_mfma_f32_16x16x32_bf16 v[56:59], v[156:159], v[180:183], v[56:59]
	v_mfma_f32_16x16x32_bf16 v[52:55], v[148:151], v[188:191], v[52:55]
	v_mfma_f32_16x16x32_bf16 v[44:47], v[156:159], v[188:191], v[44:47]
	v_mfma_f32_16x16x32_bf16 v[36:39], v[148:151], v[196:199], v[36:39]
	v_mfma_f32_16x16x32_bf16 v[28:31], v[156:159], v[196:199], v[28:31]
	v_mfma_f32_16x16x32_bf16 v[20:23], v[148:151], v[204:207], v[20:23]
	v_mfma_f32_16x16x32_bf16 v[12:15], v[156:159], v[204:207], v[12:15]
	v_mfma_f32_16x16x32_bf16 v[60:63], v[152:155], v[184:187], v[60:63]
	v_mfma_f32_16x16x32_bf16 v[56:59], v[160:163], v[184:187], v[56:59]
	v_mfma_f32_16x16x32_bf16 v[52:55], v[152:155], v[192:195], v[52:55]
	v_mfma_f32_16x16x32_bf16 v[44:47], v[160:163], v[192:195], v[44:47]
	v_mfma_f32_16x16x32_bf16 v[36:39], v[152:155], v[200:203], v[36:39]
	v_mfma_f32_16x16x32_bf16 v[28:31], v[160:163], v[200:203], v[28:31]
	v_mfma_f32_16x16x32_bf16 v[20:23], v[152:155], v[208:211], v[20:23]
	v_mfma_f32_16x16x32_bf16 v[12:15], v[160:163], v[208:211], v[12:15]
	v_mfma_f32_16x16x32_bf16 v[48:51], v[164:167], v[180:183], v[48:51]
	v_mfma_f32_16x16x32_bf16 v[40:43], v[172:175], v[180:183], v[40:43]
	v_mfma_f32_16x16x32_bf16 v[32:35], v[164:167], v[188:191], v[32:35]
	v_mfma_f32_16x16x32_bf16 v[24:27], v[172:175], v[188:191], v[24:27]
	v_mfma_f32_16x16x32_bf16 v[16:19], v[164:167], v[196:199], v[16:19]
	v_mfma_f32_16x16x32_bf16 v[8:11], v[172:175], v[196:199], v[8:11]
	v_mfma_f32_16x16x32_bf16 v[4:7], v[164:167], v[204:207], v[4:7]
	v_mfma_f32_16x16x32_bf16 v[0:3], v[172:175], v[204:207], v[0:3]
	v_mfma_f32_16x16x32_bf16 v[48:51], v[168:171], v[184:187], v[48:51]
	v_mfma_f32_16x16x32_bf16 v[40:43], v[176:179], v[184:187], v[40:43]
	v_mfma_f32_16x16x32_bf16 v[32:35], v[168:171], v[192:195], v[32:35]
	v_mfma_f32_16x16x32_bf16 v[24:27], v[176:179], v[192:195], v[24:27]
	v_mfma_f32_16x16x32_bf16 v[16:19], v[168:171], v[200:203], v[16:19]
	v_mfma_f32_16x16x32_bf16 v[8:11], v[176:179], v[200:203], v[8:11]
	v_mfma_f32_16x16x32_bf16 v[4:7], v[168:171], v[208:211], v[4:7]
	v_mfma_f32_16x16x32_bf16 v[0:3], v[176:179], v[208:211], v[0:3]
	s_barrier
	s_setprio 0
	s_andn2_b64 vcc, exec, s[48:49]
	s_mov_b64 s[50:51], -1
	s_mov_b64 s[48:49], 0
	s_mov_b64 s[52:53], 0x100
	s_cbranch_vccz .LBB0_585
	s_and_b64 vcc, exec, s[22:23]
	s_cbranch_vccz .LBB0_588
	s_barrier

.LBB0_661:
	s_add_u32 s64, s44, 0x100
	s_addc_u32 s65, s45, 0
	s_mov_b32 s66, -2
	s_waitcnt lgkmcnt(0)
	s_waitcnt vmcnt(0)
	ds_read_b128 v[144:147], v151
	ds_read_b128 v[156:159], v151 offset:1024
	ds_read_b128 v[160:163], v151 offset:2048
	ds_read_b128 v[164:167], v151 offset:3072
	ds_read_b128 v[168:171], v152
	ds_read_b128 v[172:175], v152 offset:1024
	ds_read_b128 v[176:179], v152 offset:2048
	ds_read_b128 v[180:183], v152 offset:3072
	s_add_u32 s44, s42, 0x100
	s_addc_u32 s45, s43, 0
	s_cmp_eq_u32 s66, 40
	s_cselect_b32 s69, s1, s45
	s_cselect_b32 s68, s0, s44
	s_cselect_b32 s47, s41, s65
	s_cselect_b32 s46, s40, s64
	v_lshl_add_u64 v[216:217], s[42:43], 0, v[136:137]
	s_add_i32 m0, s48, 0xc000
	ds_read_b128 v[184:187], v153
	ds_read_b128 v[188:191], v153 offset:1024
	ds_read_b128 v[192:195], v153 offset:2048
	ds_read_b128 v[196:199], v153 offset:3072
	ds_read_b128 v[200:203], v153 offset:4096
	ds_read_b128 v[204:207], v153 offset:5120
	ds_read_b128 v[208:211], v153 offset:6144
	ds_read_b128 v[212:215], v153 offset:7168
	global_load_lds_dwordx4 v[216:217], off
	s_add_i32 m0, s48, 0xe000
	v_lshl_add_u64 v[216:217], s[42:43], 0, v[138:139]
	global_load_lds_dwordx4 v[216:217], off
	s_waitcnt vmcnt(8) lgkmcnt(0)
	s_setprio 1
	s_barrier
	v_mfma_f32_16x16x32_bf16 v[124:127], v[144:147], v[184:187], 0
	v_mfma_f32_16x16x32_bf16 v[120:123], v[160:163], v[184:187], 0
	v_mfma_f32_16x16x32_bf16 v[108:111], v[144:147], v[192:195], 0
	v_mfma_f32_16x16x32_bf16 v[104:107], v[160:163], v[192:195], 0
	v_mfma_f32_16x16x32_bf16 v[92:95], v[144:147], v[200:203], 0
	v_mfma_f32_16x16x32_bf16 v[88:91], v[160:163], v[200:203], 0
	v_mfma_f32_16x16x32_bf16 v[76:79], v[144:147], v[208:211], 0
	v_mfma_f32_16x16x32_bf16 v[72:75], v[160:163], v[208:211], 0
	v_mfma_f32_16x16x32_bf16 v[124:127], v[156:159], v[188:191], v[124:127]
	v_mfma_f32_16x16x32_bf16 v[120:123], v[164:167], v[188:191], v[120:123]
	v_mfma_f32_16x16x32_bf16 v[108:111], v[156:159], v[196:199], v[108:111]
	v_mfma_f32_16x16x32_bf16 v[104:107], v[164:167], v[196:199], v[104:107]
	v_mfma_f32_16x16x32_bf16 v[92:95], v[156:159], v[204:207], v[92:95]
	v_mfma_f32_16x16x32_bf16 v[88:91], v[164:167], v[204:207], v[88:91]
	v_mfma_f32_16x16x32_bf16 v[76:79], v[156:159], v[212:215], v[76:79]
	v_mfma_f32_16x16x32_bf16 v[72:75], v[164:167], v[212:215], v[72:75]
	v_mfma_f32_16x16x32_bf16 v[116:119], v[168:171], v[184:187], 0
	v_mfma_f32_16x16x32_bf16 v[112:115], v[176:179], v[184:187], 0
	v_mfma_f32_16x16x32_bf16 v[100:103], v[168:171], v[192:195], 0
	v_mfma_f32_16x16x32_bf16 v[96:99], v[176:179], v[192:195], 0
	v_mfma_f32_16x16x32_bf16 v[84:87], v[168:171], v[200:203], 0
	v_mfma_f32_16x16x32_bf16 v[80:83], v[176:179], v[200:203], 0
	v_mfma_f32_16x16x32_bf16 v[68:71], v[168:171], v[208:211], 0
	v_mfma_f32_16x16x32_bf16 v[64:67], v[176:179], v[208:211], 0
	v_mfma_f32_16x16x32_bf16 v[116:119], v[172:175], v[188:191], v[116:119]
	v_mfma_f32_16x16x32_bf16 v[112:115], v[180:183], v[188:191], v[112:115]
	v_mfma_f32_16x16x32_bf16 v[100:103], v[172:175], v[196:199], v[100:103]
	v_mfma_f32_16x16x32_bf16 v[96:99], v[180:183], v[196:199], v[96:99]
	v_mfma_f32_16x16x32_bf16 v[84:87], v[172:175], v[204:207], v[84:87]
	v_mfma_f32_16x16x32_bf16 v[80:83], v[180:183], v[204:207], v[80:83]
	v_mfma_f32_16x16x32_bf16 v[68:71], v[172:175], v[212:215], v[68:71]
	v_mfma_f32_16x16x32_bf16 v[64:67], v[180:183], v[212:215], v[64:67]
	s_barrier
	s_setprio 0
	s_add_i32 s42, s59, s35
	v_lshl_add_u64 v[216:217], s[46:47], 0, v[130:131]
	s_mov_b32 m0, s42
	ds_read_b128 v[184:187], v153 offset:16384
	ds_read_b128 v[188:191], v153 offset:17408
	ds_read_b128 v[192:195], v153 offset:18432
	ds_read_b128 v[196:199], v153 offset:19456
	ds_read_b128 v[200:203], v153 offset:20480
	ds_read_b128 v[204:207], v153 offset:21504
	ds_read_b128 v[208:211], v153 offset:22528
	ds_read_b128 v[212:215], v153 offset:23552
	global_load_lds_dwordx4 v[216:217], off
	s_add_i32 m0, s42, 0x2000
	s_add_u32 s42, s46, 0xb0000
	v_lshl_add_u64 v[220:221], s[46:47], 0, v[134:135]
	s_addc_u32 s43, s47, 0
	s_add_i32 s67, s60, s35
	global_load_lds_dwordx4 v[220:221], off
	v_lshl_add_u64 v[224:225], s[42:43], 0, v[130:131]
	s_mov_b32 m0, s67
	v_lshl_add_u64 v[226:227], s[68:69], 0, v[132:133]
	global_load_lds_dwordx4 v[224:225], off
	v_lshl_add_u64 v[224:225], s[42:43], 0, v[134:135]
	s_add_i32 m0, s67, 0x2000
	v_lshl_add_u64 v[228:229], v[226:227], 0, s[14:15]
	global_load_lds_dwordx4 v[224:225], off
	s_mov_b32 m0, s48
	v_lshl_add_u64 v[224:225], s[68:69], 0, v[128:129]
	global_load_lds_dwordx4 v[224:225], off
	s_mov_b32 m0, s49
	s_nop 0
	global_load_lds_dwordx4 v[228:229], off
	s_waitcnt vmcnt(8) lgkmcnt(0)
	s_setprio 1
	s_barrier
	v_mfma_f32_16x16x32_bf16 v[60:63], v[144:147], v[184:187], 0
	v_mfma_f32_16x16x32_bf16 v[56:59], v[160:163], v[184:187], 0
	v_mfma_f32_16x16x32_bf16 v[44:47], v[144:147], v[192:195], 0
	v_mfma_f32_16x16x32_bf16 v[40:43], v[160:163], v[192:195], 0
	v_mfma_f32_16x16x32_bf16 v[28:31], v[144:147], v[200:203], 0
	v_mfma_f32_16x16x32_bf16 v[24:27], v[160:163], v[200:203], 0
	v_mfma_f32_16x16x32_bf16 v[12:15], v[144:147], v[208:211], 0
	v_mfma_f32_16x16x32_bf16 v[8:11], v[160:163], v[208:211], 0
	v_mfma_f32_16x16x32_bf16 v[60:63], v[156:159], v[188:191], v[60:63]
	v_mfma_f32_16x16x32_bf16 v[56:59], v[164:167], v[188:191], v[56:59]
	v_mfma_f32_16x16x32_bf16 v[44:47], v[156:159], v[196:199], v[44:47]
	v_mfma_f32_16x16x32_bf16 v[40:43], v[164:167], v[196:199], v[40:43]
	v_mfma_f32_16x16x32_bf16 v[28:31], v[156:159], v[204:207], v[28:31]
	v_mfma_f32_16x16x32_bf16 v[24:27], v[164:167], v[204:207], v[24:27]
	v_mfma_f32_16x16x32_bf16 v[12:15], v[156:159], v[212:215], v[12:15]
	v_mfma_f32_16x16x32_bf16 v[8:11], v[164:167], v[212:215], v[8:11]
	v_mfma_f32_16x16x32_bf16 v[52:55], v[168:171], v[184:187], 0
	v_mfma_f32_16x16x32_bf16 v[48:51], v[176:179], v[184:187], 0
	v_mfma_f32_16x16x32_bf16 v[36:39], v[168:171], v[192:195], 0
	v_mfma_f32_16x16x32_bf16 v[32:35], v[176:179], v[192:195], 0
	v_mfma_f32_16x16x32_bf16 v[20:23], v[168:171], v[200:203], 0
	v_mfma_f32_16x16x32_bf16 v[16:19], v[176:179], v[200:203], 0
	v_mfma_f32_16x16x32_bf16 v[4:7], v[168:171], v[208:211], 0
	v_mfma_f32_16x16x32_bf16 v[0:3], v[176:179], v[208:211], 0
	v_mfma_f32_16x16x32_bf16 v[52:55], v[172:175], v[188:191], v[52:55]
	v_mfma_f32_16x16x32_bf16 v[48:51], v[180:183], v[188:191], v[48:51]
	v_mfma_f32_16x16x32_bf16 v[36:39], v[172:175], v[196:199], v[36:39]
	v_mfma_f32_16x16x32_bf16 v[32:35], v[180:183], v[196:199], v[32:35]
	v_mfma_f32_16x16x32_bf16 v[20:23], v[172:175], v[204:207], v[20:23]
	v_mfma_f32_16x16x32_bf16 v[16:19], v[180:183], v[204:207], v[16:19]
	v_mfma_f32_16x16x32_bf16 v[4:7], v[172:175], v[212:215], v[4:7]
	v_mfma_f32_16x16x32_bf16 v[0:3], v[180:183], v[212:215], v[0:3]
	s_barrier
	s_setprio 0
	s_add_i32 s42, 0, 0x18000
	v_add_u32_e32 v155, s42, v149
	s_add_i32 s67, 0, 0x1c000
	ds_read_b128 v[144:147], v155
	ds_read_b128 v[156:159], v155 offset:1024
	ds_read_b128 v[160:163], v155 offset:2048
	ds_read_b128 v[164:167], v155 offset:3072
	v_add_u32_e32 v155, s67, v149
	ds_read_b128 v[168:171], v155
	ds_read_b128 v[172:175], v155 offset:1024
	ds_read_b128 v[176:179], v155 offset:2048
	ds_read_b128 v[180:183], v155 offset:3072
	s_mov_b32 m0, s50
	v_lshl_add_u64 v[228:229], v[224:225], 0, s[12:13]
	ds_read_b128 v[184:187], v153 offset:32768
	ds_read_b128 v[188:191], v153 offset:33792
	ds_read_b128 v[192:195], v153 offset:34816
	ds_read_b128 v[196:199], v153 offset:35840
	ds_read_b128 v[200:203], v153 offset:36864
	ds_read_b128 v[204:207], v153 offset:37888
	ds_read_b128 v[208:211], v153 offset:38912
	ds_read_b128 v[212:215], v153 offset:39936
	global_load_lds_dwordx4 v[228:229], off
	s_mov_b32 m0, s51
	v_lshl_add_u64 v[228:229], v[226:227], 0, s[16:17]
	global_load_lds_dwordx4 v[228:229], off
	s_waitcnt vmcnt(8) lgkmcnt(0)
	s_setprio 1
	s_barrier
	v_mfma_f32_16x16x32_bf16 v[124:127], v[144:147], v[184:187], v[124:127]
	v_mfma_f32_16x16x32_bf16 v[120:123], v[160:163], v[184:187], v[120:123]
	v_mfma_f32_16x16x32_bf16 v[108:111], v[144:147], v[192:195], v[108:111]
	v_mfma_f32_16x16x32_bf16 v[104:107], v[160:163], v[192:195], v[104:107]
	v_mfma_f32_16x16x32_bf16 v[92:95], v[144:147], v[200:203], v[92:95]
	v_mfma_f32_16x16x32_bf16 v[88:91], v[160:163], v[200:203], v[88:91]
	v_mfma_f32_16x16x32_bf16 v[76:79], v[144:147], v[208:211], v[76:79]
	v_mfma_f32_16x16x32_bf16 v[72:75], v[160:163], v[208:211], v[72:75]
	v_mfma_f32_16x16x32_bf16 v[124:127], v[156:159], v[188:191], v[124:127]
	v_mfma_f32_16x16x32_bf16 v[120:123], v[164:167], v[188:191], v[120:123]
	v_mfma_f32_16x16x32_bf16 v[108:111], v[156:159], v[196:199], v[108:111]
	v_mfma_f32_16x16x32_bf16 v[104:107], v[164:167], v[196:199], v[104:107]
	v_mfma_f32_16x16x32_bf16 v[92:95], v[156:159], v[204:207], v[92:95]
	v_mfma_f32_16x16x32_bf16 v[88:91], v[164:167], v[204:207], v[88:91]
	v_mfma_f32_16x16x32_bf16 v[76:79], v[156:159], v[212:215], v[76:79]
	v_mfma_f32_16x16x32_bf16 v[72:75], v[164:167], v[212:215], v[72:75]
	v_mfma_f32_16x16x32_bf16 v[116:119], v[168:171], v[184:187], v[116:119]
	v_mfma_f32_16x16x32_bf16 v[112:115], v[176:179], v[184:187], v[112:115]
	v_mfma_f32_16x16x32_bf16 v[100:103], v[168:171], v[192:195], v[100:103]
	v_mfma_f32_16x16x32_bf16 v[96:99], v[176:179], v[192:195], v[96:99]
	v_mfma_f32_16x16x32_bf16 v[84:87], v[168:171], v[200:203], v[84:87]
	v_mfma_f32_16x16x32_bf16 v[80:83], v[176:179], v[200:203], v[80:83]
	v_mfma_f32_16x16x32_bf16 v[68:71], v[168:171], v[208:211], v[68:71]
	v_mfma_f32_16x16x32_bf16 v[64:67], v[176:179], v[208:211], v[64:67]
	v_mfma_f32_16x16x32_bf16 v[116:119], v[172:175], v[188:191], v[116:119]
	v_mfma_f32_16x16x32_bf16 v[112:115], v[180:183], v[188:191], v[112:115]
	v_mfma_f32_16x16x32_bf16 v[100:103], v[172:175], v[196:199], v[100:103]
	v_mfma_f32_16x16x32_bf16 v[96:99], v[180:183], v[196:199], v[96:99]
	v_mfma_f32_16x16x32_bf16 v[84:87], v[172:175], v[204:207], v[84:87]
	v_mfma_f32_16x16x32_bf16 v[80:83], v[180:183], v[204:207], v[80:83]
	v_mfma_f32_16x16x32_bf16 v[68:71], v[172:175], v[212:215], v[68:71]
	v_mfma_f32_16x16x32_bf16 v[64:67], v[180:183], v[212:215], v[64:67]
	s_barrier
	s_setprio 0
	s_add_i32 s42, s42, s35
	v_lshl_add_u64 v[216:217], v[216:217], 0, s[24:25]
	s_mov_b32 m0, s42
	ds_read_b128 v[184:187], v153 offset:49152
	ds_read_b128 v[188:191], v153 offset:50176
	ds_read_b128 v[192:195], v153 offset:51200
	ds_read_b128 v[196:199], v153 offset:52224
	ds_read_b128 v[200:203], v153 offset:53248
	ds_read_b128 v[204:207], v153 offset:54272
	ds_read_b128 v[208:211], v153 offset:55296
	ds_read_b128 v[212:215], v153 offset:56320
	global_load_lds_dwordx4 v[216:217], off
	s_add_i32 m0, s42, 0x2000
	s_add_u32 s42, s46, 0xb0080
	v_lshl_add_u64 v[216:217], v[220:221], 0, s[24:25]
	s_addc_u32 s43, s47, 0
	s_add_i32 s46, s67, s35
	global_load_lds_dwordx4 v[216:217], off
	s_mov_b32 m0, s46
	v_lshl_add_u64 v[216:217], s[42:43], 0, v[130:131]
	global_load_lds_dwordx4 v[216:217], off
	s_add_i32 m0, s46, 0x2000
	v_lshl_add_u64 v[216:217], s[42:43], 0, v[134:135]
	global_load_lds_dwordx4 v[216:217], off
	s_mov_b32 m0, s53
	v_lshl_add_u64 v[216:217], v[224:225], 0, s[24:25]
	global_load_lds_dwordx4 v[216:217], off
	s_mov_b32 m0, s54
	v_lshl_add_u64 v[216:217], v[226:227], 0, s[36:37]
	global_load_lds_dwordx4 v[216:217], off
	s_waitcnt vmcnt(8) lgkmcnt(0)
	s_setprio 1
	s_barrier
	v_mfma_f32_16x16x32_bf16 v[60:63], v[144:147], v[184:187], v[60:63]
	v_mfma_f32_16x16x32_bf16 v[56:59], v[160:163], v[184:187], v[56:59]
	v_mfma_f32_16x16x32_bf16 v[44:47], v[144:147], v[192:195], v[44:47]
	v_mfma_f32_16x16x32_bf16 v[40:43], v[160:163], v[192:195], v[40:43]
	v_mfma_f32_16x16x32_bf16 v[28:31], v[144:147], v[200:203], v[28:31]
	v_mfma_f32_16x16x32_bf16 v[24:27], v[160:163], v[200:203], v[24:27]
	v_mfma_f32_16x16x32_bf16 v[12:15], v[144:147], v[208:211], v[12:15]
	v_mfma_f32_16x16x32_bf16 v[8:11], v[160:163], v[208:211], v[8:11]
	v_mfma_f32_16x16x32_bf16 v[60:63], v[156:159], v[188:191], v[60:63]
	v_mfma_f32_16x16x32_bf16 v[56:59], v[164:167], v[188:191], v[56:59]
	v_mfma_f32_16x16x32_bf16 v[44:47], v[156:159], v[196:199], v[44:47]
	v_mfma_f32_16x16x32_bf16 v[40:43], v[164:167], v[196:199], v[40:43]
	v_mfma_f32_16x16x32_bf16 v[28:31], v[156:159], v[204:207], v[28:31]
	v_mfma_f32_16x16x32_bf16 v[24:27], v[164:167], v[204:207], v[24:27]
	v_mfma_f32_16x16x32_bf16 v[12:15], v[156:159], v[212:215], v[12:15]
	v_mfma_f32_16x16x32_bf16 v[8:11], v[164:167], v[212:215], v[8:11]
	v_mfma_f32_16x16x32_bf16 v[52:55], v[168:171], v[184:187], v[52:55]
	v_mfma_f32_16x16x32_bf16 v[48:51], v[176:179], v[184:187], v[48:51]
	v_mfma_f32_16x16x32_bf16 v[36:39], v[168:171], v[192:195], v[36:39]
	v_mfma_f32_16x16x32_bf16 v[32:35], v[176:179], v[192:195], v[32:35]
	v_mfma_f32_16x16x32_bf16 v[20:23], v[168:171], v[200:203], v[20:23]
	v_mfma_f32_16x16x32_bf16 v[16:19], v[176:179], v[200:203], v[16:19]
	v_mfma_f32_16x16x32_bf16 v[4:7], v[168:171], v[208:211], v[4:7]
	v_mfma_f32_16x16x32_bf16 v[0:3], v[176:179], v[208:211], v[0:3]
	v_mfma_f32_16x16x32_bf16 v[52:55], v[172:175], v[188:191], v[52:55]
	v_mfma_f32_16x16x32_bf16 v[48:51], v[180:183], v[188:191], v[48:51]
	v_mfma_f32_16x16x32_bf16 v[36:39], v[172:175], v[196:199], v[36:39]
	v_mfma_f32_16x16x32_bf16 v[32:35], v[180:183], v[196:199], v[32:35]
	v_mfma_f32_16x16x32_bf16 v[20:23], v[172:175], v[204:207], v[20:23]
	v_mfma_f32_16x16x32_bf16 v[16:19], v[180:183], v[204:207], v[16:19]
	v_mfma_f32_16x16x32_bf16 v[4:7], v[172:175], v[212:215], v[4:7]
	v_mfma_f32_16x16x32_bf16 v[0:3], v[180:183], v[212:215], v[0:3]
	s_barrier
	s_setprio 0
	s_add_i32 s66, s66, 2
	s_add_u32 s64, s64, 0x100
	s_addc_u32 s65, s65, 0
	s_cmp_gt_u32 s66, 41
	s_mov_b64 s[42:43], s[44:45]
.LBB0_662:
	ds_read_b128 v[144:147], v151
	ds_read_b128 v[156:159], v151 offset:1024
	ds_read_b128 v[160:163], v151 offset:2048
	ds_read_b128 v[164:167], v151 offset:3072
	ds_read_b128 v[168:171], v152
	ds_read_b128 v[172:175], v152 offset:1024
	ds_read_b128 v[176:179], v152 offset:2048
	ds_read_b128 v[180:183], v152 offset:3072
	s_add_u32 s44, s42, 0x100
	s_addc_u32 s45, s43, 0
	s_cmp_eq_u32 s66, 40
	s_cselect_b32 s69, s1, s45
	s_cselect_b32 s68, s0, s44
	s_cselect_b32 s47, s41, s65
	s_cselect_b32 s46, s40, s64
	v_lshl_add_u64 v[216:217], s[42:43], 0, v[136:137]
	s_add_i32 m0, s48, 0xc000
	ds_read_b128 v[184:187], v153
	ds_read_b128 v[188:191], v153 offset:1024
	ds_read_b128 v[192:195], v153 offset:2048
	ds_read_b128 v[196:199], v153 offset:3072
	ds_read_b128 v[200:203], v153 offset:4096
	ds_read_b128 v[204:207], v153 offset:5120
	ds_read_b128 v[208:211], v153 offset:6144
	ds_read_b128 v[212:215], v153 offset:7168
	global_load_lds_dwordx4 v[216:217], off
	s_add_i32 m0, s48, 0xe000
	v_lshl_add_u64 v[216:217], s[42:43], 0, v[138:139]
	global_load_lds_dwordx4 v[216:217], off
	s_waitcnt vmcnt(8) lgkmcnt(0)
	s_setprio 1
	s_barrier
	v_mfma_f32_16x16x32_bf16 v[124:127], v[144:147], v[184:187], v[124:127]
	v_mfma_f32_16x16x32_bf16 v[120:123], v[160:163], v[184:187], v[120:123]
	v_mfma_f32_16x16x32_bf16 v[108:111], v[144:147], v[192:195], v[108:111]
	v_mfma_f32_16x16x32_bf16 v[104:107], v[160:163], v[192:195], v[104:107]
	v_mfma_f32_16x16x32_bf16 v[92:95], v[144:147], v[200:203], v[92:95]
	v_mfma_f32_16x16x32_bf16 v[88:91], v[160:163], v[200:203], v[88:91]
	v_mfma_f32_16x16x32_bf16 v[76:79], v[144:147], v[208:211], v[76:79]
	v_mfma_f32_16x16x32_bf16 v[72:75], v[160:163], v[208:211], v[72:75]
	v_mfma_f32_16x16x32_bf16 v[124:127], v[156:159], v[188:191], v[124:127]
	v_mfma_f32_16x16x32_bf16 v[120:123], v[164:167], v[188:191], v[120:123]
	v_mfma_f32_16x16x32_bf16 v[108:111], v[156:159], v[196:199], v[108:111]
	v_mfma_f32_16x16x32_bf16 v[104:107], v[164:167], v[196:199], v[104:107]
	v_mfma_f32_16x16x32_bf16 v[92:95], v[156:159], v[204:207], v[92:95]
	v_mfma_f32_16x16x32_bf16 v[88:91], v[164:167], v[204:207], v[88:91]
	v_mfma_f32_16x16x32_bf16 v[76:79], v[156:159], v[212:215], v[76:79]
	v_mfma_f32_16x16x32_bf16 v[72:75], v[164:167], v[212:215], v[72:75]
	v_mfma_f32_16x16x32_bf16 v[116:119], v[168:171], v[184:187], v[116:119]
	v_mfma_f32_16x16x32_bf16 v[112:115], v[176:179], v[184:187], v[112:115]
	v_mfma_f32_16x16x32_bf16 v[100:103], v[168:171], v[192:195], v[100:103]
	v_mfma_f32_16x16x32_bf16 v[96:99], v[176:179], v[192:195], v[96:99]
	v_mfma_f32_16x16x32_bf16 v[84:87], v[168:171], v[200:203], v[84:87]
	v_mfma_f32_16x16x32_bf16 v[80:83], v[176:179], v[200:203], v[80:83]
	v_mfma_f32_16x16x32_bf16 v[68:71], v[168:171], v[208:211], v[68:71]
	v_mfma_f32_16x16x32_bf16 v[64:67], v[176:179], v[208:211], v[64:67]
	v_mfma_f32_16x16x32_bf16 v[116:119], v[172:175], v[188:191], v[116:119]
	v_mfma_f32_16x16x32_bf16 v[112:115], v[180:183], v[188:191], v[112:115]
	v_mfma_f32_16x16x32_bf16 v[100:103], v[172:175], v[196:199], v[100:103]
	v_mfma_f32_16x16x32_bf16 v[96:99], v[180:183], v[196:199], v[96:99]
	v_mfma_f32_16x16x32_bf16 v[84:87], v[172:175], v[204:207], v[84:87]
	v_mfma_f32_16x16x32_bf16 v[80:83], v[180:183], v[204:207], v[80:83]
	v_mfma_f32_16x16x32_bf16 v[68:71], v[172:175], v[212:215], v[68:71]
	v_mfma_f32_16x16x32_bf16 v[64:67], v[180:183], v[212:215], v[64:67]
	s_barrier
	s_setprio 0
	s_add_i32 s42, s59, s35
	v_lshl_add_u64 v[216:217], s[46:47], 0, v[130:131]
	s_mov_b32 m0, s42
	ds_read_b128 v[184:187], v153 offset:16384
	ds_read_b128 v[188:191], v153 offset:17408
	ds_read_b128 v[192:195], v153 offset:18432
	ds_read_b128 v[196:199], v153 offset:19456
	ds_read_b128 v[200:203], v153 offset:20480
	ds_read_b128 v[204:207], v153 offset:21504
	ds_read_b128 v[208:211], v153 offset:22528
	ds_read_b128 v[212:215], v153 offset:23552
	global_load_lds_dwordx4 v[216:217], off
	s_add_i32 m0, s42, 0x2000
	s_add_u32 s42, s46, 0xb0000
	v_lshl_add_u64 v[220:221], s[46:47], 0, v[134:135]
	s_addc_u32 s43, s47, 0
	s_add_i32 s67, s60, s35
	global_load_lds_dwordx4 v[220:221], off
	v_lshl_add_u64 v[224:225], s[42:43], 0, v[130:131]
	s_mov_b32 m0, s67
	v_lshl_add_u64 v[226:227], s[68:69], 0, v[132:133]
	global_load_lds_dwordx4 v[224:225], off
	v_lshl_add_u64 v[224:225], s[42:43], 0, v[134:135]
	s_add_i32 m0, s67, 0x2000
	v_lshl_add_u64 v[228:229], v[226:227], 0, s[14:15]
	global_load_lds_dwordx4 v[224:225], off
	s_mov_b32 m0, s48
	v_lshl_add_u64 v[224:225], s[68:69], 0, v[128:129]
	global_load_lds_dwordx4 v[224:225], off
	s_mov_b32 m0, s49
	s_nop 0
	global_load_lds_dwordx4 v[228:229], off
	s_waitcnt vmcnt(8) lgkmcnt(0)
	s_setprio 1
	s_barrier
	v_mfma_f32_16x16x32_bf16 v[60:63], v[144:147], v[184:187], v[60:63]
	v_mfma_f32_16x16x32_bf16 v[56:59], v[160:163], v[184:187], v[56:59]
	v_mfma_f32_16x16x32_bf16 v[44:47], v[144:147], v[192:195], v[44:47]
	v_mfma_f32_16x16x32_bf16 v[40:43], v[160:163], v[192:195], v[40:43]
	v_mfma_f32_16x16x32_bf16 v[28:31], v[144:147], v[200:203], v[28:31]
	v_mfma_f32_16x16x32_bf16 v[24:27], v[160:163], v[200:203], v[24:27]
	v_mfma_f32_16x16x32_bf16 v[12:15], v[144:147], v[208:211], v[12:15]
	v_mfma_f32_16x16x32_bf16 v[8:11], v[160:163], v[208:211], v[8:11]
	v_mfma_f32_16x16x32_bf16 v[60:63], v[156:159], v[188:191], v[60:63]
	v_mfma_f32_16x16x32_bf16 v[56:59], v[164:167], v[188:191], v[56:59]
	v_mfma_f32_16x16x32_bf16 v[44:47], v[156:159], v[196:199], v[44:47]
	v_mfma_f32_16x16x32_bf16 v[40:43], v[164:167], v[196:199], v[40:43]
	v_mfma_f32_16x16x32_bf16 v[28:31], v[156:159], v[204:207], v[28:31]
	v_mfma_f32_16x16x32_bf16 v[24:27], v[164:167], v[204:207], v[24:27]
	v_mfma_f32_16x16x32_bf16 v[12:15], v[156:159], v[212:215], v[12:15]
	v_mfma_f32_16x16x32_bf16 v[8:11], v[164:167], v[212:215], v[8:11]
	v_mfma_f32_16x16x32_bf16 v[52:55], v[168:171], v[184:187], v[52:55]
	v_mfma_f32_16x16x32_bf16 v[48:51], v[176:179], v[184:187], v[48:51]
	v_mfma_f32_16x16x32_bf16 v[36:39], v[168:171], v[192:195], v[36:39]
	v_mfma_f32_16x16x32_bf16 v[32:35], v[176:179], v[192:195], v[32:35]
	v_mfma_f32_16x16x32_bf16 v[20:23], v[168:171], v[200:203], v[20:23]
	v_mfma_f32_16x16x32_bf16 v[16:19], v[176:179], v[200:203], v[16:19]
	v_mfma_f32_16x16x32_bf16 v[4:7], v[168:171], v[208:211], v[4:7]
	v_mfma_f32_16x16x32_bf16 v[0:3], v[176:179], v[208:211], v[0:3]
	v_mfma_f32_16x16x32_bf16 v[52:55], v[172:175], v[188:191], v[52:55]
	v_mfma_f32_16x16x32_bf16 v[48:51], v[180:183], v[188:191], v[48:51]
	v_mfma_f32_16x16x32_bf16 v[36:39], v[172:175], v[196:199], v[36:39]
	v_mfma_f32_16x16x32_bf16 v[32:35], v[180:183], v[196:199], v[32:35]
	v_mfma_f32_16x16x32_bf16 v[20:23], v[172:175], v[204:207], v[20:23]
	v_mfma_f32_16x16x32_bf16 v[16:19], v[180:183], v[204:207], v[16:19]
	v_mfma_f32_16x16x32_bf16 v[4:7], v[172:175], v[212:215], v[4:7]
	v_mfma_f32_16x16x32_bf16 v[0:3], v[180:183], v[212:215], v[0:3]
	s_barrier
	s_setprio 0
	s_add_i32 s42, 0, 0x18000
	v_add_u32_e32 v155, s42, v149
	s_add_i32 s67, 0, 0x1c000
	ds_read_b128 v[144:147], v155
	ds_read_b128 v[156:159], v155 offset:1024
	ds_read_b128 v[160:163], v155 offset:2048
	ds_read_b128 v[164:167], v155 offset:3072
	v_add_u32_e32 v155, s67, v149
	ds_read_b128 v[168:171], v155
	ds_read_b128 v[172:175], v155 offset:1024
	ds_read_b128 v[176:179], v155 offset:2048
	ds_read_b128 v[180:183], v155 offset:3072
	s_mov_b32 m0, s50
	v_lshl_add_u64 v[228:229], v[224:225], 0, s[12:13]
	ds_read_b128 v[184:187], v153 offset:32768
	ds_read_b128 v[188:191], v153 offset:33792
	ds_read_b128 v[192:195], v153 offset:34816
	ds_read_b128 v[196:199], v153 offset:35840
	ds_read_b128 v[200:203], v153 offset:36864
	ds_read_b128 v[204:207], v153 offset:37888
	ds_read_b128 v[208:211], v153 offset:38912
	ds_read_b128 v[212:215], v153 offset:39936
	global_load_lds_dwordx4 v[228:229], off
	s_mov_b32 m0, s51
	v_lshl_add_u64 v[228:229], v[226:227], 0, s[16:17]
	global_load_lds_dwordx4 v[228:229], off
	s_waitcnt vmcnt(8) lgkmcnt(0)
	s_setprio 1
	s_barrier
	v_mfma_f32_16x16x32_bf16 v[124:127], v[144:147], v[184:187], v[124:127]
	v_mfma_f32_16x16x32_bf16 v[120:123], v[160:163], v[184:187], v[120:123]
	v_mfma_f32_16x16x32_bf16 v[108:111], v[144:147], v[192:195], v[108:111]
	v_mfma_f32_16x16x32_bf16 v[104:107], v[160:163], v[192:195], v[104:107]
	v_mfma_f32_16x16x32_bf16 v[92:95], v[144:147], v[200:203], v[92:95]
	v_mfma_f32_16x16x32_bf16 v[88:91], v[160:163], v[200:203], v[88:91]
	v_mfma_f32_16x16x32_bf16 v[76:79], v[144:147], v[208:211], v[76:79]
	v_mfma_f32_16x16x32_bf16 v[72:75], v[160:163], v[208:211], v[72:75]
	v_mfma_f32_16x16x32_bf16 v[124:127], v[156:159], v[188:191], v[124:127]
	v_mfma_f32_16x16x32_bf16 v[120:123], v[164:167], v[188:191], v[120:123]
	v_mfma_f32_16x16x32_bf16 v[108:111], v[156:159], v[196:199], v[108:111]
	v_mfma_f32_16x16x32_bf16 v[104:107], v[164:167], v[196:199], v[104:107]
	v_mfma_f32_16x16x32_bf16 v[92:95], v[156:159], v[204:207], v[92:95]
	v_mfma_f32_16x16x32_bf16 v[88:91], v[164:167], v[204:207], v[88:91]
	v_mfma_f32_16x16x32_bf16 v[76:79], v[156:159], v[212:215], v[76:79]
	v_mfma_f32_16x16x32_bf16 v[72:75], v[164:167], v[212:215], v[72:75]
	v_mfma_f32_16x16x32_bf16 v[116:119], v[168:171], v[184:187], v[116:119]
	v_mfma_f32_16x16x32_bf16 v[112:115], v[176:179], v[184:187], v[112:115]
	v_mfma_f32_16x16x32_bf16 v[100:103], v[168:171], v[192:195], v[100:103]
	v_mfma_f32_16x16x32_bf16 v[96:99], v[176:179], v[192:195], v[96:99]
	v_mfma_f32_16x16x32_bf16 v[84:87], v[168:171], v[200:203], v[84:87]
	v_mfma_f32_16x16x32_bf16 v[80:83], v[176:179], v[200:203], v[80:83]
	v_mfma_f32_16x16x32_bf16 v[68:71], v[168:171], v[208:211], v[68:71]
	v_mfma_f32_16x16x32_bf16 v[64:67], v[176:179], v[208:211], v[64:67]
	v_mfma_f32_16x16x32_bf16 v[116:119], v[172:175], v[188:191], v[116:119]
	v_mfma_f32_16x16x32_bf16 v[112:115], v[180:183], v[188:191], v[112:115]
	v_mfma_f32_16x16x32_bf16 v[100:103], v[172:175], v[196:199], v[100:103]
	v_mfma_f32_16x16x32_bf16 v[96:99], v[180:183], v[196:199], v[96:99]
	v_mfma_f32_16x16x32_bf16 v[84:87], v[172:175], v[204:207], v[84:87]
	v_mfma_f32_16x16x32_bf16 v[80:83], v[180:183], v[204:207], v[80:83]
	v_mfma_f32_16x16x32_bf16 v[68:71], v[172:175], v[212:215], v[68:71]
	v_mfma_f32_16x16x32_bf16 v[64:67], v[180:183], v[212:215], v[64:67]
	s_barrier
	s_setprio 0
	s_add_i32 s42, s42, s35
	v_lshl_add_u64 v[216:217], v[216:217], 0, s[24:25]
	s_mov_b32 m0, s42
	ds_read_b128 v[184:187], v153 offset:49152
	ds_read_b128 v[188:191], v153 offset:50176
	ds_read_b128 v[192:195], v153 offset:51200
	ds_read_b128 v[196:199], v153 offset:52224
	ds_read_b128 v[200:203], v153 offset:53248
	ds_read_b128 v[204:207], v153 offset:54272
	ds_read_b128 v[208:211], v153 offset:55296
	ds_read_b128 v[212:215], v153 offset:56320
	global_load_lds_dwordx4 v[216:217], off
	s_add_i32 m0, s42, 0x2000
	s_add_u32 s42, s46, 0xb0080
	v_lshl_add_u64 v[216:217], v[220:221], 0, s[24:25]
	s_addc_u32 s43, s47, 0
	s_add_i32 s46, s67, s35
	global_load_lds_dwordx4 v[216:217], off
	s_mov_b32 m0, s46
	v_lshl_add_u64 v[216:217], s[42:43], 0, v[130:131]
	global_load_lds_dwordx4 v[216:217], off
	s_add_i32 m0, s46, 0x2000
	v_lshl_add_u64 v[216:217], s[42:43], 0, v[134:135]
	global_load_lds_dwordx4 v[216:217], off
	s_mov_b32 m0, s53
	v_lshl_add_u64 v[216:217], v[224:225], 0, s[24:25]
	global_load_lds_dwordx4 v[216:217], off
	s_mov_b32 m0, s54
	v_lshl_add_u64 v[216:217], v[226:227], 0, s[36:37]
	global_load_lds_dwordx4 v[216:217], off
	s_waitcnt vmcnt(8) lgkmcnt(0)
	s_setprio 1
	s_barrier
	v_mfma_f32_16x16x32_bf16 v[60:63], v[144:147], v[184:187], v[60:63]
	v_mfma_f32_16x16x32_bf16 v[56:59], v[160:163], v[184:187], v[56:59]
	v_mfma_f32_16x16x32_bf16 v[44:47], v[144:147], v[192:195], v[44:47]
	v_mfma_f32_16x16x32_bf16 v[40:43], v[160:163], v[192:195], v[40:43]
	v_mfma_f32_16x16x32_bf16 v[28:31], v[144:147], v[200:203], v[28:31]
	v_mfma_f32_16x16x32_bf16 v[24:27], v[160:163], v[200:203], v[24:27]
	v_mfma_f32_16x16x32_bf16 v[12:15], v[144:147], v[208:211], v[12:15]
	v_mfma_f32_16x16x32_bf16 v[8:11], v[160:163], v[208:211], v[8:11]
	v_mfma_f32_16x16x32_bf16 v[60:63], v[156:159], v[188:191], v[60:63]
	v_mfma_f32_16x16x32_bf16 v[56:59], v[164:167], v[188:191], v[56:59]
	v_mfma_f32_16x16x32_bf16 v[44:47], v[156:159], v[196:199], v[44:47]
	v_mfma_f32_16x16x32_bf16 v[40:43], v[164:167], v[196:199], v[40:43]
	v_mfma_f32_16x16x32_bf16 v[28:31], v[156:159], v[204:207], v[28:31]
	v_mfma_f32_16x16x32_bf16 v[24:27], v[164:167], v[204:207], v[24:27]
	v_mfma_f32_16x16x32_bf16 v[12:15], v[156:159], v[212:215], v[12:15]
	v_mfma_f32_16x16x32_bf16 v[8:11], v[164:167], v[212:215], v[8:11]
	v_mfma_f32_16x16x32_bf16 v[52:55], v[168:171], v[184:187], v[52:55]
	v_mfma_f32_16x16x32_bf16 v[48:51], v[176:179], v[184:187], v[48:51]
	v_mfma_f32_16x16x32_bf16 v[36:39], v[168:171], v[192:195], v[36:39]
	v_mfma_f32_16x16x32_bf16 v[32:35], v[176:179], v[192:195], v[32:35]
	v_mfma_f32_16x16x32_bf16 v[20:23], v[168:171], v[200:203], v[20:23]
	v_mfma_f32_16x16x32_bf16 v[16:19], v[176:179], v[200:203], v[16:19]
	v_mfma_f32_16x16x32_bf16 v[4:7], v[168:171], v[208:211], v[4:7]
	v_mfma_f32_16x16x32_bf16 v[0:3], v[176:179], v[208:211], v[0:3]
	v_mfma_f32_16x16x32_bf16 v[52:55], v[172:175], v[188:191], v[52:55]
	v_mfma_f32_16x16x32_bf16 v[48:51], v[180:183], v[188:191], v[48:51]
	v_mfma_f32_16x16x32_bf16 v[36:39], v[172:175], v[196:199], v[36:39]
	v_mfma_f32_16x16x32_bf16 v[32:35], v[180:183], v[196:199], v[32:35]
	v_mfma_f32_16x16x32_bf16 v[20:23], v[172:175], v[204:207], v[20:23]
	v_mfma_f32_16x16x32_bf16 v[16:19], v[180:183], v[204:207], v[16:19]
	v_mfma_f32_16x16x32_bf16 v[4:7], v[172:175], v[212:215], v[4:7]
	v_mfma_f32_16x16x32_bf16 v[0:3], v[180:183], v[212:215], v[0:3]
	s_barrier
	s_setprio 0
	s_add_i32 s66, s66, 2
	s_add_u32 s64, s64, 0x100
	s_addc_u32 s65, s65, 0
	s_cmp_gt_u32 s66, 41
	s_mov_b64 s[42:43], s[44:45]
	s_cbranch_scc0 .LBB0_662
	s_and_b64 vcc, exec, s[38:39]
	s_cbranch_vccz .LBB0_665
	s_barrier

.LBB0_750:
	s_lshl_b32 s38, s65, 8
	s_ashr_i32 s39, s38, 31
	s_lshl_b64 s[38:39], s[38:39], 11
	s_add_u32 s38, s8, s38
	s_addc_u32 s39, s9, s39
	s_and_b64 s[40:41], s[4:5], exec
	s_cselect_b32 s43, s39, s45
	s_cselect_b32 s67, s38, s44
	s_ashr_i32 s37, s36, 31
	s_lshl_b64 s[40:41], s[36:37], 19
	s_add_u32 s40, s3, s40
	s_addc_u32 s41, s33, s41
	s_and_b64 s[48:49], s[4:5], exec
	s_cselect_b32 s37, s41, s47
	s_cselect_b32 s68, s40, s46
	s_add_u32 s69, s46, 0x100
	s_addc_u32 s71, s47, 0
	s_mov_b32 s72, -2
	s_waitcnt vmcnt(0)
	ds_read_b128 v[144:147], v189
	ds_read_b128 v[148:151], v189 offset:1024
	ds_read_b128 v[152:155], v189 offset:2048
	ds_read_b128 v[156:159], v189 offset:3072
	ds_read_b128 v[160:163], v190
	ds_read_b128 v[164:167], v190 offset:1024
	ds_read_b128 v[168:171], v190 offset:2048
	ds_read_b128 v[172:175], v190 offset:3072
	s_add_u32 s46, s44, 0x100
	s_addc_u32 s47, s45, 0
	s_cmp_eq_u32 s72, 12
	s_cselect_b32 s75, s43, s47
	s_cselect_b32 s74, s67, s46
	s_cselect_b32 s49, s37, s71
	s_cselect_b32 s48, s68, s69
	v_lshl_add_u64 v[184:185], s[44:45], 0, v[136:137]
	s_add_i32 m0, s51, 0xc000
	ds_read_b128 v[176:179], v191
	ds_read_b128 v[180:183], v191 offset:1024
	ds_read_b128 v[194:197], v191 offset:2048
	ds_read_b128 v[198:201], v191 offset:3072
	ds_read_b128 v[202:205], v191 offset:4096
	ds_read_b128 v[206:209], v191 offset:5120
	ds_read_b128 v[210:213], v191 offset:6144
	ds_read_b128 v[214:217], v191 offset:7168
	global_load_lds_dwordx4 v[184:185], off
	s_add_i32 m0, s51, 0xe000
	v_lshl_add_u64 v[184:185], s[44:45], 0, v[138:139]
	global_load_lds_dwordx4 v[184:185], off
	s_waitcnt vmcnt(8) lgkmcnt(0)
	s_setprio 1
	s_barrier
	v_mfma_f32_16x16x32_bf16 v[124:127], v[144:147], v[176:179], 0
	v_mfma_f32_16x16x32_bf16 v[120:123], v[152:155], v[176:179], 0
	v_mfma_f32_16x16x32_bf16 v[108:111], v[144:147], v[194:197], 0
	v_mfma_f32_16x16x32_bf16 v[104:107], v[152:155], v[194:197], 0
	v_mfma_f32_16x16x32_bf16 v[92:95], v[144:147], v[202:205], 0
	v_mfma_f32_16x16x32_bf16 v[88:91], v[152:155], v[202:205], 0
	v_mfma_f32_16x16x32_bf16 v[76:79], v[144:147], v[210:213], 0
	v_mfma_f32_16x16x32_bf16 v[72:75], v[152:155], v[210:213], 0
	v_mfma_f32_16x16x32_bf16 v[124:127], v[148:151], v[180:183], v[124:127]
	v_mfma_f32_16x16x32_bf16 v[120:123], v[156:159], v[180:183], v[120:123]
	v_mfma_f32_16x16x32_bf16 v[108:111], v[148:151], v[198:201], v[108:111]
	v_mfma_f32_16x16x32_bf16 v[104:107], v[156:159], v[198:201], v[104:107]
	v_mfma_f32_16x16x32_bf16 v[92:95], v[148:151], v[206:209], v[92:95]
	v_mfma_f32_16x16x32_bf16 v[88:91], v[156:159], v[206:209], v[88:91]
	v_mfma_f32_16x16x32_bf16 v[76:79], v[148:151], v[214:217], v[76:79]
	v_mfma_f32_16x16x32_bf16 v[72:75], v[156:159], v[214:217], v[72:75]
	v_mfma_f32_16x16x32_bf16 v[116:119], v[160:163], v[176:179], 0
	v_mfma_f32_16x16x32_bf16 v[112:115], v[168:171], v[176:179], 0
	v_mfma_f32_16x16x32_bf16 v[100:103], v[160:163], v[194:197], 0
	v_mfma_f32_16x16x32_bf16 v[96:99], v[168:171], v[194:197], 0
	v_mfma_f32_16x16x32_bf16 v[84:87], v[160:163], v[202:205], 0
	v_mfma_f32_16x16x32_bf16 v[80:83], v[168:171], v[202:205], 0
	v_mfma_f32_16x16x32_bf16 v[68:71], v[160:163], v[210:213], 0
	v_mfma_f32_16x16x32_bf16 v[64:67], v[168:171], v[210:213], 0
	v_mfma_f32_16x16x32_bf16 v[116:119], v[164:167], v[180:183], v[116:119]
	v_mfma_f32_16x16x32_bf16 v[112:115], v[172:175], v[180:183], v[112:115]
	v_mfma_f32_16x16x32_bf16 v[100:103], v[164:167], v[198:201], v[100:103]
	v_mfma_f32_16x16x32_bf16 v[96:99], v[172:175], v[198:201], v[96:99]
	v_mfma_f32_16x16x32_bf16 v[84:87], v[164:167], v[206:209], v[84:87]
	v_mfma_f32_16x16x32_bf16 v[80:83], v[172:175], v[206:209], v[80:83]
	v_mfma_f32_16x16x32_bf16 v[68:71], v[164:167], v[214:217], v[68:71]
	v_mfma_f32_16x16x32_bf16 v[64:67], v[172:175], v[214:217], v[64:67]
	s_barrier
	s_setprio 0
	s_add_i32 s44, s63, s50
	v_lshl_add_u64 v[184:185], s[48:49], 0, v[130:131]
	s_mov_b32 m0, s44
	ds_read_b128 v[176:179], v191 offset:16384
	ds_read_b128 v[180:183], v191 offset:17408
	ds_read_b128 v[194:197], v191 offset:18432
	ds_read_b128 v[198:201], v191 offset:19456
	ds_read_b128 v[202:205], v191 offset:20480
	ds_read_b128 v[206:209], v191 offset:21504
	ds_read_b128 v[210:213], v191 offset:22528
	ds_read_b128 v[214:217], v191 offset:23552
	global_load_lds_dwordx4 v[184:185], off
	s_add_i32 m0, s44, 0x2000
	s_add_u32 s44, s48, 0x40000
	v_lshl_add_u64 v[218:219], s[48:49], 0, v[134:135]
	s_addc_u32 s45, s49, 0
	s_add_i32 s70, s64, s50
	global_load_lds_dwordx4 v[218:219], off
	v_lshl_add_u64 v[220:221], s[44:45], 0, v[130:131]
	s_mov_b32 m0, s70
	v_lshl_add_u64 v[222:223], s[74:75], 0, v[132:133]
	global_load_lds_dwordx4 v[220:221], off
	v_lshl_add_u64 v[220:221], s[44:45], 0, v[134:135]
	s_add_i32 m0, s70, 0x2000
	v_lshl_add_u64 v[224:225], v[222:223], 0, s[12:13]
	global_load_lds_dwordx4 v[220:221], off
	s_mov_b32 m0, s51
	v_lshl_add_u64 v[220:221], s[74:75], 0, v[128:129]
	global_load_lds_dwordx4 v[220:221], off
	s_mov_b32 m0, s52
	s_nop 0
	global_load_lds_dwordx4 v[224:225], off
	s_waitcnt vmcnt(8) lgkmcnt(0)
	s_setprio 1
	s_barrier
	v_mfma_f32_16x16x32_bf16 v[60:63], v[144:147], v[176:179], 0
	v_mfma_f32_16x16x32_bf16 v[56:59], v[152:155], v[176:179], 0
	v_mfma_f32_16x16x32_bf16 v[44:47], v[144:147], v[194:197], 0
	v_mfma_f32_16x16x32_bf16 v[40:43], v[152:155], v[194:197], 0
	v_mfma_f32_16x16x32_bf16 v[28:31], v[144:147], v[202:205], 0
	v_mfma_f32_16x16x32_bf16 v[24:27], v[152:155], v[202:205], 0
	v_mfma_f32_16x16x32_bf16 v[12:15], v[144:147], v[210:213], 0
	v_mfma_f32_16x16x32_bf16 v[8:11], v[152:155], v[210:213], 0
	v_mfma_f32_16x16x32_bf16 v[60:63], v[148:151], v[180:183], v[60:63]
	v_mfma_f32_16x16x32_bf16 v[56:59], v[156:159], v[180:183], v[56:59]
	v_mfma_f32_16x16x32_bf16 v[44:47], v[148:151], v[198:201], v[44:47]
	v_mfma_f32_16x16x32_bf16 v[40:43], v[156:159], v[198:201], v[40:43]
	v_mfma_f32_16x16x32_bf16 v[28:31], v[148:151], v[206:209], v[28:31]
	v_mfma_f32_16x16x32_bf16 v[24:27], v[156:159], v[206:209], v[24:27]
	v_mfma_f32_16x16x32_bf16 v[12:15], v[148:151], v[214:217], v[12:15]
	v_mfma_f32_16x16x32_bf16 v[8:11], v[156:159], v[214:217], v[8:11]
	v_mfma_f32_16x16x32_bf16 v[52:55], v[160:163], v[176:179], 0
	v_mfma_f32_16x16x32_bf16 v[48:51], v[168:171], v[176:179], 0
	v_mfma_f32_16x16x32_bf16 v[36:39], v[160:163], v[194:197], 0
	v_mfma_f32_16x16x32_bf16 v[32:35], v[168:171], v[194:197], 0
	v_mfma_f32_16x16x32_bf16 v[20:23], v[160:163], v[202:205], 0
	v_mfma_f32_16x16x32_bf16 v[16:19], v[168:171], v[202:205], 0
	v_mfma_f32_16x16x32_bf16 v[4:7], v[160:163], v[210:213], 0
	v_mfma_f32_16x16x32_bf16 v[0:3], v[168:171], v[210:213], 0
	v_mfma_f32_16x16x32_bf16 v[52:55], v[164:167], v[180:183], v[52:55]
	v_mfma_f32_16x16x32_bf16 v[48:51], v[172:175], v[180:183], v[48:51]
	v_mfma_f32_16x16x32_bf16 v[36:39], v[164:167], v[198:201], v[36:39]
	v_mfma_f32_16x16x32_bf16 v[32:35], v[172:175], v[198:201], v[32:35]
	v_mfma_f32_16x16x32_bf16 v[20:23], v[164:167], v[206:209], v[20:23]
	v_mfma_f32_16x16x32_bf16 v[16:19], v[172:175], v[206:209], v[16:19]
	v_mfma_f32_16x16x32_bf16 v[4:7], v[164:167], v[214:217], v[4:7]
	v_mfma_f32_16x16x32_bf16 v[0:3], v[172:175], v[214:217], v[0:3]
	s_barrier
	s_setprio 0
	s_add_i32 s44, 0, 0x18000
	s_add_i32 s70, 0, 0x1c000
	v_add_u32_e32 v156, s44, v187
	v_add_u32_e32 v172, s70, v187
	ds_read_b128 v[144:147], v156
	ds_read_b128 v[148:151], v156 offset:1024
	ds_read_b128 v[152:155], v156 offset:2048
	ds_read_b128 v[156:159], v156 offset:3072
	ds_read_b128 v[160:163], v172
	ds_read_b128 v[164:167], v172 offset:1024
	ds_read_b128 v[168:171], v172 offset:2048
	ds_read_b128 v[172:175], v172 offset:3072
	s_mov_b32 m0, s53
	v_lshl_add_u64 v[224:225], v[220:221], 0, s[10:11]
	ds_read_b128 v[176:179], v191 offset:32768
	ds_read_b128 v[180:183], v191 offset:33792
	ds_read_b128 v[194:197], v191 offset:34816
	ds_read_b128 v[198:201], v191 offset:35840
	ds_read_b128 v[202:205], v191 offset:36864
	ds_read_b128 v[206:209], v191 offset:37888
	ds_read_b128 v[210:213], v191 offset:38912
	ds_read_b128 v[214:217], v191 offset:39936
	global_load_lds_dwordx4 v[224:225], off
	s_mov_b32 m0, s54
	v_lshl_add_u64 v[224:225], v[222:223], 0, s[14:15]
	global_load_lds_dwordx4 v[224:225], off
	s_waitcnt vmcnt(8) lgkmcnt(0)
	s_setprio 1
	s_barrier
	v_mfma_f32_16x16x32_bf16 v[124:127], v[144:147], v[176:179], v[124:127]
	v_mfma_f32_16x16x32_bf16 v[120:123], v[152:155], v[176:179], v[120:123]
	v_mfma_f32_16x16x32_bf16 v[108:111], v[144:147], v[194:197], v[108:111]
	v_mfma_f32_16x16x32_bf16 v[104:107], v[152:155], v[194:197], v[104:107]
	v_mfma_f32_16x16x32_bf16 v[92:95], v[144:147], v[202:205], v[92:95]
	v_mfma_f32_16x16x32_bf16 v[88:91], v[152:155], v[202:205], v[88:91]
	v_mfma_f32_16x16x32_bf16 v[76:79], v[144:147], v[210:213], v[76:79]
	v_mfma_f32_16x16x32_bf16 v[72:75], v[152:155], v[210:213], v[72:75]
	v_mfma_f32_16x16x32_bf16 v[124:127], v[148:151], v[180:183], v[124:127]
	v_mfma_f32_16x16x32_bf16 v[120:123], v[156:159], v[180:183], v[120:123]
	v_mfma_f32_16x16x32_bf16 v[108:111], v[148:151], v[198:201], v[108:111]
	v_mfma_f32_16x16x32_bf16 v[104:107], v[156:159], v[198:201], v[104:107]
	v_mfma_f32_16x16x32_bf16 v[92:95], v[148:151], v[206:209], v[92:95]
	v_mfma_f32_16x16x32_bf16 v[88:91], v[156:159], v[206:209], v[88:91]
	v_mfma_f32_16x16x32_bf16 v[76:79], v[148:151], v[214:217], v[76:79]
	v_mfma_f32_16x16x32_bf16 v[72:75], v[156:159], v[214:217], v[72:75]
	v_mfma_f32_16x16x32_bf16 v[116:119], v[160:163], v[176:179], v[116:119]
	v_mfma_f32_16x16x32_bf16 v[112:115], v[168:171], v[176:179], v[112:115]
	v_mfma_f32_16x16x32_bf16 v[100:103], v[160:163], v[194:197], v[100:103]
	v_mfma_f32_16x16x32_bf16 v[96:99], v[168:171], v[194:197], v[96:99]
	v_mfma_f32_16x16x32_bf16 v[84:87], v[160:163], v[202:205], v[84:87]
	v_mfma_f32_16x16x32_bf16 v[80:83], v[168:171], v[202:205], v[80:83]
	v_mfma_f32_16x16x32_bf16 v[68:71], v[160:163], v[210:213], v[68:71]
	v_mfma_f32_16x16x32_bf16 v[64:67], v[168:171], v[210:213], v[64:67]
	v_mfma_f32_16x16x32_bf16 v[116:119], v[164:167], v[180:183], v[116:119]
	v_mfma_f32_16x16x32_bf16 v[112:115], v[172:175], v[180:183], v[112:115]
	v_mfma_f32_16x16x32_bf16 v[100:103], v[164:167], v[198:201], v[100:103]
	v_mfma_f32_16x16x32_bf16 v[96:99], v[172:175], v[198:201], v[96:99]
	v_mfma_f32_16x16x32_bf16 v[84:87], v[164:167], v[206:209], v[84:87]
	v_mfma_f32_16x16x32_bf16 v[80:83], v[172:175], v[206:209], v[80:83]
	v_mfma_f32_16x16x32_bf16 v[68:71], v[164:167], v[214:217], v[68:71]
	v_mfma_f32_16x16x32_bf16 v[64:67], v[172:175], v[214:217], v[64:67]
	s_barrier
	s_setprio 0
	s_add_i32 s44, s44, s50
	v_lshl_add_u64 v[184:185], v[184:185], 0, s[24:25]
	s_mov_b32 m0, s44
	ds_read_b128 v[176:179], v191 offset:49152
	ds_read_b128 v[180:183], v191 offset:50176
	ds_read_b128 v[194:197], v191 offset:51200
	ds_read_b128 v[198:201], v191 offset:52224
	ds_read_b128 v[202:205], v191 offset:53248
	ds_read_b128 v[206:209], v191 offset:54272
	ds_read_b128 v[210:213], v191 offset:55296
	ds_read_b128 v[214:217], v191 offset:56320
	global_load_lds_dwordx4 v[184:185], off
	s_add_i32 m0, s44, 0x2000
	s_add_u32 s44, s48, 0x40080
	v_lshl_add_u64 v[184:185], v[218:219], 0, s[24:25]
	s_addc_u32 s45, s49, 0
	s_add_i32 s48, s70, s50
	global_load_lds_dwordx4 v[184:185], off
	s_mov_b32 m0, s48
	v_lshl_add_u64 v[184:185], s[44:45], 0, v[130:131]
	global_load_lds_dwordx4 v[184:185], off
	s_add_i32 m0, s48, 0x2000
	v_lshl_add_u64 v[184:185], s[44:45], 0, v[134:135]
	global_load_lds_dwordx4 v[184:185], off
	s_mov_b32 m0, s58
	v_lshl_add_u64 v[184:185], v[220:221], 0, s[24:25]
	global_load_lds_dwordx4 v[184:185], off
	s_mov_b32 m0, s59
	v_lshl_add_u64 v[184:185], v[222:223], 0, s[30:31]
	global_load_lds_dwordx4 v[184:185], off
	s_waitcnt vmcnt(8) lgkmcnt(0)
	s_setprio 1
	s_barrier
	v_mfma_f32_16x16x32_bf16 v[60:63], v[144:147], v[176:179], v[60:63]
	v_mfma_f32_16x16x32_bf16 v[56:59], v[152:155], v[176:179], v[56:59]
	v_mfma_f32_16x16x32_bf16 v[44:47], v[144:147], v[194:197], v[44:47]
	v_mfma_f32_16x16x32_bf16 v[40:43], v[152:155], v[194:197], v[40:43]
	v_mfma_f32_16x16x32_bf16 v[28:31], v[144:147], v[202:205], v[28:31]
	v_mfma_f32_16x16x32_bf16 v[24:27], v[152:155], v[202:205], v[24:27]
	v_mfma_f32_16x16x32_bf16 v[12:15], v[144:147], v[210:213], v[12:15]
	v_mfma_f32_16x16x32_bf16 v[8:11], v[152:155], v[210:213], v[8:11]
	v_mfma_f32_16x16x32_bf16 v[60:63], v[148:151], v[180:183], v[60:63]
	v_mfma_f32_16x16x32_bf16 v[56:59], v[156:159], v[180:183], v[56:59]
	v_mfma_f32_16x16x32_bf16 v[44:47], v[148:151], v[198:201], v[44:47]
	v_mfma_f32_16x16x32_bf16 v[40:43], v[156:159], v[198:201], v[40:43]
	v_mfma_f32_16x16x32_bf16 v[28:31], v[148:151], v[206:209], v[28:31]
	v_mfma_f32_16x16x32_bf16 v[24:27], v[156:159], v[206:209], v[24:27]
	v_mfma_f32_16x16x32_bf16 v[12:15], v[148:151], v[214:217], v[12:15]
	v_mfma_f32_16x16x32_bf16 v[8:11], v[156:159], v[214:217], v[8:11]
	v_mfma_f32_16x16x32_bf16 v[52:55], v[160:163], v[176:179], v[52:55]
	v_mfma_f32_16x16x32_bf16 v[48:51], v[168:171], v[176:179], v[48:51]
	v_mfma_f32_16x16x32_bf16 v[36:39], v[160:163], v[194:197], v[36:39]
	v_mfma_f32_16x16x32_bf16 v[32:35], v[168:171], v[194:197], v[32:35]
	v_mfma_f32_16x16x32_bf16 v[20:23], v[160:163], v[202:205], v[20:23]
	v_mfma_f32_16x16x32_bf16 v[16:19], v[168:171], v[202:205], v[16:19]
	v_mfma_f32_16x16x32_bf16 v[4:7], v[160:163], v[210:213], v[4:7]
	v_mfma_f32_16x16x32_bf16 v[0:3], v[168:171], v[210:213], v[0:3]
	v_mfma_f32_16x16x32_bf16 v[52:55], v[164:167], v[180:183], v[52:55]
	v_mfma_f32_16x16x32_bf16 v[48:51], v[172:175], v[180:183], v[48:51]
	v_mfma_f32_16x16x32_bf16 v[36:39], v[164:167], v[198:201], v[36:39]
	v_mfma_f32_16x16x32_bf16 v[32:35], v[172:175], v[198:201], v[32:35]
	v_mfma_f32_16x16x32_bf16 v[20:23], v[164:167], v[206:209], v[20:23]
	v_mfma_f32_16x16x32_bf16 v[16:19], v[172:175], v[206:209], v[16:19]
	v_mfma_f32_16x16x32_bf16 v[4:7], v[164:167], v[214:217], v[4:7]
	v_mfma_f32_16x16x32_bf16 v[0:3], v[172:175], v[214:217], v[0:3]
	s_barrier
	s_setprio 0
	s_add_i32 s72, s72, 2
	s_add_u32 s69, s69, 0x100
	s_addc_u32 s71, s71, 0
	s_cmp_gt_u32 s72, 13
	s_mov_b64 s[44:45], s[46:47]
.LBB0_751:
	ds_read_b128 v[144:147], v189
	ds_read_b128 v[148:151], v189 offset:1024
	ds_read_b128 v[152:155], v189 offset:2048
	ds_read_b128 v[156:159], v189 offset:3072
	ds_read_b128 v[160:163], v190
	ds_read_b128 v[164:167], v190 offset:1024
	ds_read_b128 v[168:171], v190 offset:2048
	ds_read_b128 v[172:175], v190 offset:3072
	s_add_u32 s46, s44, 0x100
	s_addc_u32 s47, s45, 0
	s_cmp_eq_u32 s72, 12
	s_cselect_b32 s75, s43, s47
	s_cselect_b32 s74, s67, s46
	s_cselect_b32 s49, s37, s71
	s_cselect_b32 s48, s68, s69
	v_lshl_add_u64 v[184:185], s[44:45], 0, v[136:137]
	s_add_i32 m0, s51, 0xc000
	ds_read_b128 v[176:179], v191
	ds_read_b128 v[180:183], v191 offset:1024
	ds_read_b128 v[194:197], v191 offset:2048
	ds_read_b128 v[198:201], v191 offset:3072
	ds_read_b128 v[202:205], v191 offset:4096
	ds_read_b128 v[206:209], v191 offset:5120
	ds_read_b128 v[210:213], v191 offset:6144
	ds_read_b128 v[214:217], v191 offset:7168
	global_load_lds_dwordx4 v[184:185], off
	s_add_i32 m0, s51, 0xe000
	v_lshl_add_u64 v[184:185], s[44:45], 0, v[138:139]
	global_load_lds_dwordx4 v[184:185], off
	s_waitcnt vmcnt(8) lgkmcnt(0)
	s_setprio 1
	s_barrier
	v_mfma_f32_16x16x32_bf16 v[124:127], v[144:147], v[176:179], v[124:127]
	v_mfma_f32_16x16x32_bf16 v[120:123], v[152:155], v[176:179], v[120:123]
	v_mfma_f32_16x16x32_bf16 v[108:111], v[144:147], v[194:197], v[108:111]
	v_mfma_f32_16x16x32_bf16 v[104:107], v[152:155], v[194:197], v[104:107]
	v_mfma_f32_16x16x32_bf16 v[92:95], v[144:147], v[202:205], v[92:95]
	v_mfma_f32_16x16x32_bf16 v[88:91], v[152:155], v[202:205], v[88:91]
	v_mfma_f32_16x16x32_bf16 v[76:79], v[144:147], v[210:213], v[76:79]
	v_mfma_f32_16x16x32_bf16 v[72:75], v[152:155], v[210:213], v[72:75]
	v_mfma_f32_16x16x32_bf16 v[124:127], v[148:151], v[180:183], v[124:127]
	v_mfma_f32_16x16x32_bf16 v[120:123], v[156:159], v[180:183], v[120:123]
	v_mfma_f32_16x16x32_bf16 v[108:111], v[148:151], v[198:201], v[108:111]
	v_mfma_f32_16x16x32_bf16 v[104:107], v[156:159], v[198:201], v[104:107]
	v_mfma_f32_16x16x32_bf16 v[92:95], v[148:151], v[206:209], v[92:95]
	v_mfma_f32_16x16x32_bf16 v[88:91], v[156:159], v[206:209], v[88:91]
	v_mfma_f32_16x16x32_bf16 v[76:79], v[148:151], v[214:217], v[76:79]
	v_mfma_f32_16x16x32_bf16 v[72:75], v[156:159], v[214:217], v[72:75]
	v_mfma_f32_16x16x32_bf16 v[116:119], v[160:163], v[176:179], v[116:119]
	v_mfma_f32_16x16x32_bf16 v[112:115], v[168:171], v[176:179], v[112:115]
	v_mfma_f32_16x16x32_bf16 v[100:103], v[160:163], v[194:197], v[100:103]
	v_mfma_f32_16x16x32_bf16 v[96:99], v[168:171], v[194:197], v[96:99]
	v_mfma_f32_16x16x32_bf16 v[84:87], v[160:163], v[202:205], v[84:87]
	v_mfma_f32_16x16x32_bf16 v[80:83], v[168:171], v[202:205], v[80:83]
	v_mfma_f32_16x16x32_bf16 v[68:71], v[160:163], v[210:213], v[68:71]
	v_mfma_f32_16x16x32_bf16 v[64:67], v[168:171], v[210:213], v[64:67]
	v_mfma_f32_16x16x32_bf16 v[116:119], v[164:167], v[180:183], v[116:119]
	v_mfma_f32_16x16x32_bf16 v[112:115], v[172:175], v[180:183], v[112:115]
	v_mfma_f32_16x16x32_bf16 v[100:103], v[164:167], v[198:201], v[100:103]
	v_mfma_f32_16x16x32_bf16 v[96:99], v[172:175], v[198:201], v[96:99]
	v_mfma_f32_16x16x32_bf16 v[84:87], v[164:167], v[206:209], v[84:87]
	v_mfma_f32_16x16x32_bf16 v[80:83], v[172:175], v[206:209], v[80:83]
	v_mfma_f32_16x16x32_bf16 v[68:71], v[164:167], v[214:217], v[68:71]
	v_mfma_f32_16x16x32_bf16 v[64:67], v[172:175], v[214:217], v[64:67]
	s_barrier
	s_setprio 0
	s_add_i32 s44, s63, s50
	v_lshl_add_u64 v[184:185], s[48:49], 0, v[130:131]
	s_mov_b32 m0, s44
	ds_read_b128 v[176:179], v191 offset:16384
	ds_read_b128 v[180:183], v191 offset:17408
	ds_read_b128 v[194:197], v191 offset:18432
	ds_read_b128 v[198:201], v191 offset:19456
	ds_read_b128 v[202:205], v191 offset:20480
	ds_read_b128 v[206:209], v191 offset:21504
	ds_read_b128 v[210:213], v191 offset:22528
	ds_read_b128 v[214:217], v191 offset:23552
	global_load_lds_dwordx4 v[184:185], off
	s_add_i32 m0, s44, 0x2000
	s_add_u32 s44, s48, 0x40000
	v_lshl_add_u64 v[218:219], s[48:49], 0, v[134:135]
	s_addc_u32 s45, s49, 0
	s_add_i32 s70, s64, s50
	global_load_lds_dwordx4 v[218:219], off
	v_lshl_add_u64 v[220:221], s[44:45], 0, v[130:131]
	s_mov_b32 m0, s70
	v_lshl_add_u64 v[222:223], s[74:75], 0, v[132:133]
	global_load_lds_dwordx4 v[220:221], off
	v_lshl_add_u64 v[220:221], s[44:45], 0, v[134:135]
	s_add_i32 m0, s70, 0x2000
	v_lshl_add_u64 v[224:225], v[222:223], 0, s[12:13]
	global_load_lds_dwordx4 v[220:221], off
	s_mov_b32 m0, s51
	v_lshl_add_u64 v[220:221], s[74:75], 0, v[128:129]
	global_load_lds_dwordx4 v[220:221], off
	s_mov_b32 m0, s52
	s_nop 0
	global_load_lds_dwordx4 v[224:225], off
	s_waitcnt vmcnt(8) lgkmcnt(0)
	s_setprio 1
	s_barrier
	v_mfma_f32_16x16x32_bf16 v[60:63], v[144:147], v[176:179], v[60:63]
	v_mfma_f32_16x16x32_bf16 v[56:59], v[152:155], v[176:179], v[56:59]
	v_mfma_f32_16x16x32_bf16 v[44:47], v[144:147], v[194:197], v[44:47]
	v_mfma_f32_16x16x32_bf16 v[40:43], v[152:155], v[194:197], v[40:43]
	v_mfma_f32_16x16x32_bf16 v[28:31], v[144:147], v[202:205], v[28:31]
	v_mfma_f32_16x16x32_bf16 v[24:27], v[152:155], v[202:205], v[24:27]
	v_mfma_f32_16x16x32_bf16 v[12:15], v[144:147], v[210:213], v[12:15]
	v_mfma_f32_16x16x32_bf16 v[8:11], v[152:155], v[210:213], v[8:11]
	v_mfma_f32_16x16x32_bf16 v[60:63], v[148:151], v[180:183], v[60:63]
	v_mfma_f32_16x16x32_bf16 v[56:59], v[156:159], v[180:183], v[56:59]
	v_mfma_f32_16x16x32_bf16 v[44:47], v[148:151], v[198:201], v[44:47]
	v_mfma_f32_16x16x32_bf16 v[40:43], v[156:159], v[198:201], v[40:43]
	v_mfma_f32_16x16x32_bf16 v[28:31], v[148:151], v[206:209], v[28:31]
	v_mfma_f32_16x16x32_bf16 v[24:27], v[156:159], v[206:209], v[24:27]
	v_mfma_f32_16x16x32_bf16 v[12:15], v[148:151], v[214:217], v[12:15]
	v_mfma_f32_16x16x32_bf16 v[8:11], v[156:159], v[214:217], v[8:11]
	v_mfma_f32_16x16x32_bf16 v[52:55], v[160:163], v[176:179], v[52:55]
	v_mfma_f32_16x16x32_bf16 v[48:51], v[168:171], v[176:179], v[48:51]
	v_mfma_f32_16x16x32_bf16 v[36:39], v[160:163], v[194:197], v[36:39]
	v_mfma_f32_16x16x32_bf16 v[32:35], v[168:171], v[194:197], v[32:35]
	v_mfma_f32_16x16x32_bf16 v[20:23], v[160:163], v[202:205], v[20:23]
	v_mfma_f32_16x16x32_bf16 v[16:19], v[168:171], v[202:205], v[16:19]
	v_mfma_f32_16x16x32_bf16 v[4:7], v[160:163], v[210:213], v[4:7]
	v_mfma_f32_16x16x32_bf16 v[0:3], v[168:171], v[210:213], v[0:3]
	v_mfma_f32_16x16x32_bf16 v[52:55], v[164:167], v[180:183], v[52:55]
	v_mfma_f32_16x16x32_bf16 v[48:51], v[172:175], v[180:183], v[48:51]
	v_mfma_f32_16x16x32_bf16 v[36:39], v[164:167], v[198:201], v[36:39]
	v_mfma_f32_16x16x32_bf16 v[32:35], v[172:175], v[198:201], v[32:35]
	v_mfma_f32_16x16x32_bf16 v[20:23], v[164:167], v[206:209], v[20:23]
	v_mfma_f32_16x16x32_bf16 v[16:19], v[172:175], v[206:209], v[16:19]
	v_mfma_f32_16x16x32_bf16 v[4:7], v[164:167], v[214:217], v[4:7]
	v_mfma_f32_16x16x32_bf16 v[0:3], v[172:175], v[214:217], v[0:3]
	s_barrier
	s_setprio 0
	s_add_i32 s44, 0, 0x18000
	s_add_i32 s70, 0, 0x1c000
	v_add_u32_e32 v156, s44, v187
	v_add_u32_e32 v172, s70, v187
	ds_read_b128 v[144:147], v156
	ds_read_b128 v[148:151], v156 offset:1024
	ds_read_b128 v[152:155], v156 offset:2048
	ds_read_b128 v[156:159], v156 offset:3072
	ds_read_b128 v[160:163], v172
	ds_read_b128 v[164:167], v172 offset:1024
	ds_read_b128 v[168:171], v172 offset:2048
	ds_read_b128 v[172:175], v172 offset:3072
	s_mov_b32 m0, s53
	v_lshl_add_u64 v[224:225], v[220:221], 0, s[10:11]
	ds_read_b128 v[176:179], v191 offset:32768
	ds_read_b128 v[180:183], v191 offset:33792
	ds_read_b128 v[194:197], v191 offset:34816
	ds_read_b128 v[198:201], v191 offset:35840
	ds_read_b128 v[202:205], v191 offset:36864
	ds_read_b128 v[206:209], v191 offset:37888
	ds_read_b128 v[210:213], v191 offset:38912
	ds_read_b128 v[214:217], v191 offset:39936
	global_load_lds_dwordx4 v[224:225], off
	s_mov_b32 m0, s54
	v_lshl_add_u64 v[224:225], v[222:223], 0, s[14:15]
	global_load_lds_dwordx4 v[224:225], off
	s_waitcnt vmcnt(8) lgkmcnt(0)
	s_setprio 1
	s_barrier
	v_mfma_f32_16x16x32_bf16 v[124:127], v[144:147], v[176:179], v[124:127]
	v_mfma_f32_16x16x32_bf16 v[120:123], v[152:155], v[176:179], v[120:123]
	v_mfma_f32_16x16x32_bf16 v[108:111], v[144:147], v[194:197], v[108:111]
	v_mfma_f32_16x16x32_bf16 v[104:107], v[152:155], v[194:197], v[104:107]
	v_mfma_f32_16x16x32_bf16 v[92:95], v[144:147], v[202:205], v[92:95]
	v_mfma_f32_16x16x32_bf16 v[88:91], v[152:155], v[202:205], v[88:91]
	v_mfma_f32_16x16x32_bf16 v[76:79], v[144:147], v[210:213], v[76:79]
	v_mfma_f32_16x16x32_bf16 v[72:75], v[152:155], v[210:213], v[72:75]
	v_mfma_f32_16x16x32_bf16 v[124:127], v[148:151], v[180:183], v[124:127]
	v_mfma_f32_16x16x32_bf16 v[120:123], v[156:159], v[180:183], v[120:123]
	v_mfma_f32_16x16x32_bf16 v[108:111], v[148:151], v[198:201], v[108:111]
	v_mfma_f32_16x16x32_bf16 v[104:107], v[156:159], v[198:201], v[104:107]
	v_mfma_f32_16x16x32_bf16 v[92:95], v[148:151], v[206:209], v[92:95]
	v_mfma_f32_16x16x32_bf16 v[88:91], v[156:159], v[206:209], v[88:91]
	v_mfma_f32_16x16x32_bf16 v[76:79], v[148:151], v[214:217], v[76:79]
	v_mfma_f32_16x16x32_bf16 v[72:75], v[156:159], v[214:217], v[72:75]
	v_mfma_f32_16x16x32_bf16 v[116:119], v[160:163], v[176:179], v[116:119]
	v_mfma_f32_16x16x32_bf16 v[112:115], v[168:171], v[176:179], v[112:115]
	v_mfma_f32_16x16x32_bf16 v[100:103], v[160:163], v[194:197], v[100:103]
	v_mfma_f32_16x16x32_bf16 v[96:99], v[168:171], v[194:197], v[96:99]
	v_mfma_f32_16x16x32_bf16 v[84:87], v[160:163], v[202:205], v[84:87]
	v_mfma_f32_16x16x32_bf16 v[80:83], v[168:171], v[202:205], v[80:83]
	v_mfma_f32_16x16x32_bf16 v[68:71], v[160:163], v[210:213], v[68:71]
	v_mfma_f32_16x16x32_bf16 v[64:67], v[168:171], v[210:213], v[64:67]
	v_mfma_f32_16x16x32_bf16 v[116:119], v[164:167], v[180:183], v[116:119]
	v_mfma_f32_16x16x32_bf16 v[112:115], v[172:175], v[180:183], v[112:115]
	v_mfma_f32_16x16x32_bf16 v[100:103], v[164:167], v[198:201], v[100:103]
	v_mfma_f32_16x16x32_bf16 v[96:99], v[172:175], v[198:201], v[96:99]
	v_mfma_f32_16x16x32_bf16 v[84:87], v[164:167], v[206:209], v[84:87]
	v_mfma_f32_16x16x32_bf16 v[80:83], v[172:175], v[206:209], v[80:83]
	v_mfma_f32_16x16x32_bf16 v[68:71], v[164:167], v[214:217], v[68:71]
	v_mfma_f32_16x16x32_bf16 v[64:67], v[172:175], v[214:217], v[64:67]
	s_barrier
	s_setprio 0
	s_add_i32 s44, s44, s50
	v_lshl_add_u64 v[184:185], v[184:185], 0, s[24:25]
	s_mov_b32 m0, s44
	ds_read_b128 v[176:179], v191 offset:49152
	ds_read_b128 v[180:183], v191 offset:50176
	ds_read_b128 v[194:197], v191 offset:51200
	ds_read_b128 v[198:201], v191 offset:52224
	ds_read_b128 v[202:205], v191 offset:53248
	ds_read_b128 v[206:209], v191 offset:54272
	ds_read_b128 v[210:213], v191 offset:55296
	ds_read_b128 v[214:217], v191 offset:56320
	global_load_lds_dwordx4 v[184:185], off
	s_add_i32 m0, s44, 0x2000
	s_add_u32 s44, s48, 0x40080
	v_lshl_add_u64 v[184:185], v[218:219], 0, s[24:25]
	s_addc_u32 s45, s49, 0
	s_add_i32 s48, s70, s50
	global_load_lds_dwordx4 v[184:185], off
	s_mov_b32 m0, s48
	v_lshl_add_u64 v[184:185], s[44:45], 0, v[130:131]
	global_load_lds_dwordx4 v[184:185], off
	s_add_i32 m0, s48, 0x2000
	v_lshl_add_u64 v[184:185], s[44:45], 0, v[134:135]
	global_load_lds_dwordx4 v[184:185], off
	s_mov_b32 m0, s58
	v_lshl_add_u64 v[184:185], v[220:221], 0, s[24:25]
	global_load_lds_dwordx4 v[184:185], off
	s_mov_b32 m0, s59
	v_lshl_add_u64 v[184:185], v[222:223], 0, s[30:31]
	global_load_lds_dwordx4 v[184:185], off
	s_waitcnt vmcnt(8) lgkmcnt(0)
	s_setprio 1
	s_barrier
	v_mfma_f32_16x16x32_bf16 v[60:63], v[144:147], v[176:179], v[60:63]
	v_mfma_f32_16x16x32_bf16 v[56:59], v[152:155], v[176:179], v[56:59]
	v_mfma_f32_16x16x32_bf16 v[44:47], v[144:147], v[194:197], v[44:47]
	v_mfma_f32_16x16x32_bf16 v[40:43], v[152:155], v[194:197], v[40:43]
	v_mfma_f32_16x16x32_bf16 v[28:31], v[144:147], v[202:205], v[28:31]
	v_mfma_f32_16x16x32_bf16 v[24:27], v[152:155], v[202:205], v[24:27]
	v_mfma_f32_16x16x32_bf16 v[12:15], v[144:147], v[210:213], v[12:15]
	v_mfma_f32_16x16x32_bf16 v[8:11], v[152:155], v[210:213], v[8:11]
	v_mfma_f32_16x16x32_bf16 v[60:63], v[148:151], v[180:183], v[60:63]
	v_mfma_f32_16x16x32_bf16 v[56:59], v[156:159], v[180:183], v[56:59]
	v_mfma_f32_16x16x32_bf16 v[44:47], v[148:151], v[198:201], v[44:47]
	v_mfma_f32_16x16x32_bf16 v[40:43], v[156:159], v[198:201], v[40:43]
	v_mfma_f32_16x16x32_bf16 v[28:31], v[148:151], v[206:209], v[28:31]
	v_mfma_f32_16x16x32_bf16 v[24:27], v[156:159], v[206:209], v[24:27]
	v_mfma_f32_16x16x32_bf16 v[12:15], v[148:151], v[214:217], v[12:15]
	v_mfma_f32_16x16x32_bf16 v[8:11], v[156:159], v[214:217], v[8:11]
	v_mfma_f32_16x16x32_bf16 v[52:55], v[160:163], v[176:179], v[52:55]
	v_mfma_f32_16x16x32_bf16 v[48:51], v[168:171], v[176:179], v[48:51]
	v_mfma_f32_16x16x32_bf16 v[36:39], v[160:163], v[194:197], v[36:39]
	v_mfma_f32_16x16x32_bf16 v[32:35], v[168:171], v[194:197], v[32:35]
	v_mfma_f32_16x16x32_bf16 v[20:23], v[160:163], v[202:205], v[20:23]
	v_mfma_f32_16x16x32_bf16 v[16:19], v[168:171], v[202:205], v[16:19]
	v_mfma_f32_16x16x32_bf16 v[4:7], v[160:163], v[210:213], v[4:7]
	v_mfma_f32_16x16x32_bf16 v[0:3], v[168:171], v[210:213], v[0:3]
	v_mfma_f32_16x16x32_bf16 v[52:55], v[164:167], v[180:183], v[52:55]
	v_mfma_f32_16x16x32_bf16 v[48:51], v[172:175], v[180:183], v[48:51]
	v_mfma_f32_16x16x32_bf16 v[36:39], v[164:167], v[198:201], v[36:39]
	v_mfma_f32_16x16x32_bf16 v[32:35], v[172:175], v[198:201], v[32:35]
	v_mfma_f32_16x16x32_bf16 v[20:23], v[164:167], v[206:209], v[20:23]
	v_mfma_f32_16x16x32_bf16 v[16:19], v[172:175], v[206:209], v[16:19]
	v_mfma_f32_16x16x32_bf16 v[4:7], v[164:167], v[214:217], v[4:7]
	v_mfma_f32_16x16x32_bf16 v[0:3], v[172:175], v[214:217], v[0:3]
	s_barrier
	s_setprio 0
	s_add_i32 s72, s72, 2
	s_add_u32 s69, s69, 0x100
	s_addc_u32 s71, s71, 0
	s_cmp_gt_u32 s72, 13
	s_mov_b64 s[44:45], s[46:47]
	s_cbranch_scc0 .LBB0_751
	s_and_b64 vcc, exec, s[34:35]
	s_cbranch_vccz .LBB0_754
	s_barrier
